# row phases: non-temporal hint on the read-once streaming loads (x, F, previous out)
# speedup vs baseline: 1.0179x; 1.0050x over previous
; __device__ __forceinline__ unsigned pk_bf16(float lo, float hi) { const f32x2 v = {lo, hi}; const bf16x2_t b = __builtin_convertvector(v, bf16x2_t); return __builtin_bit_cast(unsigned, b); }
; template <bool HAS_F, bool HAS_H>
; __device__ __forceinline__ void phase_rows(const Params& p, int sp, int sn, float resw, bool from_input, bool write_x = true) {
;     ...
;     for (int row = gw; row < T; row += NGW) {
;         const int b = row_batch(row);
;         const float* xin = !from_input ? p.out + (size_t)row * D : (row < TP ? p.in[0] + (size_t)row * D : p.in[1] + (size_t)(row - TP) * D);
;         f32x4 v[4];
; #pragma unroll
;         for (int j = 0; j < 4; ++j) v[j] = *(const f32x4*)(xin + 4 * lane + 256 * j);
;     ...
;         if (HAS_H) {
;             float ss = 0.f;
; #pragma unroll
;             for (int j = 0; j < 4; ++j) ss += (v[j].x * v[j].x + v[j].y * v[j].y) + (v[j].z * v[j].z + v[j].w * v[j].w);
;             const float rs = 1.0f / sqrtf(wave_sum(ss) * (1.0f / D) + EPS);
;             const float* sh = mod + b * 9216 + sn * 3072; const float* scl = sh + 1024; const float* gq = p.in[6] + sn * D;
; #pragma unroll
;             for (int j = 0; j < 4; ++j) { const f32x4 a = *(const f32x4*)(sh + 4 * lane + 256 * j), s = *(const f32x4*)(scl + 4 * lane + 256 * j), q = *(const f32x4*)(gq + 4 * lane + 256 * j);
;                 const f32x4 h = (v[j] * rs * q) * (s + 1.0f) + a;
;                 u32x2 w; w.x = pk_bf16(h.x, h.y); w.y = pk_bf16(h.z, h.w);
;                 *(u32x2*)(H + (size_t)row * D + 4 * lane + 256 * j) = w; }
.Lrp1_chunk1:
	s_mul_i32 s53, s51, 384
	s_cmp_ge_u32 s53, 0x18000
	s_cbranch_scc1 .Lrp1_done2
	s_add_u32 s53, s53, s50
	s_add_u32 s54, s53, 376
	s_mov_b32 s56, -1
	s_mov_b32 s55, s53
	s_add_u32 s57, s53, 0
	s_cmp_lt_u32 s57, 0x8000
	s_cselect_b32 s64, s8, s10
	s_cselect_b32 s65, s9, s11
	s_cselect_b32 s60, 0, 0x8000
	s_sub_u32 s60, s57, s60
	s_lshl_b32 s60, s60, 12
	s_add_u32 s64, s64, s60
	s_addc_u32 s65, s65, 0
	global_load_dwordx4 v[4:7], v0, s[64:65] nt
	global_load_dwordx4 v[8:11], v0, s[64:65] offset:1024 nt
	global_load_dwordx4 v[12:15], v0, s[64:65] offset:2048 nt
	global_load_dwordx4 v[16:19], v0, s[64:65] offset:3072 nt
	s_add_u32 s57, s53, 8
	s_cmp_lt_u32 s57, 0x8000
	s_cselect_b32 s64, s8, s10
	s_cselect_b32 s65, s9, s11
	s_cselect_b32 s60, 0, 0x8000
	s_sub_u32 s60, s57, s60
	s_lshl_b32 s60, s60, 12
	s_add_u32 s64, s64, s60
	s_addc_u32 s65, s65, 0
	global_load_dwordx4 v[36:39], v0, s[64:65] nt
	global_load_dwordx4 v[40:43], v0, s[64:65] offset:1024 nt
	global_load_dwordx4 v[44:47], v0, s[64:65] offset:2048 nt
	global_load_dwordx4 v[48:51], v0, s[64:65] offset:3072 nt
	s_add_u32 s57, s55, 16
	s_min_u32 s57, s57, s54
	s_cmp_lt_u32 s57, 0x8000
	s_cselect_b32 s64, s8, s10
	s_cselect_b32 s65, s9, s11
	s_cselect_b32 s60, 0, 0x8000
	s_sub_u32 s60, s57, s60
	s_lshl_b32 s60, s60, 12
	s_add_u32 s64, s64, s60
	s_addc_u32 s65, s65, 0
	global_load_dwordx4 v[68:71], v0, s[64:65] nt
	global_load_dwordx4 v[72:75], v0, s[64:65] offset:1024 nt
	global_load_dwordx4 v[76:79], v0, s[64:65] offset:2048 nt
	global_load_dwordx4 v[80:83], v0, s[64:65] offset:3072 nt
	s_lshr_b32 s60, s55, 11
	s_sub_u32 s61, s55, 0x8000
	s_lshr_b32 s61, s61, 12
	s_add_u32 s61, s61, 16
	s_cmp_lt_u32 s55, 0x8000
	s_cselect_b32 s63, s60, s61
	s_cmp_eq_u32 s63, s56
	s_cbranch_scc1 .Lrp1_pk4
	s_mov_b32 s56, s63
	s_add_u32 s0, s20, 0x0
	s_addc_u32 s1, s21, 0
	global_load_dwordx4 v[160:163], v0, s[0:1]
	global_load_dwordx4 v[164:167], v0, s[0:1] offset:1024
	global_load_dwordx4 v[168:171], v0, s[0:1] offset:2048
	global_load_dwordx4 v[172:175], v0, s[0:1] offset:3072
	s_mul_i32 s60, s56, 0x9000
	s_add_u32 s60, s60, 0x3181000
	s_add_u32 s0, s92, s60
	s_addc_u32 s1, s93, 0
	global_load_dwordx4 v[176:179], v0, s[0:1]
	global_load_dwordx4 v[180:183], v0, s[0:1] offset:1024
	global_load_dwordx4 v[184:187], v0, s[0:1] offset:2048
	global_load_dwordx4 v[188:191], v0, s[0:1] offset:3072
	s_mul_i32 s60, s56, 0x9000
	s_add_u32 s60, s60, 0x3180000
	s_add_u32 s0, s92, s60
	s_addc_u32 s1, s93, 0
	global_load_dwordx4 v[192:195], v0, s[0:1]
	global_load_dwordx4 v[196:199], v0, s[0:1] offset:1024
	global_load_dwordx4 v[200:203], v0, s[0:1] offset:2048
	global_load_dwordx4 v[204:207], v0, s[0:1] offset:3072
	s_waitcnt vmcnt(0)
	v_pk_add_f32 v[176:177], v[176:177], 1.0 op_sel_hi:[1,0]
	v_pk_add_f32 v[178:179], v[178:179], 1.0 op_sel_hi:[1,0]
	v_pk_add_f32 v[180:181], v[180:181], 1.0 op_sel_hi:[1,0]
	v_pk_add_f32 v[182:183], v[182:183], 1.0 op_sel_hi:[1,0]
	v_pk_add_f32 v[184:185], v[184:185], 1.0 op_sel_hi:[1,0]
	v_pk_add_f32 v[186:187], v[186:187], 1.0 op_sel_hi:[1,0]
	v_pk_add_f32 v[188:189], v[188:189], 1.0 op_sel_hi:[1,0]
	v_pk_add_f32 v[190:191], v[190:191], 1.0 op_sel_hi:[1,0]
.Lrp1_pk4:
	s_waitcnt vmcnt(8)
	v_pk_mul_f32 v[102:103], v[4:5], v[4:5]
	v_pk_mul_f32 v[106:107], v[6:7], v[6:7]
	v_pk_fma_f32 v[102:103], v[8:9], v[8:9], v[102:103]
	v_pk_fma_f32 v[106:107], v[10:11], v[10:11], v[106:107]
	v_pk_fma_f32 v[102:103], v[12:13], v[12:13], v[102:103]
	v_pk_fma_f32 v[106:107], v[14:15], v[14:15], v[106:107]
	v_pk_fma_f32 v[102:103], v[16:17], v[16:17], v[102:103]
	v_pk_fma_f32 v[106:107], v[18:19], v[18:19], v[106:107]
	v_pk_add_f32 v[102:103], v[102:103], v[106:107]
	v_add_f32_e32 v102, v102, v103
	s_nop 1
	v_add_f32_dpp v102, v102, v102 quad_perm:[1,0,3,2] row_mask:0xf bank_mask:0xf
	s_nop 1
	v_add_f32_dpp v102, v102, v102 quad_perm:[2,3,0,1] row_mask:0xf bank_mask:0xf
	s_nop 1
	v_add_f32_dpp v102, v102, v102 row_half_mirror row_mask:0xf bank_mask:0xf
	s_nop 1
	v_add_f32_dpp v102, v102, v102 row_mirror row_mask:0xf bank_mask:0xf
	s_nop 1
	v_add_f32_dpp v102, v102, v102 row_bcast:15 row_mask:0xa bank_mask:0xf
	s_nop 1
	v_add_f32_dpp v102, v102, v102 row_bcast:31 row_mask:0xc bank_mask:0xf
	s_nop 1
	v_readlane_b32 s74, v102, 63
	s_nop 2
	v_mov_b32_e32 v102, s74
	v_fmamk_f32 v102, v102, 0x3a800000, v2
	v_mul_f32_e32 v103, 0x4f800000, v102
	v_cmp_gt_f32_e32 vcc, 0xf800000, v102
	s_nop 1
	v_cndmask_b32_e32 v102, v102, v103, vcc
	v_sqrt_f32_e32 v103, v102
	s_nop 0
	v_add_u32_e32 v104, -1, v103
	v_add_u32_e32 v106, 1, v103
	v_fma_f32 v107, -v104, v103, v102
	v_fma_f32 v108, -v106, v103, v102
	v_cmp_ge_f32_e64 s[76:77], 0, v107
	s_nop 1
	v_cndmask_b32_e64 v103, v103, v104, s[76:77]
	v_cmp_lt_f32_e64 s[76:77], 0, v108
	s_nop 1
	v_cndmask_b32_e64 v103, v103, v106, s[76:77]
	v_mul_f32_e32 v104, 0x37800000, v103
	v_cndmask_b32_e32 v103, v103, v104, vcc
	v_cmp_class_f32_e32 vcc, v102, v3
	s_nop 1
	v_cndmask_b32_e32 v102, v103, v102, vcc
	v_div_scale_f32 v103, s[76:77], v102, v102, 1.0
	v_rcp_f32_e32 v104, v103
	v_div_scale_f32 v106, vcc, 1.0, v102, 1.0
	v_fma_f32 v107, -v103, v104, 1.0
	v_fmac_f32_e32 v104, v107, v104
	v_mul_f32_e32 v107, v106, v104
	v_fma_f32 v108, -v103, v107, v106
	v_fmac_f32_e32 v107, v108, v104
	v_fma_f32 v103, -v103, v107, v106
	v_div_fmas_f32 v103, v103, v104, v107
	v_div_fixup_f32 v110, v103, v102, 1.0
	s_lshl_b32 s60, s55, 11
	s_add_u32 s70, s78, s60
	s_addc_u32 s71, s79, 0
	v_pk_mul_f32 v[112:113], v[4:5], v[110:111] op_sel_hi:[1,0]
	v_pk_mul_f32 v[114:115], v[6:7], v[110:111] op_sel_hi:[1,0]
	v_pk_mul_f32 v[116:117], v[8:9], v[110:111] op_sel_hi:[1,0]
; __device__ __forceinline__ unsigned pk_bf16(float lo, float hi) { const f32x2 v = {lo, hi}; const bf16x2_t b = __builtin_convertvector(v, bf16x2_t); return __builtin_bit_cast(unsigned, b); }
; template <bool HAS_F, bool HAS_H>
; __device__ __forceinline__ void phase_rows(const Params& p, int sp, int sn, float resw, bool from_input, bool write_x = true) {
;     ...
;     for (int row = gw; row < T; row += NGW) {
;         const int b = row_batch(row);
;         const float* xin = !from_input ? p.out + (size_t)row * D : (row < TP ? p.in[0] + (size_t)row * D : p.in[1] + (size_t)(row - TP) * D);
;         f32x4 v[4];
; #pragma unroll
;         for (int j = 0; j < 4; ++j) v[j] = *(const f32x4*)(xin + 4 * lane + 256 * j);
;     ...
;         if (HAS_H) {
;             float ss = 0.f;
; #pragma unroll
;             for (int j = 0; j < 4; ++j) ss += (v[j].x * v[j].x + v[j].y * v[j].y) + (v[j].z * v[j].z + v[j].w * v[j].w);
;             const float rs = 1.0f / sqrtf(wave_sum(ss) * (1.0f / D) + EPS);
;             const float* sh = mod + b * 9216 + sn * 3072; const float* scl = sh + 1024; const float* gq = p.in[6] + sn * D;
; #pragma unroll
;             for (int j = 0; j < 4; ++j) { const f32x4 a = *(const f32x4*)(sh + 4 * lane + 256 * j), s = *(const f32x4*)(scl + 4 * lane + 256 * j), q = *(const f32x4*)(gq + 4 * lane + 256 * j);
;                 const f32x4 h = (v[j] * rs * q) * (s + 1.0f) + a;
;                 u32x2 w; w.x = pk_bf16(h.x, h.y); w.y = pk_bf16(h.z, h.w);
;                 *(u32x2*)(H + (size_t)row * D + 4 * lane + 256 * j) = w; }
	v_pk_mul_f32 v[118:119], v[10:11], v[110:111] op_sel_hi:[1,0]
	v_pk_mul_f32 v[120:121], v[12:13], v[110:111] op_sel_hi:[1,0]
	v_pk_mul_f32 v[122:123], v[14:15], v[110:111] op_sel_hi:[1,0]
	v_pk_mul_f32 v[124:125], v[16:17], v[110:111] op_sel_hi:[1,0]
	v_pk_mul_f32 v[100:101], v[18:19], v[110:111] op_sel_hi:[1,0]
	v_pk_mul_f32 v[112:113], v[160:161], v[112:113]
	v_pk_mul_f32 v[114:115], v[162:163], v[114:115]
	v_pk_mul_f32 v[116:117], v[164:165], v[116:117]
	v_pk_mul_f32 v[118:119], v[166:167], v[118:119]
	v_pk_mul_f32 v[120:121], v[168:169], v[120:121]
	v_pk_mul_f32 v[122:123], v[170:171], v[122:123]
	v_pk_mul_f32 v[124:125], v[172:173], v[124:125]
	v_pk_mul_f32 v[100:101], v[174:175], v[100:101]
	v_pk_fma_f32 v[112:113], v[176:177], v[112:113], v[192:193]
	v_pk_fma_f32 v[114:115], v[178:179], v[114:115], v[194:195]
	v_pk_fma_f32 v[116:117], v[180:181], v[116:117], v[196:197]
	v_pk_fma_f32 v[118:119], v[182:183], v[118:119], v[198:199]
	v_pk_fma_f32 v[120:121], v[184:185], v[120:121], v[200:201]
	v_pk_fma_f32 v[122:123], v[186:187], v[122:123], v[202:203]
	v_pk_fma_f32 v[124:125], v[188:189], v[124:125], v[204:205]
	v_pk_fma_f32 v[100:101], v[190:191], v[100:101], v[206:207]
	v_cvt_pk_bf16_f32 v240, v112, v113
	v_cvt_pk_bf16_f32 v241, v114, v115
	v_cvt_pk_bf16_f32 v242, v116, v117
	v_cvt_pk_bf16_f32 v243, v118, v119
	v_cvt_pk_bf16_f32 v244, v120, v121
	v_cvt_pk_bf16_f32 v245, v122, v123
	v_cvt_pk_bf16_f32 v246, v124, v125
	v_cvt_pk_bf16_f32 v247, v100, v101
	global_store_dwordx2 v1, v[240:241], s[70:71]
	global_store_dwordx2 v1, v[242:243], s[70:71] offset:512
	global_store_dwordx2 v1, v[244:245], s[70:71] offset:1024
	global_store_dwordx2 v1, v[246:247], s[70:71] offset:1536
	s_add_u32 s55, s55, 8
	s_add_u32 s57, s55, 16
	s_min_u32 s57, s57, s54
	s_cmp_lt_u32 s57, 0x8000
	s_cselect_b32 s64, s8, s10
	s_cselect_b32 s65, s9, s11
	s_cselect_b32 s60, 0, 0x8000
	s_sub_u32 s60, s57, s60
	s_lshl_b32 s60, s60, 12
	s_add_u32 s64, s64, s60
	s_addc_u32 s65, s65, 0
	global_load_dwordx4 v[4:7], v0, s[64:65] nt
	global_load_dwordx4 v[8:11], v0, s[64:65] offset:1024 nt
	global_load_dwordx4 v[12:15], v0, s[64:65] offset:2048 nt
	global_load_dwordx4 v[16:19], v0, s[64:65] offset:3072 nt
	s_lshr_b32 s60, s55, 11
	s_sub_u32 s61, s55, 0x8000
	s_lshr_b32 s61, s61, 12
	s_add_u32 s61, s61, 16
	s_cmp_lt_u32 s55, 0x8000
	s_cselect_b32 s63, s60, s61
	s_cmp_eq_u32 s63, s56
	s_cbranch_scc1 .Lrp1_pk5
	s_mov_b32 s56, s63
	s_add_u32 s0, s20, 0x0
	s_addc_u32 s1, s21, 0
	global_load_dwordx4 v[160:163], v0, s[0:1]
	global_load_dwordx4 v[164:167], v0, s[0:1] offset:1024
	global_load_dwordx4 v[168:171], v0, s[0:1] offset:2048
	global_load_dwordx4 v[172:175], v0, s[0:1] offset:3072
	s_mul_i32 s60, s56, 0x9000
	s_add_u32 s60, s60, 0x3181000
	s_add_u32 s0, s92, s60
	s_addc_u32 s1, s93, 0
	global_load_dwordx4 v[176:179], v0, s[0:1]
	global_load_dwordx4 v[180:183], v0, s[0:1] offset:1024
	global_load_dwordx4 v[184:187], v0, s[0:1] offset:2048
	global_load_dwordx4 v[188:191], v0, s[0:1] offset:3072
	s_mul_i32 s60, s56, 0x9000
	s_add_u32 s60, s60, 0x3180000
	s_add_u32 s0, s92, s60
	s_addc_u32 s1, s93, 0
	global_load_dwordx4 v[192:195], v0, s[0:1]
	global_load_dwordx4 v[196:199], v0, s[0:1] offset:1024
	global_load_dwordx4 v[200:203], v0, s[0:1] offset:2048
	global_load_dwordx4 v[204:207], v0, s[0:1] offset:3072
	s_waitcnt vmcnt(0)
	v_pk_add_f32 v[176:177], v[176:177], 1.0 op_sel_hi:[1,0]
	v_pk_add_f32 v[178:179], v[178:179], 1.0 op_sel_hi:[1,0]
	v_pk_add_f32 v[180:181], v[180:181], 1.0 op_sel_hi:[1,0]
	v_pk_add_f32 v[182:183], v[182:183], 1.0 op_sel_hi:[1,0]
	v_pk_add_f32 v[184:185], v[184:185], 1.0 op_sel_hi:[1,0]
	v_pk_add_f32 v[186:187], v[186:187], 1.0 op_sel_hi:[1,0]
	v_pk_add_f32 v[188:189], v[188:189], 1.0 op_sel_hi:[1,0]
	v_pk_add_f32 v[190:191], v[190:191], 1.0 op_sel_hi:[1,0]
; __device__ __forceinline__ unsigned pk_bf16(float lo, float hi) { const f32x2 v = {lo, hi}; const bf16x2_t b = __builtin_convertvector(v, bf16x2_t); return __builtin_bit_cast(unsigned, b); }
; template <bool HAS_F, bool HAS_H>
; __device__ __forceinline__ void phase_rows(const Params& p, int sp, int sn, float resw, bool from_input, bool write_x = true) {
;     ...
;     for (int row = gw; row < T; row += NGW) {
;         const int b = row_batch(row);
;         const float* xin = !from_input ? p.out + (size_t)row * D : (row < TP ? p.in[0] + (size_t)row * D : p.in[1] + (size_t)(row - TP) * D);
;         f32x4 v[4];
; #pragma unroll
;         for (int j = 0; j < 4; ++j) v[j] = *(const f32x4*)(xin + 4 * lane + 256 * j);
;     ...
;         if (HAS_H) {
;             float ss = 0.f;
; #pragma unroll
;             for (int j = 0; j < 4; ++j) ss += (v[j].x * v[j].x + v[j].y * v[j].y) + (v[j].z * v[j].z + v[j].w * v[j].w);
;             const float rs = 1.0f / sqrtf(wave_sum(ss) * (1.0f / D) + EPS);
;             const float* sh = mod + b * 9216 + sn * 3072; const float* scl = sh + 1024; const float* gq = p.in[6] + sn * D;
; #pragma unroll
;             for (int j = 0; j < 4; ++j) { const f32x4 a = *(const f32x4*)(sh + 4 * lane + 256 * j), s = *(const f32x4*)(scl + 4 * lane + 256 * j), q = *(const f32x4*)(gq + 4 * lane + 256 * j);
;                 const f32x4 h = (v[j] * rs * q) * (s + 1.0f) + a;
;                 u32x2 w; w.x = pk_bf16(h.x, h.y); w.y = pk_bf16(h.z, h.w);
;                 *(u32x2*)(H + (size_t)row * D + 4 * lane + 256 * j) = w; }
.Lrp1_pk5:
	s_waitcnt vmcnt(12)
	v_pk_mul_f32 v[102:103], v[36:37], v[36:37]
	v_pk_mul_f32 v[106:107], v[38:39], v[38:39]
	v_pk_fma_f32 v[102:103], v[40:41], v[40:41], v[102:103]
	v_pk_fma_f32 v[106:107], v[42:43], v[42:43], v[106:107]
	v_pk_fma_f32 v[102:103], v[44:45], v[44:45], v[102:103]
	v_pk_fma_f32 v[106:107], v[46:47], v[46:47], v[106:107]
	v_pk_fma_f32 v[102:103], v[48:49], v[48:49], v[102:103]
	v_pk_fma_f32 v[106:107], v[50:51], v[50:51], v[106:107]
	v_pk_add_f32 v[102:103], v[102:103], v[106:107]
	v_add_f32_e32 v102, v102, v103
	s_nop 1
	v_add_f32_dpp v102, v102, v102 quad_perm:[1,0,3,2] row_mask:0xf bank_mask:0xf
	s_nop 1
	v_add_f32_dpp v102, v102, v102 quad_perm:[2,3,0,1] row_mask:0xf bank_mask:0xf
	s_nop 1
	v_add_f32_dpp v102, v102, v102 row_half_mirror row_mask:0xf bank_mask:0xf
	s_nop 1
	v_add_f32_dpp v102, v102, v102 row_mirror row_mask:0xf bank_mask:0xf
	s_nop 1
	v_add_f32_dpp v102, v102, v102 row_bcast:15 row_mask:0xa bank_mask:0xf
	s_nop 1
	v_add_f32_dpp v102, v102, v102 row_bcast:31 row_mask:0xc bank_mask:0xf
	s_nop 1
	v_readlane_b32 s74, v102, 63
	s_nop 2
	v_mov_b32_e32 v102, s74
	v_fmamk_f32 v102, v102, 0x3a800000, v2
	v_mul_f32_e32 v103, 0x4f800000, v102
	v_cmp_gt_f32_e32 vcc, 0xf800000, v102
	s_nop 1
	v_cndmask_b32_e32 v102, v102, v103, vcc
	v_sqrt_f32_e32 v103, v102
	s_nop 0
	v_add_u32_e32 v104, -1, v103
	v_add_u32_e32 v106, 1, v103
	v_fma_f32 v107, -v104, v103, v102
	v_fma_f32 v108, -v106, v103, v102
	v_cmp_ge_f32_e64 s[76:77], 0, v107
	s_nop 1
	v_cndmask_b32_e64 v103, v103, v104, s[76:77]
	v_cmp_lt_f32_e64 s[76:77], 0, v108
	s_nop 1
	v_cndmask_b32_e64 v103, v103, v106, s[76:77]
	v_mul_f32_e32 v104, 0x37800000, v103
	v_cndmask_b32_e32 v103, v103, v104, vcc
	v_cmp_class_f32_e32 vcc, v102, v3
	s_nop 1
	v_cndmask_b32_e32 v102, v103, v102, vcc
	v_div_scale_f32 v103, s[76:77], v102, v102, 1.0
	v_rcp_f32_e32 v104, v103
	v_div_scale_f32 v106, vcc, 1.0, v102, 1.0
	v_fma_f32 v107, -v103, v104, 1.0
	v_fmac_f32_e32 v104, v107, v104
	v_mul_f32_e32 v107, v106, v104
	v_fma_f32 v108, -v103, v107, v106
	v_fmac_f32_e32 v107, v108, v104
	v_fma_f32 v103, -v103, v107, v106
	v_div_fmas_f32 v103, v103, v104, v107
	v_div_fixup_f32 v110, v103, v102, 1.0
	s_lshl_b32 s60, s55, 11
	s_add_u32 s70, s78, s60
	s_addc_u32 s71, s79, 0
	v_pk_mul_f32 v[112:113], v[36:37], v[110:111] op_sel_hi:[1,0]
	v_pk_mul_f32 v[114:115], v[38:39], v[110:111] op_sel_hi:[1,0]
	v_pk_mul_f32 v[116:117], v[40:41], v[110:111] op_sel_hi:[1,0]
	v_pk_mul_f32 v[118:119], v[42:43], v[110:111] op_sel_hi:[1,0]
	v_pk_mul_f32 v[120:121], v[44:45], v[110:111] op_sel_hi:[1,0]
	v_pk_mul_f32 v[122:123], v[46:47], v[110:111] op_sel_hi:[1,0]
	v_pk_mul_f32 v[124:125], v[48:49], v[110:111] op_sel_hi:[1,0]
	v_pk_mul_f32 v[100:101], v[50:51], v[110:111] op_sel_hi:[1,0]
	v_pk_mul_f32 v[112:113], v[160:161], v[112:113]
	v_pk_mul_f32 v[114:115], v[162:163], v[114:115]
	v_pk_mul_f32 v[116:117], v[164:165], v[116:117]
	v_pk_mul_f32 v[118:119], v[166:167], v[118:119]
	v_pk_mul_f32 v[120:121], v[168:169], v[120:121]
	v_pk_mul_f32 v[122:123], v[170:171], v[122:123]
	v_pk_mul_f32 v[124:125], v[172:173], v[124:125]
	v_pk_mul_f32 v[100:101], v[174:175], v[100:101]
	v_pk_fma_f32 v[112:113], v[176:177], v[112:113], v[192:193]
	v_pk_fma_f32 v[114:115], v[178:179], v[114:115], v[194:195]
	v_pk_fma_f32 v[116:117], v[180:181], v[116:117], v[196:197]
	v_pk_fma_f32 v[118:119], v[182:183], v[118:119], v[198:199]
	v_pk_fma_f32 v[120:121], v[184:185], v[120:121], v[200:201]
	v_pk_fma_f32 v[122:123], v[186:187], v[122:123], v[202:203]
	v_pk_fma_f32 v[124:125], v[188:189], v[124:125], v[204:205]
	v_pk_fma_f32 v[100:101], v[190:191], v[100:101], v[206:207]
	v_cvt_pk_bf16_f32 v240, v112, v113
	v_cvt_pk_bf16_f32 v241, v114, v115
	v_cvt_pk_bf16_f32 v242, v116, v117
	v_cvt_pk_bf16_f32 v243, v118, v119
	v_cvt_pk_bf16_f32 v244, v120, v121
	v_cvt_pk_bf16_f32 v245, v122, v123
	v_cvt_pk_bf16_f32 v246, v124, v125
	v_cvt_pk_bf16_f32 v247, v100, v101
	global_store_dwordx2 v1, v[240:241], s[70:71]
	global_store_dwordx2 v1, v[242:243], s[70:71] offset:512
	global_store_dwordx2 v1, v[244:245], s[70:71] offset:1024
	global_store_dwordx2 v1, v[246:247], s[70:71] offset:1536
	s_add_u32 s55, s55, 8
	s_add_u32 s57, s55, 16
	s_min_u32 s57, s57, s54
	s_cmp_lt_u32 s57, 0x8000
	s_cselect_b32 s64, s8, s10
	s_cselect_b32 s65, s9, s11
	s_cselect_b32 s60, 0, 0x8000
	s_sub_u32 s60, s57, s60
	s_lshl_b32 s60, s60, 12
	s_add_u32 s64, s64, s60
	s_addc_u32 s65, s65, 0
	global_load_dwordx4 v[36:39], v0, s[64:65] nt
	global_load_dwordx4 v[40:43], v0, s[64:65] offset:1024 nt
	global_load_dwordx4 v[44:47], v0, s[64:65] offset:2048 nt
	global_load_dwordx4 v[48:51], v0, s[64:65] offset:3072 nt
	s_lshr_b32 s60, s55, 11
	s_sub_u32 s61, s55, 0x8000
	s_lshr_b32 s61, s61, 12
	s_add_u32 s61, s61, 16
	s_cmp_lt_u32 s55, 0x8000
	s_cselect_b32 s63, s60, s61
	s_cmp_eq_u32 s63, s56
	s_cbranch_scc1 .Lrp1_pk6
	s_mov_b32 s56, s63
	s_add_u32 s0, s20, 0x0
	s_addc_u32 s1, s21, 0
	global_load_dwordx4 v[160:163], v0, s[0:1]
	global_load_dwordx4 v[164:167], v0, s[0:1] offset:1024
	global_load_dwordx4 v[168:171], v0, s[0:1] offset:2048
	global_load_dwordx4 v[172:175], v0, s[0:1] offset:3072
	s_mul_i32 s60, s56, 0x9000
	s_add_u32 s60, s60, 0x3181000
	s_add_u32 s0, s92, s60
	s_addc_u32 s1, s93, 0
	global_load_dwordx4 v[176:179], v0, s[0:1]
	global_load_dwordx4 v[180:183], v0, s[0:1] offset:1024
	global_load_dwordx4 v[184:187], v0, s[0:1] offset:2048
	global_load_dwordx4 v[188:191], v0, s[0:1] offset:3072
	s_mul_i32 s60, s56, 0x9000
	s_add_u32 s60, s60, 0x3180000
	s_add_u32 s0, s92, s60
	s_addc_u32 s1, s93, 0
	global_load_dwordx4 v[192:195], v0, s[0:1]
	global_load_dwordx4 v[196:199], v0, s[0:1] offset:1024
	global_load_dwordx4 v[200:203], v0, s[0:1] offset:2048
	global_load_dwordx4 v[204:207], v0, s[0:1] offset:3072
	s_waitcnt vmcnt(0)
	v_pk_add_f32 v[176:177], v[176:177], 1.0 op_sel_hi:[1,0]
	v_pk_add_f32 v[178:179], v[178:179], 1.0 op_sel_hi:[1,0]
	v_pk_add_f32 v[180:181], v[180:181], 1.0 op_sel_hi:[1,0]
	v_pk_add_f32 v[182:183], v[182:183], 1.0 op_sel_hi:[1,0]
	v_pk_add_f32 v[184:185], v[184:185], 1.0 op_sel_hi:[1,0]
	v_pk_add_f32 v[186:187], v[186:187], 1.0 op_sel_hi:[1,0]
	v_pk_add_f32 v[188:189], v[188:189], 1.0 op_sel_hi:[1,0]
	v_pk_add_f32 v[190:191], v[190:191], 1.0 op_sel_hi:[1,0]

; __device__ __forceinline__ unsigned pk_bf16(float lo, float hi) { const f32x2 v = {lo, hi}; const bf16x2_t b = __builtin_convertvector(v, bf16x2_t); return __builtin_bit_cast(unsigned, b); }
; template <bool HAS_F, bool HAS_H>
; __device__ __forceinline__ void phase_rows(const Params& p, int sp, int sn, float resw, bool from_input, bool write_x = true) {
;     ...
;     for (int row = gw; row < T; row += NGW) {
;         const int b = row_batch(row);
;         const float* xin = !from_input ? p.out + (size_t)row * D : (row < TP ? p.in[0] + (size_t)row * D : p.in[1] + (size_t)(row - TP) * D);
;         f32x4 v[4];
; #pragma unroll
;         for (int j = 0; j < 4; ++j) v[j] = *(const f32x4*)(xin + 4 * lane + 256 * j);
;     ...
;         if (HAS_H) {
;             float ss = 0.f;
; #pragma unroll
;             for (int j = 0; j < 4; ++j) ss += (v[j].x * v[j].x + v[j].y * v[j].y) + (v[j].z * v[j].z + v[j].w * v[j].w);
;             const float rs = 1.0f / sqrtf(wave_sum(ss) * (1.0f / D) + EPS);
;             const float* sh = mod + b * 9216 + sn * 3072; const float* scl = sh + 1024; const float* gq = p.in[6] + sn * D;
; #pragma unroll
;             for (int j = 0; j < 4; ++j) { const f32x4 a = *(const f32x4*)(sh + 4 * lane + 256 * j), s = *(const f32x4*)(scl + 4 * lane + 256 * j), q = *(const f32x4*)(gq + 4 * lane + 256 * j);
;                 const f32x4 h = (v[j] * rs * q) * (s + 1.0f) + a;
;                 u32x2 w; w.x = pk_bf16(h.x, h.y); w.y = pk_bf16(h.z, h.w);
;                 *(u32x2*)(H + (size_t)row * D + 4 * lane + 256 * j) = w; }
.Lrp1_loop3:
	s_add_u32 s57, s55, 16
	s_min_u32 s57, s57, s54
	s_cmp_lt_u32 s57, 0x8000
	s_cselect_b32 s64, s8, s10
	s_cselect_b32 s65, s9, s11
	s_cselect_b32 s60, 0, 0x8000
	s_sub_u32 s60, s57, s60
	s_lshl_b32 s60, s60, 12
	s_add_u32 s64, s64, s60
	s_addc_u32 s65, s65, 0
	global_load_dwordx4 v[68:71], v0, s[64:65] nt
	global_load_dwordx4 v[72:75], v0, s[64:65] offset:1024 nt
	global_load_dwordx4 v[76:79], v0, s[64:65] offset:2048 nt
	global_load_dwordx4 v[80:83], v0, s[64:65] offset:3072 nt
	s_lshr_b32 s60, s55, 11
	s_sub_u32 s61, s55, 0x8000
	s_lshr_b32 s61, s61, 12
	s_add_u32 s61, s61, 16
	s_cmp_lt_u32 s55, 0x8000
	s_cselect_b32 s63, s60, s61
	s_cmp_eq_u32 s63, s56
	s_cbranch_scc1 .Lrp1_pk7
	s_mov_b32 s56, s63
	s_add_u32 s0, s20, 0x0
	s_addc_u32 s1, s21, 0
	global_load_dwordx4 v[160:163], v0, s[0:1]
	global_load_dwordx4 v[164:167], v0, s[0:1] offset:1024
	global_load_dwordx4 v[168:171], v0, s[0:1] offset:2048
	global_load_dwordx4 v[172:175], v0, s[0:1] offset:3072
	s_mul_i32 s60, s56, 0x9000
	s_add_u32 s60, s60, 0x3181000
	s_add_u32 s0, s92, s60
	s_addc_u32 s1, s93, 0
	global_load_dwordx4 v[176:179], v0, s[0:1]
	global_load_dwordx4 v[180:183], v0, s[0:1] offset:1024
	global_load_dwordx4 v[184:187], v0, s[0:1] offset:2048
	global_load_dwordx4 v[188:191], v0, s[0:1] offset:3072
	s_mul_i32 s60, s56, 0x9000
	s_add_u32 s60, s60, 0x3180000
	s_add_u32 s0, s92, s60
	s_addc_u32 s1, s93, 0
	global_load_dwordx4 v[192:195], v0, s[0:1]
	global_load_dwordx4 v[196:199], v0, s[0:1] offset:1024
	global_load_dwordx4 v[200:203], v0, s[0:1] offset:2048
	global_load_dwordx4 v[204:207], v0, s[0:1] offset:3072
	s_waitcnt vmcnt(0)
	v_pk_add_f32 v[176:177], v[176:177], 1.0 op_sel_hi:[1,0]
	v_pk_add_f32 v[178:179], v[178:179], 1.0 op_sel_hi:[1,0]
	v_pk_add_f32 v[180:181], v[180:181], 1.0 op_sel_hi:[1,0]
	v_pk_add_f32 v[182:183], v[182:183], 1.0 op_sel_hi:[1,0]
	v_pk_add_f32 v[184:185], v[184:185], 1.0 op_sel_hi:[1,0]
	v_pk_add_f32 v[186:187], v[186:187], 1.0 op_sel_hi:[1,0]
	v_pk_add_f32 v[188:189], v[188:189], 1.0 op_sel_hi:[1,0]
	v_pk_add_f32 v[190:191], v[190:191], 1.0 op_sel_hi:[1,0]
.Lrp1_pk7:
	s_waitcnt vmcnt(16)
	v_pk_mul_f32 v[102:103], v[4:5], v[4:5]
	v_pk_mul_f32 v[106:107], v[6:7], v[6:7]
	v_pk_fma_f32 v[102:103], v[8:9], v[8:9], v[102:103]
	v_pk_fma_f32 v[106:107], v[10:11], v[10:11], v[106:107]
	v_pk_fma_f32 v[102:103], v[12:13], v[12:13], v[102:103]
	v_pk_fma_f32 v[106:107], v[14:15], v[14:15], v[106:107]
	v_pk_fma_f32 v[102:103], v[16:17], v[16:17], v[102:103]
	v_pk_fma_f32 v[106:107], v[18:19], v[18:19], v[106:107]
	v_pk_add_f32 v[102:103], v[102:103], v[106:107]
	v_add_f32_e32 v102, v102, v103
	s_nop 1
	v_add_f32_dpp v102, v102, v102 quad_perm:[1,0,3,2] row_mask:0xf bank_mask:0xf
	s_nop 1
	v_add_f32_dpp v102, v102, v102 quad_perm:[2,3,0,1] row_mask:0xf bank_mask:0xf
	s_nop 1
	v_add_f32_dpp v102, v102, v102 row_half_mirror row_mask:0xf bank_mask:0xf
	s_nop 1
	v_add_f32_dpp v102, v102, v102 row_mirror row_mask:0xf bank_mask:0xf
	s_nop 1
	v_add_f32_dpp v102, v102, v102 row_bcast:15 row_mask:0xa bank_mask:0xf
	s_nop 1
	v_add_f32_dpp v102, v102, v102 row_bcast:31 row_mask:0xc bank_mask:0xf
	s_nop 1
	v_readlane_b32 s74, v102, 63
	s_nop 2
	v_mov_b32_e32 v102, s74
	v_fmamk_f32 v102, v102, 0x3a800000, v2
	v_mul_f32_e32 v103, 0x4f800000, v102
	v_cmp_gt_f32_e32 vcc, 0xf800000, v102
	s_nop 1
	v_cndmask_b32_e32 v102, v102, v103, vcc
	v_sqrt_f32_e32 v103, v102
	s_nop 0
	v_add_u32_e32 v104, -1, v103
	v_add_u32_e32 v106, 1, v103
	v_fma_f32 v107, -v104, v103, v102
	v_fma_f32 v108, -v106, v103, v102
	v_cmp_ge_f32_e64 s[76:77], 0, v107
	s_nop 1
	v_cndmask_b32_e64 v103, v103, v104, s[76:77]
	v_cmp_lt_f32_e64 s[76:77], 0, v108
	s_nop 1
	v_cndmask_b32_e64 v103, v103, v106, s[76:77]
	v_mul_f32_e32 v104, 0x37800000, v103
	v_cndmask_b32_e32 v103, v103, v104, vcc
	v_cmp_class_f32_e32 vcc, v102, v3
	s_nop 1
	v_cndmask_b32_e32 v102, v103, v102, vcc
	v_div_scale_f32 v103, s[76:77], v102, v102, 1.0
	v_rcp_f32_e32 v104, v103
	v_div_scale_f32 v106, vcc, 1.0, v102, 1.0
	v_fma_f32 v107, -v103, v104, 1.0
	v_fmac_f32_e32 v104, v107, v104
	v_mul_f32_e32 v107, v106, v104
	v_fma_f32 v108, -v103, v107, v106
	v_fmac_f32_e32 v107, v108, v104
	v_fma_f32 v103, -v103, v107, v106
	v_div_fmas_f32 v103, v103, v104, v107
	v_div_fixup_f32 v110, v103, v102, 1.0
	s_lshl_b32 s60, s55, 11
	s_add_u32 s70, s78, s60
	s_addc_u32 s71, s79, 0
	v_pk_mul_f32 v[112:113], v[4:5], v[110:111] op_sel_hi:[1,0]
	v_pk_mul_f32 v[114:115], v[6:7], v[110:111] op_sel_hi:[1,0]
	v_pk_mul_f32 v[116:117], v[8:9], v[110:111] op_sel_hi:[1,0]
	v_pk_mul_f32 v[118:119], v[10:11], v[110:111] op_sel_hi:[1,0]
	v_pk_mul_f32 v[120:121], v[12:13], v[110:111] op_sel_hi:[1,0]
	v_pk_mul_f32 v[122:123], v[14:15], v[110:111] op_sel_hi:[1,0]
	v_pk_mul_f32 v[124:125], v[16:17], v[110:111] op_sel_hi:[1,0]
	v_pk_mul_f32 v[100:101], v[18:19], v[110:111] op_sel_hi:[1,0]
	v_pk_mul_f32 v[112:113], v[160:161], v[112:113]
	v_pk_mul_f32 v[114:115], v[162:163], v[114:115]
	v_pk_mul_f32 v[116:117], v[164:165], v[116:117]
	v_pk_mul_f32 v[118:119], v[166:167], v[118:119]
	v_pk_mul_f32 v[120:121], v[168:169], v[120:121]
	v_pk_mul_f32 v[122:123], v[170:171], v[122:123]
	v_pk_mul_f32 v[124:125], v[172:173], v[124:125]
	v_pk_mul_f32 v[100:101], v[174:175], v[100:101]
	v_pk_fma_f32 v[112:113], v[176:177], v[112:113], v[192:193]
	v_pk_fma_f32 v[114:115], v[178:179], v[114:115], v[194:195]
	v_pk_fma_f32 v[116:117], v[180:181], v[116:117], v[196:197]
	v_pk_fma_f32 v[118:119], v[182:183], v[118:119], v[198:199]
	v_pk_fma_f32 v[120:121], v[184:185], v[120:121], v[200:201]
	v_pk_fma_f32 v[122:123], v[186:187], v[122:123], v[202:203]
	v_pk_fma_f32 v[124:125], v[188:189], v[124:125], v[204:205]
	v_pk_fma_f32 v[100:101], v[190:191], v[100:101], v[206:207]
	v_cvt_pk_bf16_f32 v240, v112, v113
	v_cvt_pk_bf16_f32 v241, v114, v115
	v_cvt_pk_bf16_f32 v242, v116, v117
	v_cvt_pk_bf16_f32 v243, v118, v119
	v_cvt_pk_bf16_f32 v244, v120, v121
	v_cvt_pk_bf16_f32 v245, v122, v123
	v_cvt_pk_bf16_f32 v246, v124, v125
	v_cvt_pk_bf16_f32 v247, v100, v101
	global_store_dwordx2 v1, v[240:241], s[70:71]
	global_store_dwordx2 v1, v[242:243], s[70:71] offset:512
	global_store_dwordx2 v1, v[244:245], s[70:71] offset:1024
	global_store_dwordx2 v1, v[246:247], s[70:71] offset:1536
	s_add_u32 s55, s55, 8
	s_add_u32 s57, s55, 16
	s_min_u32 s57, s57, s54
	s_cmp_lt_u32 s57, 0x8000
	s_cselect_b32 s64, s8, s10
	s_cselect_b32 s65, s9, s11
	s_cselect_b32 s60, 0, 0x8000
	s_sub_u32 s60, s57, s60
	s_lshl_b32 s60, s60, 12
	s_add_u32 s64, s64, s60
	s_addc_u32 s65, s65, 0
	global_load_dwordx4 v[4:7], v0, s[64:65] nt
	global_load_dwordx4 v[8:11], v0, s[64:65] offset:1024 nt
	global_load_dwordx4 v[12:15], v0, s[64:65] offset:2048 nt
	global_load_dwordx4 v[16:19], v0, s[64:65] offset:3072 nt
	s_lshr_b32 s60, s55, 11
	s_sub_u32 s61, s55, 0x8000
	s_lshr_b32 s61, s61, 12
	s_add_u32 s61, s61, 16
	s_cmp_lt_u32 s55, 0x8000
	s_cselect_b32 s63, s60, s61
	s_cmp_eq_u32 s63, s56
	s_cbranch_scc1 .Lrp1_pk8
; template <bool HAS_F, bool HAS_H>
; __device__ __forceinline__ void phase_rows(const Params& p, int sp, int sn, float resw, bool from_input, bool write_x = true) {
;     ...
;             const float* sh = mod + b * 9216 + sn * 3072; const float* scl = sh + 1024; const float* gq = p.in[6] + sn * D;
; #pragma unroll
;             for (int j = 0; j < 4; ++j) { const f32x4 a = *(const f32x4*)(sh + 4 * lane + 256 * j), s = *(const f32x4*)(scl + 4 * lane + 256 * j), q = *(const f32x4*)(gq + 4 * lane + 256 * j);
	s_mov_b32 s56, s63
	s_add_u32 s0, s20, 0x0
	s_addc_u32 s1, s21, 0
	global_load_dwordx4 v[160:163], v0, s[0:1]
	global_load_dwordx4 v[164:167], v0, s[0:1] offset:1024
	global_load_dwordx4 v[168:171], v0, s[0:1] offset:2048
	global_load_dwordx4 v[172:175], v0, s[0:1] offset:3072
	s_mul_i32 s60, s56, 0x9000
	s_add_u32 s60, s60, 0x3181000
	s_add_u32 s0, s92, s60
	s_addc_u32 s1, s93, 0
	global_load_dwordx4 v[176:179], v0, s[0:1]
	global_load_dwordx4 v[180:183], v0, s[0:1] offset:1024
	global_load_dwordx4 v[184:187], v0, s[0:1] offset:2048
	global_load_dwordx4 v[188:191], v0, s[0:1] offset:3072
	s_mul_i32 s60, s56, 0x9000
	s_add_u32 s60, s60, 0x3180000
	s_add_u32 s0, s92, s60
	s_addc_u32 s1, s93, 0
	global_load_dwordx4 v[192:195], v0, s[0:1]
	global_load_dwordx4 v[196:199], v0, s[0:1] offset:1024
	global_load_dwordx4 v[200:203], v0, s[0:1] offset:2048
	global_load_dwordx4 v[204:207], v0, s[0:1] offset:3072
	s_waitcnt vmcnt(0)
	v_pk_add_f32 v[176:177], v[176:177], 1.0 op_sel_hi:[1,0]
	v_pk_add_f32 v[178:179], v[178:179], 1.0 op_sel_hi:[1,0]
	v_pk_add_f32 v[180:181], v[180:181], 1.0 op_sel_hi:[1,0]
	v_pk_add_f32 v[182:183], v[182:183], 1.0 op_sel_hi:[1,0]
	v_pk_add_f32 v[184:185], v[184:185], 1.0 op_sel_hi:[1,0]
	v_pk_add_f32 v[186:187], v[186:187], 1.0 op_sel_hi:[1,0]
	v_pk_add_f32 v[188:189], v[188:189], 1.0 op_sel_hi:[1,0]
	v_pk_add_f32 v[190:191], v[190:191], 1.0 op_sel_hi:[1,0]
; __device__ __forceinline__ unsigned pk_bf16(float lo, float hi) { const f32x2 v = {lo, hi}; const bf16x2_t b = __builtin_convertvector(v, bf16x2_t); return __builtin_bit_cast(unsigned, b); }
; template <bool HAS_F, bool HAS_H>
; __device__ __forceinline__ void phase_rows(const Params& p, int sp, int sn, float resw, bool from_input, bool write_x = true) {
;     ...
;     for (int row = gw; row < T; row += NGW) {
;         const int b = row_batch(row);
;         const float* xin = !from_input ? p.out + (size_t)row * D : (row < TP ? p.in[0] + (size_t)row * D : p.in[1] + (size_t)(row - TP) * D);
;         f32x4 v[4];
; #pragma unroll
;         for (int j = 0; j < 4; ++j) v[j] = *(const f32x4*)(xin + 4 * lane + 256 * j);
;     ...
;         if (HAS_H) {
;             float ss = 0.f;
; #pragma unroll
;             for (int j = 0; j < 4; ++j) ss += (v[j].x * v[j].x + v[j].y * v[j].y) + (v[j].z * v[j].z + v[j].w * v[j].w);
;             const float rs = 1.0f / sqrtf(wave_sum(ss) * (1.0f / D) + EPS);
;             const float* sh = mod + b * 9216 + sn * 3072; const float* scl = sh + 1024; const float* gq = p.in[6] + sn * D;
; #pragma unroll
;             for (int j = 0; j < 4; ++j) { const f32x4 a = *(const f32x4*)(sh + 4 * lane + 256 * j), s = *(const f32x4*)(scl + 4 * lane + 256 * j), q = *(const f32x4*)(gq + 4 * lane + 256 * j);
;                 const f32x4 h = (v[j] * rs * q) * (s + 1.0f) + a;
;                 u32x2 w; w.x = pk_bf16(h.x, h.y); w.y = pk_bf16(h.z, h.w);
;                 *(u32x2*)(H + (size_t)row * D + 4 * lane + 256 * j) = w; }
.Lrp1_pk8:
	s_waitcnt vmcnt(16)
	v_pk_mul_f32 v[102:103], v[36:37], v[36:37]
	v_pk_mul_f32 v[106:107], v[38:39], v[38:39]
	v_pk_fma_f32 v[102:103], v[40:41], v[40:41], v[102:103]
	v_pk_fma_f32 v[106:107], v[42:43], v[42:43], v[106:107]
	v_pk_fma_f32 v[102:103], v[44:45], v[44:45], v[102:103]
	v_pk_fma_f32 v[106:107], v[46:47], v[46:47], v[106:107]
	v_pk_fma_f32 v[102:103], v[48:49], v[48:49], v[102:103]
	v_pk_fma_f32 v[106:107], v[50:51], v[50:51], v[106:107]
	v_pk_add_f32 v[102:103], v[102:103], v[106:107]
	v_add_f32_e32 v102, v102, v103
	s_nop 1
	v_add_f32_dpp v102, v102, v102 quad_perm:[1,0,3,2] row_mask:0xf bank_mask:0xf
	s_nop 1
	v_add_f32_dpp v102, v102, v102 quad_perm:[2,3,0,1] row_mask:0xf bank_mask:0xf
	s_nop 1
	v_add_f32_dpp v102, v102, v102 row_half_mirror row_mask:0xf bank_mask:0xf
	s_nop 1
	v_add_f32_dpp v102, v102, v102 row_mirror row_mask:0xf bank_mask:0xf
	s_nop 1
	v_add_f32_dpp v102, v102, v102 row_bcast:15 row_mask:0xa bank_mask:0xf
	s_nop 1
	v_add_f32_dpp v102, v102, v102 row_bcast:31 row_mask:0xc bank_mask:0xf
	s_nop 1
	v_readlane_b32 s74, v102, 63
	s_nop 2
	v_mov_b32_e32 v102, s74
	v_fmamk_f32 v102, v102, 0x3a800000, v2
	v_mul_f32_e32 v103, 0x4f800000, v102
	v_cmp_gt_f32_e32 vcc, 0xf800000, v102
	s_nop 1
	v_cndmask_b32_e32 v102, v102, v103, vcc
	v_sqrt_f32_e32 v103, v102
	s_nop 0
	v_add_u32_e32 v104, -1, v103
	v_add_u32_e32 v106, 1, v103
	v_fma_f32 v107, -v104, v103, v102
	v_fma_f32 v108, -v106, v103, v102
	v_cmp_ge_f32_e64 s[76:77], 0, v107
	s_nop 1
	v_cndmask_b32_e64 v103, v103, v104, s[76:77]
	v_cmp_lt_f32_e64 s[76:77], 0, v108
	s_nop 1
	v_cndmask_b32_e64 v103, v103, v106, s[76:77]
	v_mul_f32_e32 v104, 0x37800000, v103
	v_cndmask_b32_e32 v103, v103, v104, vcc
	v_cmp_class_f32_e32 vcc, v102, v3
	s_nop 1
	v_cndmask_b32_e32 v102, v103, v102, vcc
	v_div_scale_f32 v103, s[76:77], v102, v102, 1.0
	v_rcp_f32_e32 v104, v103
	v_div_scale_f32 v106, vcc, 1.0, v102, 1.0
	v_fma_f32 v107, -v103, v104, 1.0
	v_fmac_f32_e32 v104, v107, v104
	v_mul_f32_e32 v107, v106, v104
	v_fma_f32 v108, -v103, v107, v106
	v_fmac_f32_e32 v107, v108, v104
	v_fma_f32 v103, -v103, v107, v106
	v_div_fmas_f32 v103, v103, v104, v107
	v_div_fixup_f32 v110, v103, v102, 1.0
	s_lshl_b32 s60, s55, 11
	s_add_u32 s70, s78, s60
	s_addc_u32 s71, s79, 0
	v_pk_mul_f32 v[112:113], v[36:37], v[110:111] op_sel_hi:[1,0]
	v_pk_mul_f32 v[114:115], v[38:39], v[110:111] op_sel_hi:[1,0]
	v_pk_mul_f32 v[116:117], v[40:41], v[110:111] op_sel_hi:[1,0]
	v_pk_mul_f32 v[118:119], v[42:43], v[110:111] op_sel_hi:[1,0]
	v_pk_mul_f32 v[120:121], v[44:45], v[110:111] op_sel_hi:[1,0]
	v_pk_mul_f32 v[122:123], v[46:47], v[110:111] op_sel_hi:[1,0]
	v_pk_mul_f32 v[124:125], v[48:49], v[110:111] op_sel_hi:[1,0]
	v_pk_mul_f32 v[100:101], v[50:51], v[110:111] op_sel_hi:[1,0]
	v_pk_mul_f32 v[112:113], v[160:161], v[112:113]
	v_pk_mul_f32 v[114:115], v[162:163], v[114:115]
	v_pk_mul_f32 v[116:117], v[164:165], v[116:117]
	v_pk_mul_f32 v[118:119], v[166:167], v[118:119]
	v_pk_mul_f32 v[120:121], v[168:169], v[120:121]
	v_pk_mul_f32 v[122:123], v[170:171], v[122:123]
	v_pk_mul_f32 v[124:125], v[172:173], v[124:125]
	v_pk_mul_f32 v[100:101], v[174:175], v[100:101]
	v_pk_fma_f32 v[112:113], v[176:177], v[112:113], v[192:193]
	v_pk_fma_f32 v[114:115], v[178:179], v[114:115], v[194:195]
	v_pk_fma_f32 v[116:117], v[180:181], v[116:117], v[196:197]
	v_pk_fma_f32 v[118:119], v[182:183], v[118:119], v[198:199]
	v_pk_fma_f32 v[120:121], v[184:185], v[120:121], v[200:201]
	v_pk_fma_f32 v[122:123], v[186:187], v[122:123], v[202:203]
	v_pk_fma_f32 v[124:125], v[188:189], v[124:125], v[204:205]
	v_pk_fma_f32 v[100:101], v[190:191], v[100:101], v[206:207]
	v_cvt_pk_bf16_f32 v240, v112, v113
	v_cvt_pk_bf16_f32 v241, v114, v115
	v_cvt_pk_bf16_f32 v242, v116, v117
	v_cvt_pk_bf16_f32 v243, v118, v119
	v_cvt_pk_bf16_f32 v244, v120, v121
	v_cvt_pk_bf16_f32 v245, v122, v123
	v_cvt_pk_bf16_f32 v246, v124, v125
	v_cvt_pk_bf16_f32 v247, v100, v101
	global_store_dwordx2 v1, v[240:241], s[70:71]
	global_store_dwordx2 v1, v[242:243], s[70:71] offset:512
	global_store_dwordx2 v1, v[244:245], s[70:71] offset:1024
	global_store_dwordx2 v1, v[246:247], s[70:71] offset:1536
	s_add_u32 s55, s55, 8
	s_add_u32 s57, s55, 16
	s_min_u32 s57, s57, s54
	s_cmp_lt_u32 s57, 0x8000
	s_cselect_b32 s64, s8, s10
	s_cselect_b32 s65, s9, s11
	s_cselect_b32 s60, 0, 0x8000
	s_sub_u32 s60, s57, s60
	s_lshl_b32 s60, s60, 12
	s_add_u32 s64, s64, s60
	s_addc_u32 s65, s65, 0
	global_load_dwordx4 v[36:39], v0, s[64:65] nt
	global_load_dwordx4 v[40:43], v0, s[64:65] offset:1024 nt
	global_load_dwordx4 v[44:47], v0, s[64:65] offset:2048 nt
	global_load_dwordx4 v[48:51], v0, s[64:65] offset:3072 nt
	s_lshr_b32 s60, s55, 11
	s_sub_u32 s61, s55, 0x8000
	s_lshr_b32 s61, s61, 12
	s_add_u32 s61, s61, 16
	s_cmp_lt_u32 s55, 0x8000
	s_cselect_b32 s63, s60, s61
	s_cmp_eq_u32 s63, s56
	s_cbranch_scc1 .Lrp1_pk9
	s_mov_b32 s56, s63
	s_add_u32 s0, s20, 0x0
	s_addc_u32 s1, s21, 0
	global_load_dwordx4 v[160:163], v0, s[0:1]
	global_load_dwordx4 v[164:167], v0, s[0:1] offset:1024
	global_load_dwordx4 v[168:171], v0, s[0:1] offset:2048
	global_load_dwordx4 v[172:175], v0, s[0:1] offset:3072
	s_mul_i32 s60, s56, 0x9000
	s_add_u32 s60, s60, 0x3181000
	s_add_u32 s0, s92, s60
	s_addc_u32 s1, s93, 0
	global_load_dwordx4 v[176:179], v0, s[0:1]
	global_load_dwordx4 v[180:183], v0, s[0:1] offset:1024
	global_load_dwordx4 v[184:187], v0, s[0:1] offset:2048
	global_load_dwordx4 v[188:191], v0, s[0:1] offset:3072
	s_mul_i32 s60, s56, 0x9000
	s_add_u32 s60, s60, 0x3180000
	s_add_u32 s0, s92, s60
	s_addc_u32 s1, s93, 0
	global_load_dwordx4 v[192:195], v0, s[0:1]
	global_load_dwordx4 v[196:199], v0, s[0:1] offset:1024
	global_load_dwordx4 v[200:203], v0, s[0:1] offset:2048
	global_load_dwordx4 v[204:207], v0, s[0:1] offset:3072
	s_waitcnt vmcnt(0)
	v_pk_add_f32 v[176:177], v[176:177], 1.0 op_sel_hi:[1,0]
	v_pk_add_f32 v[178:179], v[178:179], 1.0 op_sel_hi:[1,0]
	v_pk_add_f32 v[180:181], v[180:181], 1.0 op_sel_hi:[1,0]
	v_pk_add_f32 v[182:183], v[182:183], 1.0 op_sel_hi:[1,0]
	v_pk_add_f32 v[184:185], v[184:185], 1.0 op_sel_hi:[1,0]
	v_pk_add_f32 v[186:187], v[186:187], 1.0 op_sel_hi:[1,0]
	v_pk_add_f32 v[188:189], v[188:189], 1.0 op_sel_hi:[1,0]
	v_pk_add_f32 v[190:191], v[190:191], 1.0 op_sel_hi:[1,0]

; __device__ __forceinline__ float lo_bf(unsigned w) { return __uint_as_float(w << 16); }
; __device__ __forceinline__ float hi_bf(unsigned w) { return __uint_as_float(w & 0xffff0000u); }
; template <bool HAS_F, bool HAS_H>
; __device__ __forceinline__ void phase_rows(const Params& p, int sp, int sn, float resw, bool from_input, bool write_x = true) {
;     ...
;     for (int row = gw; row < T; row += NGW) {
;         const int b = row_batch(row);
;         const float* xin = !from_input ? p.out + (size_t)row * D : (row < TP ? p.in[0] + (size_t)row * D : p.in[1] + (size_t)(row - TP) * D);
;         f32x4 v[4];
; #pragma unroll
;         for (int j = 0; j < 4; ++j) v[j] = *(const f32x4*)(xin + 4 * lane + 256 * j);
;         if (HAS_F) {
;             f32x4 f[4]; float ss = 0.f;
; #pragma unroll
;             for (int j = 0; j < 4; ++j) { const u32x2 w = *(const u32x2*)(F + (size_t)row * D + 4 * lane + 256 * j);
;                 f[j] = (f32x4){lo_bf(w.x), hi_bf(w.x), lo_bf(w.y), hi_bf(w.y)}; ss += (f[j].x * f[j].x + f[j].y * f[j].y) + (f[j].z * f[j].z + f[j].w * f[j].w); }
;             const float rs = 1.0f / sqrtf(wave_sum(ss) * (1.0f / D) + EPS) * resw;
;             const float* gate = mod + b * 9216 + sp * 3072 + 2048; const float* gp = p.in[7] + sp * D;
; #pragma unroll
;             for (int j = 0; j < 4; ++j) { const f32x4 g = *(const f32x4*)(gate + 4 * lane + 256 * j), q = *(const f32x4*)(gp + 4 * lane + 256 * j);
.Lrp4_chunk1:
	s_mul_i32 s53, s51, 384
	s_cmp_ge_u32 s53, 0x18000
	s_cbranch_scc1 .Lrp4_done2
	s_add_u32 s53, s53, s50
	s_add_u32 s54, s53, 376
	s_mov_b32 s56, -1
	s_mov_b32 s55, s53
	s_add_u32 s57, s53, 0
	s_cmp_lt_u32 s57, 0x8000
	s_cselect_b32 s64, s8, s10
	s_cselect_b32 s65, s9, s11
	s_cselect_b32 s60, 0, 0x8000
	s_sub_u32 s60, s57, s60
	s_lshl_b32 s60, s60, 12
	s_add_u32 s64, s64, s60
	s_addc_u32 s65, s65, 0
	s_lshl_b32 s60, s57, 11
	s_add_u32 s66, s82, s60
	s_addc_u32 s67, s83, 0
	global_load_dwordx4 v[4:7], v0, s[64:65] nt
	global_load_dwordx4 v[8:11], v0, s[64:65] offset:1024 nt
	global_load_dwordx4 v[12:15], v0, s[64:65] offset:2048 nt
	global_load_dwordx4 v[16:19], v0, s[64:65] offset:3072 nt
	global_load_dwordx2 v[20:21], v1, s[66:67] nt
	global_load_dwordx2 v[22:23], v1, s[66:67] offset:512 nt
	global_load_dwordx2 v[24:25], v1, s[66:67] offset:1024 nt
	global_load_dwordx2 v[26:27], v1, s[66:67] offset:1536 nt
	s_add_u32 s57, s53, 8
	s_cmp_lt_u32 s57, 0x8000
	s_cselect_b32 s64, s8, s10
	s_cselect_b32 s65, s9, s11
	s_cselect_b32 s60, 0, 0x8000
	s_sub_u32 s60, s57, s60
	s_lshl_b32 s60, s60, 12
	s_add_u32 s64, s64, s60
	s_addc_u32 s65, s65, 0
	s_lshl_b32 s60, s57, 11
	s_add_u32 s66, s82, s60
	s_addc_u32 s67, s83, 0
	global_load_dwordx4 v[36:39], v0, s[64:65] nt
	global_load_dwordx4 v[40:43], v0, s[64:65] offset:1024 nt
	global_load_dwordx4 v[44:47], v0, s[64:65] offset:2048 nt
	global_load_dwordx4 v[48:51], v0, s[64:65] offset:3072 nt
	global_load_dwordx2 v[52:53], v1, s[66:67] nt
	global_load_dwordx2 v[54:55], v1, s[66:67] offset:512 nt
	global_load_dwordx2 v[56:57], v1, s[66:67] offset:1024 nt
	global_load_dwordx2 v[58:59], v1, s[66:67] offset:1536 nt
	s_add_u32 s57, s55, 16
	s_min_u32 s57, s57, s54
	s_cmp_lt_u32 s57, 0x8000
	s_cselect_b32 s64, s8, s10
	s_cselect_b32 s65, s9, s11
	s_cselect_b32 s60, 0, 0x8000
	s_sub_u32 s60, s57, s60
	s_lshl_b32 s60, s60, 12
	s_add_u32 s64, s64, s60
	s_addc_u32 s65, s65, 0
	s_lshl_b32 s60, s57, 11
	s_add_u32 s66, s82, s60
	s_addc_u32 s67, s83, 0
	global_load_dwordx4 v[68:71], v0, s[64:65] nt
	global_load_dwordx4 v[72:75], v0, s[64:65] offset:1024 nt
	global_load_dwordx4 v[76:79], v0, s[64:65] offset:2048 nt
	global_load_dwordx4 v[80:83], v0, s[64:65] offset:3072 nt
	global_load_dwordx2 v[84:85], v1, s[66:67] nt
	global_load_dwordx2 v[86:87], v1, s[66:67] offset:512 nt
	global_load_dwordx2 v[88:89], v1, s[66:67] offset:1024 nt
	global_load_dwordx2 v[90:91], v1, s[66:67] offset:1536 nt
	s_lshr_b32 s60, s55, 11
	s_sub_u32 s61, s55, 0x8000
	s_lshr_b32 s61, s61, 12
	s_add_u32 s61, s61, 16
	s_cmp_lt_u32 s55, 0x8000
	s_cselect_b32 s63, s60, s61
	s_cmp_eq_u32 s63, s56
	s_cbranch_scc1 .Lrp4_pk4
	s_mov_b32 s56, s63
	s_mul_i32 s60, s56, 0x9000
	s_add_u32 s60, s60, 0x3182000
	s_add_u32 s0, s92, s60
	s_addc_u32 s1, s93, 0
	global_load_dwordx4 v[160:163], v0, s[0:1]
	global_load_dwordx4 v[164:167], v0, s[0:1] offset:1024
	global_load_dwordx4 v[168:171], v0, s[0:1] offset:2048
	global_load_dwordx4 v[172:175], v0, s[0:1] offset:3072
	s_add_u32 s0, s22, 0x0
	s_addc_u32 s1, s23, 0
	global_load_dwordx4 v[176:179], v0, s[0:1]
	global_load_dwordx4 v[180:183], v0, s[0:1] offset:1024
	global_load_dwordx4 v[184:187], v0, s[0:1] offset:2048
	global_load_dwordx4 v[188:191], v0, s[0:1] offset:3072
	s_add_u32 s0, s20, 0x1000
	s_addc_u32 s1, s21, 0
	global_load_dwordx4 v[192:195], v0, s[0:1]
	global_load_dwordx4 v[196:199], v0, s[0:1] offset:1024
	global_load_dwordx4 v[200:203], v0, s[0:1] offset:2048
	global_load_dwordx4 v[204:207], v0, s[0:1] offset:3072
	s_mul_i32 s60, s56, 0x9000
	s_add_u32 s60, s60, 0x3184000
	s_add_u32 s0, s92, s60
	s_addc_u32 s1, s93, 0
	global_load_dwordx4 v[208:211], v0, s[0:1]
	global_load_dwordx4 v[212:215], v0, s[0:1] offset:1024
	global_load_dwordx4 v[216:219], v0, s[0:1] offset:2048
	global_load_dwordx4 v[220:223], v0, s[0:1] offset:3072
	s_mul_i32 s60, s56, 0x9000
	s_add_u32 s60, s60, 0x3183000
	s_add_u32 s0, s92, s60
	s_addc_u32 s1, s93, 0
	global_load_dwordx4 v[224:227], v0, s[0:1]
	global_load_dwordx4 v[228:231], v0, s[0:1] offset:1024
	global_load_dwordx4 v[232:235], v0, s[0:1] offset:2048
	global_load_dwordx4 v[236:239], v0, s[0:1] offset:3072
	s_waitcnt vmcnt(0)
	v_pk_add_f32 v[208:209], v[208:209], 1.0 op_sel_hi:[1,0]
	v_pk_add_f32 v[210:211], v[210:211], 1.0 op_sel_hi:[1,0]
	v_pk_add_f32 v[212:213], v[212:213], 1.0 op_sel_hi:[1,0]
	v_pk_add_f32 v[214:215], v[214:215], 1.0 op_sel_hi:[1,0]
	v_pk_add_f32 v[216:217], v[216:217], 1.0 op_sel_hi:[1,0]
	v_pk_add_f32 v[218:219], v[218:219], 1.0 op_sel_hi:[1,0]
	v_pk_add_f32 v[220:221], v[220:221], 1.0 op_sel_hi:[1,0]
	v_pk_add_f32 v[222:223], v[222:223], 1.0 op_sel_hi:[1,0]
; __device__ __forceinline__ float lo_bf(unsigned w) { return __uint_as_float(w << 16); }
; __device__ __forceinline__ float hi_bf(unsigned w) { return __uint_as_float(w & 0xffff0000u); }
; template <bool HAS_F, bool HAS_H>
; __device__ __forceinline__ void phase_rows(const Params& p, int sp, int sn, float resw, bool from_input, bool write_x = true) {
;     ...
;         if (HAS_F) {
;             f32x4 f[4]; float ss = 0.f;
; #pragma unroll
;             for (int j = 0; j < 4; ++j) { const u32x2 w = *(const u32x2*)(F + (size_t)row * D + 4 * lane + 256 * j);
;                 f[j] = (f32x4){lo_bf(w.x), hi_bf(w.x), lo_bf(w.y), hi_bf(w.y)}; ss += (f[j].x * f[j].x + f[j].y * f[j].y) + (f[j].z * f[j].z + f[j].w * f[j].w); }
;             const float rs = 1.0f / sqrtf(wave_sum(ss) * (1.0f / D) + EPS) * resw;
;             const float* gate = mod + b * 9216 + sp * 3072 + 2048; const float* gp = p.in[7] + sp * D;
; #pragma unroll
;             for (int j = 0; j < 4; ++j) { const f32x4 g = *(const f32x4*)(gate + 4 * lane + 256 * j), q = *(const f32x4*)(gp + 4 * lane + 256 * j);
;                 v[j] = v[j] + g * (f[j] * rs * q);
;                 if (write_x) *(f32x4*)(p.out + (size_t)row * D + 4 * lane + 256 * j) = v[j]; }
;         }
;         if (HAS_H) {
;             float ss = 0.f;
; #pragma unroll
;             for (int j = 0; j < 4; ++j) ss += (v[j].x * v[j].x + v[j].y * v[j].y) + (v[j].z * v[j].z + v[j].w * v[j].w);
;             const float rs = 1.0f / sqrtf(wave_sum(ss) * (1.0f / D) + EPS);
.Lrp4_pk4:
	s_waitcnt vmcnt(16)
	v_lshlrev_b32_e32 v112, 16, v20
	v_and_b32_e32 v113, 0xffff0000, v20
	v_lshlrev_b32_e32 v114, 16, v21
	v_and_b32_e32 v115, 0xffff0000, v21
	v_lshlrev_b32_e32 v116, 16, v22
	v_and_b32_e32 v117, 0xffff0000, v22
	v_lshlrev_b32_e32 v118, 16, v23
	v_and_b32_e32 v119, 0xffff0000, v23
	v_lshlrev_b32_e32 v120, 16, v24
	v_and_b32_e32 v121, 0xffff0000, v24
	v_lshlrev_b32_e32 v122, 16, v25
	v_and_b32_e32 v123, 0xffff0000, v25
	v_lshlrev_b32_e32 v124, 16, v26
	v_and_b32_e32 v125, 0xffff0000, v26
	v_lshlrev_b32_e32 v100, 16, v27
	v_and_b32_e32 v101, 0xffff0000, v27
	v_pk_mul_f32 v[102:103], v[112:113], v[112:113]
	v_pk_mul_f32 v[106:107], v[114:115], v[114:115]
	v_pk_fma_f32 v[102:103], v[116:117], v[116:117], v[102:103]
	v_pk_fma_f32 v[106:107], v[118:119], v[118:119], v[106:107]
	v_pk_fma_f32 v[102:103], v[120:121], v[120:121], v[102:103]
	v_pk_fma_f32 v[106:107], v[122:123], v[122:123], v[106:107]
	v_pk_fma_f32 v[102:103], v[124:125], v[124:125], v[102:103]
	v_pk_fma_f32 v[106:107], v[100:101], v[100:101], v[106:107]
	v_pk_add_f32 v[102:103], v[102:103], v[106:107]
	v_add_f32_e32 v102, v102, v103
	s_nop 1
	v_add_f32_dpp v102, v102, v102 quad_perm:[1,0,3,2] row_mask:0xf bank_mask:0xf
	s_nop 1
	v_add_f32_dpp v102, v102, v102 quad_perm:[2,3,0,1] row_mask:0xf bank_mask:0xf
	s_nop 1
	v_add_f32_dpp v102, v102, v102 row_half_mirror row_mask:0xf bank_mask:0xf
	s_nop 1
	v_add_f32_dpp v102, v102, v102 row_mirror row_mask:0xf bank_mask:0xf
	s_nop 1
	v_add_f32_dpp v102, v102, v102 row_bcast:15 row_mask:0xa bank_mask:0xf
	s_nop 1
	v_add_f32_dpp v102, v102, v102 row_bcast:31 row_mask:0xc bank_mask:0xf
	s_nop 1
	v_readlane_b32 s74, v102, 63
	s_nop 2
	v_mov_b32_e32 v102, s74
	v_fmamk_f32 v102, v102, 0x3a800000, v2
	v_mul_f32_e32 v103, 0x4f800000, v102
	v_cmp_gt_f32_e32 vcc, 0xf800000, v102
	s_nop 1
	v_cndmask_b32_e32 v102, v102, v103, vcc
	v_sqrt_f32_e32 v103, v102
	s_nop 0
	v_add_u32_e32 v104, -1, v103
	v_add_u32_e32 v106, 1, v103
	v_fma_f32 v107, -v104, v103, v102
	v_fma_f32 v108, -v106, v103, v102
	v_cmp_ge_f32_e64 s[76:77], 0, v107
	s_nop 1
	v_cndmask_b32_e64 v103, v103, v104, s[76:77]
	v_cmp_lt_f32_e64 s[76:77], 0, v108
	s_nop 1
	v_cndmask_b32_e64 v103, v103, v106, s[76:77]
	v_mul_f32_e32 v104, 0x37800000, v103
	v_cndmask_b32_e32 v103, v103, v104, vcc
	v_cmp_class_f32_e32 vcc, v102, v3
	s_nop 1
	v_cndmask_b32_e32 v102, v103, v102, vcc
	v_div_scale_f32 v103, s[76:77], v102, v102, 1.0
	v_rcp_f32_e32 v104, v103
	v_div_scale_f32 v106, vcc, 1.0, v102, 1.0
	v_fma_f32 v107, -v103, v104, 1.0
	v_fmac_f32_e32 v104, v107, v104
	v_mul_f32_e32 v107, v106, v104
	v_fma_f32 v108, -v103, v107, v106
	v_fmac_f32_e32 v107, v108, v104
	v_fma_f32 v103, -v103, v107, v106
	v_div_fmas_f32 v103, v103, v104, v107
	v_div_fixup_f32 v110, v103, v102, 1.0
	v_mul_f32_e32 v110, 0.5, v110
	v_pk_mul_f32 v[112:113], v[112:113], v[110:111] op_sel_hi:[1,0]
	v_pk_mul_f32 v[114:115], v[114:115], v[110:111] op_sel_hi:[1,0]
	v_pk_mul_f32 v[116:117], v[116:117], v[110:111] op_sel_hi:[1,0]
	v_pk_mul_f32 v[118:119], v[118:119], v[110:111] op_sel_hi:[1,0]
	v_pk_mul_f32 v[120:121], v[120:121], v[110:111] op_sel_hi:[1,0]
	v_pk_mul_f32 v[122:123], v[122:123], v[110:111] op_sel_hi:[1,0]
	v_pk_mul_f32 v[124:125], v[124:125], v[110:111] op_sel_hi:[1,0]
	v_pk_mul_f32 v[100:101], v[100:101], v[110:111] op_sel_hi:[1,0]
	v_pk_mul_f32 v[112:113], v[176:177], v[112:113]
	v_pk_mul_f32 v[114:115], v[178:179], v[114:115]
	v_pk_mul_f32 v[116:117], v[180:181], v[116:117]
	v_pk_mul_f32 v[118:119], v[182:183], v[118:119]
	v_pk_mul_f32 v[120:121], v[184:185], v[120:121]
	v_pk_mul_f32 v[122:123], v[186:187], v[122:123]
	v_pk_mul_f32 v[124:125], v[188:189], v[124:125]
	v_pk_mul_f32 v[100:101], v[190:191], v[100:101]
	v_pk_fma_f32 v[4:5], v[160:161], v[112:113], v[4:5]
	v_pk_fma_f32 v[6:7], v[162:163], v[114:115], v[6:7]
	v_pk_fma_f32 v[8:9], v[164:165], v[116:117], v[8:9]
	v_pk_fma_f32 v[10:11], v[166:167], v[118:119], v[10:11]
	v_pk_fma_f32 v[12:13], v[168:169], v[120:121], v[12:13]
	v_pk_fma_f32 v[14:15], v[170:171], v[122:123], v[14:15]
	v_pk_fma_f32 v[16:17], v[172:173], v[124:125], v[16:17]
	v_pk_fma_f32 v[18:19], v[174:175], v[100:101], v[18:19]
	s_lshl_b32 s60, s55, 12
	s_add_u32 s72, s84, s60
	s_addc_u32 s73, s85, 0
	global_store_dwordx4 v0, v[4:7], s[72:73]
	global_store_dwordx4 v0, v[8:11], s[72:73] offset:1024
	global_store_dwordx4 v0, v[12:15], s[72:73] offset:2048
	global_store_dwordx4 v0, v[16:19], s[72:73] offset:3072
	v_pk_mul_f32 v[102:103], v[4:5], v[4:5]
	v_pk_mul_f32 v[106:107], v[6:7], v[6:7]
	v_pk_fma_f32 v[102:103], v[8:9], v[8:9], v[102:103]
	v_pk_fma_f32 v[106:107], v[10:11], v[10:11], v[106:107]
	v_pk_fma_f32 v[102:103], v[12:13], v[12:13], v[102:103]
	v_pk_fma_f32 v[106:107], v[14:15], v[14:15], v[106:107]
	v_pk_fma_f32 v[102:103], v[16:17], v[16:17], v[102:103]
	v_pk_fma_f32 v[106:107], v[18:19], v[18:19], v[106:107]
	v_pk_add_f32 v[102:103], v[102:103], v[106:107]
	v_add_f32_e32 v102, v102, v103
	s_nop 1
	v_add_f32_dpp v102, v102, v102 quad_perm:[1,0,3,2] row_mask:0xf bank_mask:0xf
	s_nop 1
	v_add_f32_dpp v102, v102, v102 quad_perm:[2,3,0,1] row_mask:0xf bank_mask:0xf
	s_nop 1
	v_add_f32_dpp v102, v102, v102 row_half_mirror row_mask:0xf bank_mask:0xf
	s_nop 1
	v_add_f32_dpp v102, v102, v102 row_mirror row_mask:0xf bank_mask:0xf
	s_nop 1
	v_add_f32_dpp v102, v102, v102 row_bcast:15 row_mask:0xa bank_mask:0xf
	s_nop 1
	v_add_f32_dpp v102, v102, v102 row_bcast:31 row_mask:0xc bank_mask:0xf
	s_nop 1
	v_readlane_b32 s74, v102, 63
	s_nop 2
	v_mov_b32_e32 v102, s74
	v_fmamk_f32 v102, v102, 0x3a800000, v2
	v_mul_f32_e32 v103, 0x4f800000, v102
	v_cmp_gt_f32_e32 vcc, 0xf800000, v102
; __device__ __forceinline__ unsigned pk_bf16(float lo, float hi) { const f32x2 v = {lo, hi}; const bf16x2_t b = __builtin_convertvector(v, bf16x2_t); return __builtin_bit_cast(unsigned, b); }
; template <bool HAS_F, bool HAS_H>
; __device__ __forceinline__ void phase_rows(const Params& p, int sp, int sn, float resw, bool from_input, bool write_x = true) {
;     ...
;     for (int row = gw; row < T; row += NGW) {
;         const int b = row_batch(row);
;         const float* xin = !from_input ? p.out + (size_t)row * D : (row < TP ? p.in[0] + (size_t)row * D : p.in[1] + (size_t)(row - TP) * D);
;         f32x4 v[4];
; #pragma unroll
;         for (int j = 0; j < 4; ++j) v[j] = *(const f32x4*)(xin + 4 * lane + 256 * j);
;         if (HAS_F) {
;             f32x4 f[4]; float ss = 0.f;
; #pragma unroll
;             for (int j = 0; j < 4; ++j) { const u32x2 w = *(const u32x2*)(F + (size_t)row * D + 4 * lane + 256 * j);
;     ...
;             const float rs = 1.0f / sqrtf(wave_sum(ss) * (1.0f / D) + EPS);
;             const float* sh = mod + b * 9216 + sn * 3072; const float* scl = sh + 1024; const float* gq = p.in[6] + sn * D;
; #pragma unroll
;             for (int j = 0; j < 4; ++j) { const f32x4 a = *(const f32x4*)(sh + 4 * lane + 256 * j), s = *(const f32x4*)(scl + 4 * lane + 256 * j), q = *(const f32x4*)(gq + 4 * lane + 256 * j);
;                 const f32x4 h = (v[j] * rs * q) * (s + 1.0f) + a;
;                 u32x2 w; w.x = pk_bf16(h.x, h.y); w.y = pk_bf16(h.z, h.w);
;                 *(u32x2*)(H + (size_t)row * D + 4 * lane + 256 * j) = w; }
	s_nop 1
	v_cndmask_b32_e32 v102, v102, v103, vcc
	v_sqrt_f32_e32 v103, v102
	s_nop 0
	v_add_u32_e32 v104, -1, v103
	v_add_u32_e32 v106, 1, v103
	v_fma_f32 v107, -v104, v103, v102
	v_fma_f32 v108, -v106, v103, v102
	v_cmp_ge_f32_e64 s[76:77], 0, v107
	s_nop 1
	v_cndmask_b32_e64 v103, v103, v104, s[76:77]
	v_cmp_lt_f32_e64 s[76:77], 0, v108
	s_nop 1
	v_cndmask_b32_e64 v103, v103, v106, s[76:77]
	v_mul_f32_e32 v104, 0x37800000, v103
	v_cndmask_b32_e32 v103, v103, v104, vcc
	v_cmp_class_f32_e32 vcc, v102, v3
	s_nop 1
	v_cndmask_b32_e32 v102, v103, v102, vcc
	v_div_scale_f32 v103, s[76:77], v102, v102, 1.0
	v_rcp_f32_e32 v104, v103
	v_div_scale_f32 v106, vcc, 1.0, v102, 1.0
	v_fma_f32 v107, -v103, v104, 1.0
	v_fmac_f32_e32 v104, v107, v104
	v_mul_f32_e32 v107, v106, v104
	v_fma_f32 v108, -v103, v107, v106
	v_fmac_f32_e32 v107, v108, v104
	v_fma_f32 v103, -v103, v107, v106
	v_div_fmas_f32 v103, v103, v104, v107
	v_div_fixup_f32 v110, v103, v102, 1.0
	s_lshl_b32 s60, s55, 11
	s_add_u32 s70, s78, s60
	s_addc_u32 s71, s79, 0
	v_pk_mul_f32 v[112:113], v[4:5], v[110:111] op_sel_hi:[1,0]
	v_pk_mul_f32 v[114:115], v[6:7], v[110:111] op_sel_hi:[1,0]
	v_pk_mul_f32 v[116:117], v[8:9], v[110:111] op_sel_hi:[1,0]
	v_pk_mul_f32 v[118:119], v[10:11], v[110:111] op_sel_hi:[1,0]
	v_pk_mul_f32 v[120:121], v[12:13], v[110:111] op_sel_hi:[1,0]
	v_pk_mul_f32 v[122:123], v[14:15], v[110:111] op_sel_hi:[1,0]
	v_pk_mul_f32 v[124:125], v[16:17], v[110:111] op_sel_hi:[1,0]
	v_pk_mul_f32 v[100:101], v[18:19], v[110:111] op_sel_hi:[1,0]
	v_pk_mul_f32 v[112:113], v[192:193], v[112:113]
	v_pk_mul_f32 v[114:115], v[194:195], v[114:115]
	v_pk_mul_f32 v[116:117], v[196:197], v[116:117]
	v_pk_mul_f32 v[118:119], v[198:199], v[118:119]
	v_pk_mul_f32 v[120:121], v[200:201], v[120:121]
	v_pk_mul_f32 v[122:123], v[202:203], v[122:123]
	v_pk_mul_f32 v[124:125], v[204:205], v[124:125]
	v_pk_mul_f32 v[100:101], v[206:207], v[100:101]
	v_pk_fma_f32 v[112:113], v[208:209], v[112:113], v[224:225]
	v_pk_fma_f32 v[114:115], v[210:211], v[114:115], v[226:227]
	v_pk_fma_f32 v[116:117], v[212:213], v[116:117], v[228:229]
	v_pk_fma_f32 v[118:119], v[214:215], v[118:119], v[230:231]
	v_pk_fma_f32 v[120:121], v[216:217], v[120:121], v[232:233]
	v_pk_fma_f32 v[122:123], v[218:219], v[122:123], v[234:235]
	v_pk_fma_f32 v[124:125], v[220:221], v[124:125], v[236:237]
	v_pk_fma_f32 v[100:101], v[222:223], v[100:101], v[238:239]
	v_cvt_pk_bf16_f32 v240, v112, v113
	v_cvt_pk_bf16_f32 v241, v114, v115
	v_cvt_pk_bf16_f32 v242, v116, v117
	v_cvt_pk_bf16_f32 v243, v118, v119
	v_cvt_pk_bf16_f32 v244, v120, v121
	v_cvt_pk_bf16_f32 v245, v122, v123
	v_cvt_pk_bf16_f32 v246, v124, v125
	v_cvt_pk_bf16_f32 v247, v100, v101
	global_store_dwordx2 v1, v[240:241], s[70:71]
	global_store_dwordx2 v1, v[242:243], s[70:71] offset:512
	global_store_dwordx2 v1, v[244:245], s[70:71] offset:1024
	global_store_dwordx2 v1, v[246:247], s[70:71] offset:1536
	s_add_u32 s55, s55, 8
	s_add_u32 s57, s55, 16
	s_min_u32 s57, s57, s54
	s_cmp_lt_u32 s57, 0x8000
	s_cselect_b32 s64, s8, s10
	s_cselect_b32 s65, s9, s11
	s_cselect_b32 s60, 0, 0x8000
	s_sub_u32 s60, s57, s60
	s_lshl_b32 s60, s60, 12
	s_add_u32 s64, s64, s60
	s_addc_u32 s65, s65, 0
	s_lshl_b32 s60, s57, 11
	s_add_u32 s66, s82, s60
	s_addc_u32 s67, s83, 0
	global_load_dwordx4 v[4:7], v0, s[64:65] nt
	global_load_dwordx4 v[8:11], v0, s[64:65] offset:1024 nt
	global_load_dwordx4 v[12:15], v0, s[64:65] offset:2048 nt
	global_load_dwordx4 v[16:19], v0, s[64:65] offset:3072 nt
	global_load_dwordx2 v[20:21], v1, s[66:67] nt
	global_load_dwordx2 v[22:23], v1, s[66:67] offset:512 nt
	global_load_dwordx2 v[24:25], v1, s[66:67] offset:1024 nt
	global_load_dwordx2 v[26:27], v1, s[66:67] offset:1536 nt
	s_lshr_b32 s60, s55, 11
	s_sub_u32 s61, s55, 0x8000
	s_lshr_b32 s61, s61, 12
	s_add_u32 s61, s61, 16
	s_cmp_lt_u32 s55, 0x8000
	s_cselect_b32 s63, s60, s61
	s_cmp_eq_u32 s63, s56
	s_cbranch_scc1 .Lrp4_pk5
	s_mov_b32 s56, s63
	s_mul_i32 s60, s56, 0x9000
	s_add_u32 s60, s60, 0x3182000
	s_add_u32 s0, s92, s60
	s_addc_u32 s1, s93, 0
	global_load_dwordx4 v[160:163], v0, s[0:1]
	global_load_dwordx4 v[164:167], v0, s[0:1] offset:1024
	global_load_dwordx4 v[168:171], v0, s[0:1] offset:2048
	global_load_dwordx4 v[172:175], v0, s[0:1] offset:3072
	s_add_u32 s0, s22, 0x0
	s_addc_u32 s1, s23, 0
	global_load_dwordx4 v[176:179], v0, s[0:1]
	global_load_dwordx4 v[180:183], v0, s[0:1] offset:1024
	global_load_dwordx4 v[184:187], v0, s[0:1] offset:2048
	global_load_dwordx4 v[188:191], v0, s[0:1] offset:3072
	s_add_u32 s0, s20, 0x1000
	s_addc_u32 s1, s21, 0
	global_load_dwordx4 v[192:195], v0, s[0:1]
	global_load_dwordx4 v[196:199], v0, s[0:1] offset:1024
	global_load_dwordx4 v[200:203], v0, s[0:1] offset:2048
	global_load_dwordx4 v[204:207], v0, s[0:1] offset:3072
	s_mul_i32 s60, s56, 0x9000
	s_add_u32 s60, s60, 0x3184000
	s_add_u32 s0, s92, s60
	s_addc_u32 s1, s93, 0
	global_load_dwordx4 v[208:211], v0, s[0:1]
	global_load_dwordx4 v[212:215], v0, s[0:1] offset:1024
	global_load_dwordx4 v[216:219], v0, s[0:1] offset:2048
	global_load_dwordx4 v[220:223], v0, s[0:1] offset:3072
	s_mul_i32 s60, s56, 0x9000
	s_add_u32 s60, s60, 0x3183000
	s_add_u32 s0, s92, s60
	s_addc_u32 s1, s93, 0
	global_load_dwordx4 v[224:227], v0, s[0:1]
	global_load_dwordx4 v[228:231], v0, s[0:1] offset:1024
	global_load_dwordx4 v[232:235], v0, s[0:1] offset:2048
	global_load_dwordx4 v[236:239], v0, s[0:1] offset:3072
	s_waitcnt vmcnt(0)
	v_pk_add_f32 v[208:209], v[208:209], 1.0 op_sel_hi:[1,0]
	v_pk_add_f32 v[210:211], v[210:211], 1.0 op_sel_hi:[1,0]
	v_pk_add_f32 v[212:213], v[212:213], 1.0 op_sel_hi:[1,0]
	v_pk_add_f32 v[214:215], v[214:215], 1.0 op_sel_hi:[1,0]
	v_pk_add_f32 v[216:217], v[216:217], 1.0 op_sel_hi:[1,0]
	v_pk_add_f32 v[218:219], v[218:219], 1.0 op_sel_hi:[1,0]
	v_pk_add_f32 v[220:221], v[220:221], 1.0 op_sel_hi:[1,0]
	v_pk_add_f32 v[222:223], v[222:223], 1.0 op_sel_hi:[1,0]
; __device__ __forceinline__ float lo_bf(unsigned w) { return __uint_as_float(w << 16); }
; __device__ __forceinline__ float hi_bf(unsigned w) { return __uint_as_float(w & 0xffff0000u); }
; template <bool HAS_F, bool HAS_H>
; __device__ __forceinline__ void phase_rows(const Params& p, int sp, int sn, float resw, bool from_input, bool write_x = true) {
;     ...
;             f32x4 f[4]; float ss = 0.f;
; #pragma unroll
;             for (int j = 0; j < 4; ++j) { const u32x2 w = *(const u32x2*)(F + (size_t)row * D + 4 * lane + 256 * j);
;                 f[j] = (f32x4){lo_bf(w.x), hi_bf(w.x), lo_bf(w.y), hi_bf(w.y)}; ss += (f[j].x * f[j].x + f[j].y * f[j].y) + (f[j].z * f[j].z + f[j].w * f[j].w); }
;             const float rs = 1.0f / sqrtf(wave_sum(ss) * (1.0f / D) + EPS) * resw;
;             const float* gate = mod + b * 9216 + sp * 3072 + 2048; const float* gp = p.in[7] + sp * D;
; #pragma unroll
;             for (int j = 0; j < 4; ++j) { const f32x4 g = *(const f32x4*)(gate + 4 * lane + 256 * j), q = *(const f32x4*)(gp + 4 * lane + 256 * j);
;                 v[j] = v[j] + g * (f[j] * rs * q);
;                 if (write_x) *(f32x4*)(p.out + (size_t)row * D + 4 * lane + 256 * j) = v[j]; }
;         }
;         if (HAS_H) {
;             float ss = 0.f;
; #pragma unroll
;             for (int j = 0; j < 4; ++j) ss += (v[j].x * v[j].x + v[j].y * v[j].y) + (v[j].z * v[j].z + v[j].w * v[j].w);
;             const float rs = 1.0f / sqrtf(wave_sum(ss) * (1.0f / D) + EPS);
.Lrp4_pk5:
	s_waitcnt vmcnt(24)
	v_lshlrev_b32_e32 v112, 16, v52
	v_and_b32_e32 v113, 0xffff0000, v52
	v_lshlrev_b32_e32 v114, 16, v53
	v_and_b32_e32 v115, 0xffff0000, v53
	v_lshlrev_b32_e32 v116, 16, v54
	v_and_b32_e32 v117, 0xffff0000, v54
	v_lshlrev_b32_e32 v118, 16, v55
	v_and_b32_e32 v119, 0xffff0000, v55
	v_lshlrev_b32_e32 v120, 16, v56
	v_and_b32_e32 v121, 0xffff0000, v56
	v_lshlrev_b32_e32 v122, 16, v57
	v_and_b32_e32 v123, 0xffff0000, v57
	v_lshlrev_b32_e32 v124, 16, v58
	v_and_b32_e32 v125, 0xffff0000, v58
	v_lshlrev_b32_e32 v100, 16, v59
	v_and_b32_e32 v101, 0xffff0000, v59
	v_pk_mul_f32 v[102:103], v[112:113], v[112:113]
	v_pk_mul_f32 v[106:107], v[114:115], v[114:115]
	v_pk_fma_f32 v[102:103], v[116:117], v[116:117], v[102:103]
	v_pk_fma_f32 v[106:107], v[118:119], v[118:119], v[106:107]
	v_pk_fma_f32 v[102:103], v[120:121], v[120:121], v[102:103]
	v_pk_fma_f32 v[106:107], v[122:123], v[122:123], v[106:107]
	v_pk_fma_f32 v[102:103], v[124:125], v[124:125], v[102:103]
	v_pk_fma_f32 v[106:107], v[100:101], v[100:101], v[106:107]
	v_pk_add_f32 v[102:103], v[102:103], v[106:107]
	v_add_f32_e32 v102, v102, v103
	s_nop 1
	v_add_f32_dpp v102, v102, v102 quad_perm:[1,0,3,2] row_mask:0xf bank_mask:0xf
	s_nop 1
	v_add_f32_dpp v102, v102, v102 quad_perm:[2,3,0,1] row_mask:0xf bank_mask:0xf
	s_nop 1
	v_add_f32_dpp v102, v102, v102 row_half_mirror row_mask:0xf bank_mask:0xf
	s_nop 1
	v_add_f32_dpp v102, v102, v102 row_mirror row_mask:0xf bank_mask:0xf
	s_nop 1
	v_add_f32_dpp v102, v102, v102 row_bcast:15 row_mask:0xa bank_mask:0xf
	s_nop 1
	v_add_f32_dpp v102, v102, v102 row_bcast:31 row_mask:0xc bank_mask:0xf
	s_nop 1
	v_readlane_b32 s74, v102, 63
	s_nop 2
	v_mov_b32_e32 v102, s74
	v_fmamk_f32 v102, v102, 0x3a800000, v2
	v_mul_f32_e32 v103, 0x4f800000, v102
	v_cmp_gt_f32_e32 vcc, 0xf800000, v102
	s_nop 1
	v_cndmask_b32_e32 v102, v102, v103, vcc
	v_sqrt_f32_e32 v103, v102
	s_nop 0
	v_add_u32_e32 v104, -1, v103
	v_add_u32_e32 v106, 1, v103
	v_fma_f32 v107, -v104, v103, v102
	v_fma_f32 v108, -v106, v103, v102
	v_cmp_ge_f32_e64 s[76:77], 0, v107
	s_nop 1
	v_cndmask_b32_e64 v103, v103, v104, s[76:77]
	v_cmp_lt_f32_e64 s[76:77], 0, v108
	s_nop 1
	v_cndmask_b32_e64 v103, v103, v106, s[76:77]
	v_mul_f32_e32 v104, 0x37800000, v103
	v_cndmask_b32_e32 v103, v103, v104, vcc
	v_cmp_class_f32_e32 vcc, v102, v3
	s_nop 1
	v_cndmask_b32_e32 v102, v103, v102, vcc
	v_div_scale_f32 v103, s[76:77], v102, v102, 1.0
	v_rcp_f32_e32 v104, v103
	v_div_scale_f32 v106, vcc, 1.0, v102, 1.0
	v_fma_f32 v107, -v103, v104, 1.0
	v_fmac_f32_e32 v104, v107, v104
	v_mul_f32_e32 v107, v106, v104
	v_fma_f32 v108, -v103, v107, v106
	v_fmac_f32_e32 v107, v108, v104
	v_fma_f32 v103, -v103, v107, v106
	v_div_fmas_f32 v103, v103, v104, v107
	v_div_fixup_f32 v110, v103, v102, 1.0
	v_mul_f32_e32 v110, 0.5, v110
	v_pk_mul_f32 v[112:113], v[112:113], v[110:111] op_sel_hi:[1,0]
	v_pk_mul_f32 v[114:115], v[114:115], v[110:111] op_sel_hi:[1,0]
	v_pk_mul_f32 v[116:117], v[116:117], v[110:111] op_sel_hi:[1,0]
	v_pk_mul_f32 v[118:119], v[118:119], v[110:111] op_sel_hi:[1,0]
	v_pk_mul_f32 v[120:121], v[120:121], v[110:111] op_sel_hi:[1,0]
	v_pk_mul_f32 v[122:123], v[122:123], v[110:111] op_sel_hi:[1,0]
	v_pk_mul_f32 v[124:125], v[124:125], v[110:111] op_sel_hi:[1,0]
	v_pk_mul_f32 v[100:101], v[100:101], v[110:111] op_sel_hi:[1,0]
	v_pk_mul_f32 v[112:113], v[176:177], v[112:113]
	v_pk_mul_f32 v[114:115], v[178:179], v[114:115]
	v_pk_mul_f32 v[116:117], v[180:181], v[116:117]
	v_pk_mul_f32 v[118:119], v[182:183], v[118:119]
	v_pk_mul_f32 v[120:121], v[184:185], v[120:121]
	v_pk_mul_f32 v[122:123], v[186:187], v[122:123]
	v_pk_mul_f32 v[124:125], v[188:189], v[124:125]
	v_pk_mul_f32 v[100:101], v[190:191], v[100:101]
	v_pk_fma_f32 v[36:37], v[160:161], v[112:113], v[36:37]
	v_pk_fma_f32 v[38:39], v[162:163], v[114:115], v[38:39]
	v_pk_fma_f32 v[40:41], v[164:165], v[116:117], v[40:41]
	v_pk_fma_f32 v[42:43], v[166:167], v[118:119], v[42:43]
	v_pk_fma_f32 v[44:45], v[168:169], v[120:121], v[44:45]
	v_pk_fma_f32 v[46:47], v[170:171], v[122:123], v[46:47]
	v_pk_fma_f32 v[48:49], v[172:173], v[124:125], v[48:49]
	v_pk_fma_f32 v[50:51], v[174:175], v[100:101], v[50:51]
	s_lshl_b32 s60, s55, 12
	s_add_u32 s72, s84, s60
	s_addc_u32 s73, s85, 0
	global_store_dwordx4 v0, v[36:39], s[72:73]
	global_store_dwordx4 v0, v[40:43], s[72:73] offset:1024
	global_store_dwordx4 v0, v[44:47], s[72:73] offset:2048
	global_store_dwordx4 v0, v[48:51], s[72:73] offset:3072
	v_pk_mul_f32 v[102:103], v[36:37], v[36:37]
	v_pk_mul_f32 v[106:107], v[38:39], v[38:39]
	v_pk_fma_f32 v[102:103], v[40:41], v[40:41], v[102:103]
	v_pk_fma_f32 v[106:107], v[42:43], v[42:43], v[106:107]
	v_pk_fma_f32 v[102:103], v[44:45], v[44:45], v[102:103]
	v_pk_fma_f32 v[106:107], v[46:47], v[46:47], v[106:107]
	v_pk_fma_f32 v[102:103], v[48:49], v[48:49], v[102:103]
	v_pk_fma_f32 v[106:107], v[50:51], v[50:51], v[106:107]
	v_pk_add_f32 v[102:103], v[102:103], v[106:107]
	v_add_f32_e32 v102, v102, v103
	s_nop 1
	v_add_f32_dpp v102, v102, v102 quad_perm:[1,0,3,2] row_mask:0xf bank_mask:0xf
	s_nop 1
	v_add_f32_dpp v102, v102, v102 quad_perm:[2,3,0,1] row_mask:0xf bank_mask:0xf
	s_nop 1
	v_add_f32_dpp v102, v102, v102 row_half_mirror row_mask:0xf bank_mask:0xf
	s_nop 1
	v_add_f32_dpp v102, v102, v102 row_mirror row_mask:0xf bank_mask:0xf
	s_nop 1
	v_add_f32_dpp v102, v102, v102 row_bcast:15 row_mask:0xa bank_mask:0xf
	s_nop 1
	v_add_f32_dpp v102, v102, v102 row_bcast:31 row_mask:0xc bank_mask:0xf
	s_nop 1
	v_readlane_b32 s74, v102, 63
	s_nop 2
	v_mov_b32_e32 v102, s74
	v_fmamk_f32 v102, v102, 0x3a800000, v2
	v_mul_f32_e32 v103, 0x4f800000, v102
; __device__ __forceinline__ float lo_bf(unsigned w) { return __uint_as_float(w << 16); }
; template <bool HAS_F, bool HAS_H>
; __device__ __forceinline__ void phase_rows(const Params& p, int sp, int sn, float resw, bool from_input, bool write_x = true) {
;     ...
;     for (int row = gw; row < T; row += NGW) {
;         const int b = row_batch(row);
;         const float* xin = !from_input ? p.out + (size_t)row * D : (row < TP ? p.in[0] + (size_t)row * D : p.in[1] + (size_t)(row - TP) * D);
;         f32x4 v[4];
; #pragma unroll
;         for (int j = 0; j < 4; ++j) v[j] = *(const f32x4*)(xin + 4 * lane + 256 * j);
;         if (HAS_F) {
;             f32x4 f[4]; float ss = 0.f;
; #pragma unroll
;             for (int j = 0; j < 4; ++j) { const u32x2 w = *(const u32x2*)(F + (size_t)row * D + 4 * lane + 256 * j);
;                 f[j] = (f32x4){lo_bf(w.x), hi_bf(w.x), lo_bf(w.y), hi_bf(w.y)}; ss += (f[j].x * f[j].x + f[j].y * f[j].y) + (f[j].z * f[j].z + f[j].w * f[j].w); }
;             const float rs = 1.0f / sqrtf(wave_sum(ss) * (1.0f / D) + EPS) * resw;
;             const float* gate = mod + b * 9216 + sp * 3072 + 2048; const float* gp = p.in[7] + sp * D;
; #pragma unroll
;             for (int j = 0; j < 4; ++j) { const f32x4 g = *(const f32x4*)(gate + 4 * lane + 256 * j), q = *(const f32x4*)(gp + 4 * lane + 256 * j);
;                 v[j] = v[j] + g * (f[j] * rs * q);
;                 if (write_x) *(f32x4*)(p.out + (size_t)row * D + 4 * lane + 256 * j) = v[j]; }
;         }
;         if (HAS_H) {
;             float ss = 0.f;
; #pragma unroll
;             for (int j = 0; j < 4; ++j) ss += (v[j].x * v[j].x + v[j].y * v[j].y) + (v[j].z * v[j].z + v[j].w * v[j].w);
;             const float rs = 1.0f / sqrtf(wave_sum(ss) * (1.0f / D) + EPS);
;             const float* sh = mod + b * 9216 + sn * 3072; const float* scl = sh + 1024; const float* gq = p.in[6] + sn * D;
; #pragma unroll
;             for (int j = 0; j < 4; ++j) { const f32x4 a = *(const f32x4*)(sh + 4 * lane + 256 * j), s = *(const f32x4*)(scl + 4 * lane + 256 * j), q = *(const f32x4*)(gq + 4 * lane + 256 * j);
;                 const f32x4 h = (v[j] * rs * q) * (s + 1.0f) + a;
;                 u32x2 w; w.x = pk_bf16(h.x, h.y); w.y = pk_bf16(h.z, h.w);
;                 *(u32x2*)(H + (size_t)row * D + 4 * lane + 256 * j) = w; }
	v_cmp_gt_f32_e32 vcc, 0xf800000, v102
	s_nop 1
	v_cndmask_b32_e32 v102, v102, v103, vcc
	v_sqrt_f32_e32 v103, v102
	s_nop 0
	v_add_u32_e32 v104, -1, v103
	v_add_u32_e32 v106, 1, v103
	v_fma_f32 v107, -v104, v103, v102
	v_fma_f32 v108, -v106, v103, v102
	v_cmp_ge_f32_e64 s[76:77], 0, v107
	s_nop 1
	v_cndmask_b32_e64 v103, v103, v104, s[76:77]
	v_cmp_lt_f32_e64 s[76:77], 0, v108
	s_nop 1
	v_cndmask_b32_e64 v103, v103, v106, s[76:77]
	v_mul_f32_e32 v104, 0x37800000, v103
	v_cndmask_b32_e32 v103, v103, v104, vcc
	v_cmp_class_f32_e32 vcc, v102, v3
	s_nop 1
	v_cndmask_b32_e32 v102, v103, v102, vcc
	v_div_scale_f32 v103, s[76:77], v102, v102, 1.0
	v_rcp_f32_e32 v104, v103
	v_div_scale_f32 v106, vcc, 1.0, v102, 1.0
	v_fma_f32 v107, -v103, v104, 1.0
	v_fmac_f32_e32 v104, v107, v104
	v_mul_f32_e32 v107, v106, v104
	v_fma_f32 v108, -v103, v107, v106
	v_fmac_f32_e32 v107, v108, v104
	v_fma_f32 v103, -v103, v107, v106
	v_div_fmas_f32 v103, v103, v104, v107
	v_div_fixup_f32 v110, v103, v102, 1.0
	s_lshl_b32 s60, s55, 11
	s_add_u32 s70, s78, s60
	s_addc_u32 s71, s79, 0
	v_pk_mul_f32 v[112:113], v[36:37], v[110:111] op_sel_hi:[1,0]
	v_pk_mul_f32 v[114:115], v[38:39], v[110:111] op_sel_hi:[1,0]
	v_pk_mul_f32 v[116:117], v[40:41], v[110:111] op_sel_hi:[1,0]
	v_pk_mul_f32 v[118:119], v[42:43], v[110:111] op_sel_hi:[1,0]
	v_pk_mul_f32 v[120:121], v[44:45], v[110:111] op_sel_hi:[1,0]
	v_pk_mul_f32 v[122:123], v[46:47], v[110:111] op_sel_hi:[1,0]
	v_pk_mul_f32 v[124:125], v[48:49], v[110:111] op_sel_hi:[1,0]
	v_pk_mul_f32 v[100:101], v[50:51], v[110:111] op_sel_hi:[1,0]
	v_pk_mul_f32 v[112:113], v[192:193], v[112:113]
	v_pk_mul_f32 v[114:115], v[194:195], v[114:115]
	v_pk_mul_f32 v[116:117], v[196:197], v[116:117]
	v_pk_mul_f32 v[118:119], v[198:199], v[118:119]
	v_pk_mul_f32 v[120:121], v[200:201], v[120:121]
	v_pk_mul_f32 v[122:123], v[202:203], v[122:123]
	v_pk_mul_f32 v[124:125], v[204:205], v[124:125]
	v_pk_mul_f32 v[100:101], v[206:207], v[100:101]
	v_pk_fma_f32 v[112:113], v[208:209], v[112:113], v[224:225]
	v_pk_fma_f32 v[114:115], v[210:211], v[114:115], v[226:227]
	v_pk_fma_f32 v[116:117], v[212:213], v[116:117], v[228:229]
	v_pk_fma_f32 v[118:119], v[214:215], v[118:119], v[230:231]
	v_pk_fma_f32 v[120:121], v[216:217], v[120:121], v[232:233]
	v_pk_fma_f32 v[122:123], v[218:219], v[122:123], v[234:235]
	v_pk_fma_f32 v[124:125], v[220:221], v[124:125], v[236:237]
	v_pk_fma_f32 v[100:101], v[222:223], v[100:101], v[238:239]
	v_cvt_pk_bf16_f32 v240, v112, v113
	v_cvt_pk_bf16_f32 v241, v114, v115
	v_cvt_pk_bf16_f32 v242, v116, v117
	v_cvt_pk_bf16_f32 v243, v118, v119
	v_cvt_pk_bf16_f32 v244, v120, v121
	v_cvt_pk_bf16_f32 v245, v122, v123
	v_cvt_pk_bf16_f32 v246, v124, v125
	v_cvt_pk_bf16_f32 v247, v100, v101
	global_store_dwordx2 v1, v[240:241], s[70:71]
	global_store_dwordx2 v1, v[242:243], s[70:71] offset:512
	global_store_dwordx2 v1, v[244:245], s[70:71] offset:1024
	global_store_dwordx2 v1, v[246:247], s[70:71] offset:1536
	s_add_u32 s55, s55, 8
	s_add_u32 s57, s55, 16
	s_min_u32 s57, s57, s54
	s_cmp_lt_u32 s57, 0x8000
	s_cselect_b32 s64, s8, s10
	s_cselect_b32 s65, s9, s11
	s_cselect_b32 s60, 0, 0x8000
	s_sub_u32 s60, s57, s60
	s_lshl_b32 s60, s60, 12
	s_add_u32 s64, s64, s60
	s_addc_u32 s65, s65, 0
	s_lshl_b32 s60, s57, 11
	s_add_u32 s66, s82, s60
	s_addc_u32 s67, s83, 0
	global_load_dwordx4 v[36:39], v0, s[64:65] nt
	global_load_dwordx4 v[40:43], v0, s[64:65] offset:1024 nt
	global_load_dwordx4 v[44:47], v0, s[64:65] offset:2048 nt
	global_load_dwordx4 v[48:51], v0, s[64:65] offset:3072 nt
	global_load_dwordx2 v[52:53], v1, s[66:67] nt
	global_load_dwordx2 v[54:55], v1, s[66:67] offset:512 nt
	global_load_dwordx2 v[56:57], v1, s[66:67] offset:1024 nt
	global_load_dwordx2 v[58:59], v1, s[66:67] offset:1536 nt
	s_lshr_b32 s60, s55, 11
	s_sub_u32 s61, s55, 0x8000
	s_lshr_b32 s61, s61, 12
	s_add_u32 s61, s61, 16
	s_cmp_lt_u32 s55, 0x8000
	s_cselect_b32 s63, s60, s61
	s_cmp_eq_u32 s63, s56
	s_cbranch_scc1 .Lrp4_pk6
	s_mov_b32 s56, s63
	s_mul_i32 s60, s56, 0x9000
	s_add_u32 s60, s60, 0x3182000
	s_add_u32 s0, s92, s60
	s_addc_u32 s1, s93, 0
	global_load_dwordx4 v[160:163], v0, s[0:1]
	global_load_dwordx4 v[164:167], v0, s[0:1] offset:1024
	global_load_dwordx4 v[168:171], v0, s[0:1] offset:2048
	global_load_dwordx4 v[172:175], v0, s[0:1] offset:3072
	s_add_u32 s0, s22, 0x0
	s_addc_u32 s1, s23, 0
	global_load_dwordx4 v[176:179], v0, s[0:1]
	global_load_dwordx4 v[180:183], v0, s[0:1] offset:1024
	global_load_dwordx4 v[184:187], v0, s[0:1] offset:2048
	global_load_dwordx4 v[188:191], v0, s[0:1] offset:3072
	s_add_u32 s0, s20, 0x1000
	s_addc_u32 s1, s21, 0
	global_load_dwordx4 v[192:195], v0, s[0:1]
	global_load_dwordx4 v[196:199], v0, s[0:1] offset:1024
	global_load_dwordx4 v[200:203], v0, s[0:1] offset:2048
	global_load_dwordx4 v[204:207], v0, s[0:1] offset:3072
	s_mul_i32 s60, s56, 0x9000
	s_add_u32 s60, s60, 0x3184000
	s_add_u32 s0, s92, s60
	s_addc_u32 s1, s93, 0
	global_load_dwordx4 v[208:211], v0, s[0:1]
	global_load_dwordx4 v[212:215], v0, s[0:1] offset:1024
	global_load_dwordx4 v[216:219], v0, s[0:1] offset:2048
	global_load_dwordx4 v[220:223], v0, s[0:1] offset:3072
	s_mul_i32 s60, s56, 0x9000
	s_add_u32 s60, s60, 0x3183000
	s_add_u32 s0, s92, s60
	s_addc_u32 s1, s93, 0
	global_load_dwordx4 v[224:227], v0, s[0:1]
	global_load_dwordx4 v[228:231], v0, s[0:1] offset:1024
	global_load_dwordx4 v[232:235], v0, s[0:1] offset:2048
	global_load_dwordx4 v[236:239], v0, s[0:1] offset:3072
	s_waitcnt vmcnt(0)
	v_pk_add_f32 v[208:209], v[208:209], 1.0 op_sel_hi:[1,0]
	v_pk_add_f32 v[210:211], v[210:211], 1.0 op_sel_hi:[1,0]
	v_pk_add_f32 v[212:213], v[212:213], 1.0 op_sel_hi:[1,0]
	v_pk_add_f32 v[214:215], v[214:215], 1.0 op_sel_hi:[1,0]
	v_pk_add_f32 v[216:217], v[216:217], 1.0 op_sel_hi:[1,0]
	v_pk_add_f32 v[218:219], v[218:219], 1.0 op_sel_hi:[1,0]
	v_pk_add_f32 v[220:221], v[220:221], 1.0 op_sel_hi:[1,0]
	v_pk_add_f32 v[222:223], v[222:223], 1.0 op_sel_hi:[1,0]

; __device__ __forceinline__ float lo_bf(unsigned w) { return __uint_as_float(w << 16); }
; __device__ __forceinline__ float hi_bf(unsigned w) { return __uint_as_float(w & 0xffff0000u); }
; template <bool HAS_F, bool HAS_H>
; __device__ __forceinline__ void phase_rows(const Params& p, int sp, int sn, float resw, bool from_input, bool write_x = true) {
;     ...
;     for (int row = gw; row < T; row += NGW) {
;         const int b = row_batch(row);
;         const float* xin = !from_input ? p.out + (size_t)row * D : (row < TP ? p.in[0] + (size_t)row * D : p.in[1] + (size_t)(row - TP) * D);
;         f32x4 v[4];
; #pragma unroll
;         for (int j = 0; j < 4; ++j) v[j] = *(const f32x4*)(xin + 4 * lane + 256 * j);
;         if (HAS_F) {
;             f32x4 f[4]; float ss = 0.f;
; #pragma unroll
;             for (int j = 0; j < 4; ++j) { const u32x2 w = *(const u32x2*)(F + (size_t)row * D + 4 * lane + 256 * j);
;                 f[j] = (f32x4){lo_bf(w.x), hi_bf(w.x), lo_bf(w.y), hi_bf(w.y)}; ss += (f[j].x * f[j].x + f[j].y * f[j].y) + (f[j].z * f[j].z + f[j].w * f[j].w); }
;             const float rs = 1.0f / sqrtf(wave_sum(ss) * (1.0f / D) + EPS) * resw;
;             const float* gate = mod + b * 9216 + sp * 3072 + 2048; const float* gp = p.in[7] + sp * D;
; #pragma unroll
;             for (int j = 0; j < 4; ++j) { const f32x4 g = *(const f32x4*)(gate + 4 * lane + 256 * j), q = *(const f32x4*)(gp + 4 * lane + 256 * j);
.Lrp4_loop3:
	s_add_u32 s57, s55, 16
	s_min_u32 s57, s57, s54
	s_cmp_lt_u32 s57, 0x8000
	s_cselect_b32 s64, s8, s10
	s_cselect_b32 s65, s9, s11
	s_cselect_b32 s60, 0, 0x8000
	s_sub_u32 s60, s57, s60
	s_lshl_b32 s60, s60, 12
	s_add_u32 s64, s64, s60
	s_addc_u32 s65, s65, 0
	s_lshl_b32 s60, s57, 11
	s_add_u32 s66, s82, s60
	s_addc_u32 s67, s83, 0
	global_load_dwordx4 v[68:71], v0, s[64:65] nt
	global_load_dwordx4 v[72:75], v0, s[64:65] offset:1024 nt
	global_load_dwordx4 v[76:79], v0, s[64:65] offset:2048 nt
	global_load_dwordx4 v[80:83], v0, s[64:65] offset:3072 nt
	global_load_dwordx2 v[84:85], v1, s[66:67] nt
	global_load_dwordx2 v[86:87], v1, s[66:67] offset:512 nt
	global_load_dwordx2 v[88:89], v1, s[66:67] offset:1024 nt
	global_load_dwordx2 v[90:91], v1, s[66:67] offset:1536 nt
	s_lshr_b32 s60, s55, 11
	s_sub_u32 s61, s55, 0x8000
	s_lshr_b32 s61, s61, 12
	s_add_u32 s61, s61, 16
	s_cmp_lt_u32 s55, 0x8000
	s_cselect_b32 s63, s60, s61
	s_cmp_eq_u32 s63, s56
	s_cbranch_scc1 .Lrp4_pk7
	s_mov_b32 s56, s63
	s_mul_i32 s60, s56, 0x9000
	s_add_u32 s60, s60, 0x3182000
	s_add_u32 s0, s92, s60
	s_addc_u32 s1, s93, 0
	global_load_dwordx4 v[160:163], v0, s[0:1]
	global_load_dwordx4 v[164:167], v0, s[0:1] offset:1024
	global_load_dwordx4 v[168:171], v0, s[0:1] offset:2048
	global_load_dwordx4 v[172:175], v0, s[0:1] offset:3072
	s_add_u32 s0, s22, 0x0
	s_addc_u32 s1, s23, 0
	global_load_dwordx4 v[176:179], v0, s[0:1]
	global_load_dwordx4 v[180:183], v0, s[0:1] offset:1024
	global_load_dwordx4 v[184:187], v0, s[0:1] offset:2048
	global_load_dwordx4 v[188:191], v0, s[0:1] offset:3072
	s_add_u32 s0, s20, 0x1000
	s_addc_u32 s1, s21, 0
	global_load_dwordx4 v[192:195], v0, s[0:1]
	global_load_dwordx4 v[196:199], v0, s[0:1] offset:1024
	global_load_dwordx4 v[200:203], v0, s[0:1] offset:2048
	global_load_dwordx4 v[204:207], v0, s[0:1] offset:3072
	s_mul_i32 s60, s56, 0x9000
	s_add_u32 s60, s60, 0x3184000
	s_add_u32 s0, s92, s60
	s_addc_u32 s1, s93, 0
	global_load_dwordx4 v[208:211], v0, s[0:1]
	global_load_dwordx4 v[212:215], v0, s[0:1] offset:1024
	global_load_dwordx4 v[216:219], v0, s[0:1] offset:2048
	global_load_dwordx4 v[220:223], v0, s[0:1] offset:3072
	s_mul_i32 s60, s56, 0x9000
	s_add_u32 s60, s60, 0x3183000
	s_add_u32 s0, s92, s60
	s_addc_u32 s1, s93, 0
	global_load_dwordx4 v[224:227], v0, s[0:1]
	global_load_dwordx4 v[228:231], v0, s[0:1] offset:1024
	global_load_dwordx4 v[232:235], v0, s[0:1] offset:2048
	global_load_dwordx4 v[236:239], v0, s[0:1] offset:3072
	s_waitcnt vmcnt(0)
	v_pk_add_f32 v[208:209], v[208:209], 1.0 op_sel_hi:[1,0]
	v_pk_add_f32 v[210:211], v[210:211], 1.0 op_sel_hi:[1,0]
	v_pk_add_f32 v[212:213], v[212:213], 1.0 op_sel_hi:[1,0]
	v_pk_add_f32 v[214:215], v[214:215], 1.0 op_sel_hi:[1,0]
	v_pk_add_f32 v[216:217], v[216:217], 1.0 op_sel_hi:[1,0]
	v_pk_add_f32 v[218:219], v[218:219], 1.0 op_sel_hi:[1,0]
	v_pk_add_f32 v[220:221], v[220:221], 1.0 op_sel_hi:[1,0]
	v_pk_add_f32 v[222:223], v[222:223], 1.0 op_sel_hi:[1,0]
.Lrp4_pk7:
	s_waitcnt vmcnt(32)
	v_lshlrev_b32_e32 v112, 16, v20
	v_and_b32_e32 v113, 0xffff0000, v20
	v_lshlrev_b32_e32 v114, 16, v21
	v_and_b32_e32 v115, 0xffff0000, v21
	v_lshlrev_b32_e32 v116, 16, v22
	v_and_b32_e32 v117, 0xffff0000, v22
	v_lshlrev_b32_e32 v118, 16, v23
	v_and_b32_e32 v119, 0xffff0000, v23
	v_lshlrev_b32_e32 v120, 16, v24
	v_and_b32_e32 v121, 0xffff0000, v24
	v_lshlrev_b32_e32 v122, 16, v25
	v_and_b32_e32 v123, 0xffff0000, v25
	v_lshlrev_b32_e32 v124, 16, v26
	v_and_b32_e32 v125, 0xffff0000, v26
	v_lshlrev_b32_e32 v100, 16, v27
	v_and_b32_e32 v101, 0xffff0000, v27
	v_pk_mul_f32 v[102:103], v[112:113], v[112:113]
	v_pk_mul_f32 v[106:107], v[114:115], v[114:115]
	v_pk_fma_f32 v[102:103], v[116:117], v[116:117], v[102:103]
	v_pk_fma_f32 v[106:107], v[118:119], v[118:119], v[106:107]
	v_pk_fma_f32 v[102:103], v[120:121], v[120:121], v[102:103]
	v_pk_fma_f32 v[106:107], v[122:123], v[122:123], v[106:107]
	v_pk_fma_f32 v[102:103], v[124:125], v[124:125], v[102:103]
	v_pk_fma_f32 v[106:107], v[100:101], v[100:101], v[106:107]
	v_pk_add_f32 v[102:103], v[102:103], v[106:107]
	v_add_f32_e32 v102, v102, v103
	s_nop 1
	v_add_f32_dpp v102, v102, v102 quad_perm:[1,0,3,2] row_mask:0xf bank_mask:0xf
	s_nop 1
	v_add_f32_dpp v102, v102, v102 quad_perm:[2,3,0,1] row_mask:0xf bank_mask:0xf
	s_nop 1
	v_add_f32_dpp v102, v102, v102 row_half_mirror row_mask:0xf bank_mask:0xf
	s_nop 1
	v_add_f32_dpp v102, v102, v102 row_mirror row_mask:0xf bank_mask:0xf
	s_nop 1
	v_add_f32_dpp v102, v102, v102 row_bcast:15 row_mask:0xa bank_mask:0xf
	s_nop 1
	v_add_f32_dpp v102, v102, v102 row_bcast:31 row_mask:0xc bank_mask:0xf
	s_nop 1
	v_readlane_b32 s74, v102, 63
	s_nop 2
	v_mov_b32_e32 v102, s74
	v_fmamk_f32 v102, v102, 0x3a800000, v2
	v_mul_f32_e32 v103, 0x4f800000, v102
	v_cmp_gt_f32_e32 vcc, 0xf800000, v102
	s_nop 1
	v_cndmask_b32_e32 v102, v102, v103, vcc
	v_sqrt_f32_e32 v103, v102
	s_nop 0
	v_add_u32_e32 v104, -1, v103
	v_add_u32_e32 v106, 1, v103
	v_fma_f32 v107, -v104, v103, v102
	v_fma_f32 v108, -v106, v103, v102
	v_cmp_ge_f32_e64 s[76:77], 0, v107
	s_nop 1
	v_cndmask_b32_e64 v103, v103, v104, s[76:77]
	v_cmp_lt_f32_e64 s[76:77], 0, v108
	s_nop 1
	v_cndmask_b32_e64 v103, v103, v106, s[76:77]
	v_mul_f32_e32 v104, 0x37800000, v103
	v_cndmask_b32_e32 v103, v103, v104, vcc
	v_cmp_class_f32_e32 vcc, v102, v3
	s_nop 1
	v_cndmask_b32_e32 v102, v103, v102, vcc
	v_div_scale_f32 v103, s[76:77], v102, v102, 1.0
	v_rcp_f32_e32 v104, v103
	v_div_scale_f32 v106, vcc, 1.0, v102, 1.0
	v_fma_f32 v107, -v103, v104, 1.0
	v_fmac_f32_e32 v104, v107, v104
	v_mul_f32_e32 v107, v106, v104
	v_fma_f32 v108, -v103, v107, v106
	v_fmac_f32_e32 v107, v108, v104
; __device__ __forceinline__ unsigned pk_bf16(float lo, float hi) { const f32x2 v = {lo, hi}; const bf16x2_t b = __builtin_convertvector(v, bf16x2_t); return __builtin_bit_cast(unsigned, b); }
; template <bool HAS_F, bool HAS_H>
; __device__ __forceinline__ void phase_rows(const Params& p, int sp, int sn, float resw, bool from_input, bool write_x = true) {
;     ...
;             const float rs = 1.0f / sqrtf(wave_sum(ss) * (1.0f / D) + EPS) * resw;
;             const float* gate = mod + b * 9216 + sp * 3072 + 2048; const float* gp = p.in[7] + sp * D;
; #pragma unroll
;             for (int j = 0; j < 4; ++j) { const f32x4 g = *(const f32x4*)(gate + 4 * lane + 256 * j), q = *(const f32x4*)(gp + 4 * lane + 256 * j);
;                 v[j] = v[j] + g * (f[j] * rs * q);
;                 if (write_x) *(f32x4*)(p.out + (size_t)row * D + 4 * lane + 256 * j) = v[j]; }
;         }
;         if (HAS_H) {
;             float ss = 0.f;
; #pragma unroll
;             for (int j = 0; j < 4; ++j) ss += (v[j].x * v[j].x + v[j].y * v[j].y) + (v[j].z * v[j].z + v[j].w * v[j].w);
;             const float rs = 1.0f / sqrtf(wave_sum(ss) * (1.0f / D) + EPS);
;             const float* sh = mod + b * 9216 + sn * 3072; const float* scl = sh + 1024; const float* gq = p.in[6] + sn * D;
; #pragma unroll
;             for (int j = 0; j < 4; ++j) { const f32x4 a = *(const f32x4*)(sh + 4 * lane + 256 * j), s = *(const f32x4*)(scl + 4 * lane + 256 * j), q = *(const f32x4*)(gq + 4 * lane + 256 * j);
;                 const f32x4 h = (v[j] * rs * q) * (s + 1.0f) + a;
;                 u32x2 w; w.x = pk_bf16(h.x, h.y); w.y = pk_bf16(h.z, h.w);
;                 *(u32x2*)(H + (size_t)row * D + 4 * lane + 256 * j) = w; }
	v_fma_f32 v103, -v103, v107, v106
	v_div_fmas_f32 v103, v103, v104, v107
	v_div_fixup_f32 v110, v103, v102, 1.0
	v_mul_f32_e32 v110, 0.5, v110
	v_pk_mul_f32 v[112:113], v[112:113], v[110:111] op_sel_hi:[1,0]
	v_pk_mul_f32 v[114:115], v[114:115], v[110:111] op_sel_hi:[1,0]
	v_pk_mul_f32 v[116:117], v[116:117], v[110:111] op_sel_hi:[1,0]
	v_pk_mul_f32 v[118:119], v[118:119], v[110:111] op_sel_hi:[1,0]
	v_pk_mul_f32 v[120:121], v[120:121], v[110:111] op_sel_hi:[1,0]
	v_pk_mul_f32 v[122:123], v[122:123], v[110:111] op_sel_hi:[1,0]
	v_pk_mul_f32 v[124:125], v[124:125], v[110:111] op_sel_hi:[1,0]
	v_pk_mul_f32 v[100:101], v[100:101], v[110:111] op_sel_hi:[1,0]
	v_pk_mul_f32 v[112:113], v[176:177], v[112:113]
	v_pk_mul_f32 v[114:115], v[178:179], v[114:115]
	v_pk_mul_f32 v[116:117], v[180:181], v[116:117]
	v_pk_mul_f32 v[118:119], v[182:183], v[118:119]
	v_pk_mul_f32 v[120:121], v[184:185], v[120:121]
	v_pk_mul_f32 v[122:123], v[186:187], v[122:123]
	v_pk_mul_f32 v[124:125], v[188:189], v[124:125]
	v_pk_mul_f32 v[100:101], v[190:191], v[100:101]
	v_pk_fma_f32 v[4:5], v[160:161], v[112:113], v[4:5]
	v_pk_fma_f32 v[6:7], v[162:163], v[114:115], v[6:7]
	v_pk_fma_f32 v[8:9], v[164:165], v[116:117], v[8:9]
	v_pk_fma_f32 v[10:11], v[166:167], v[118:119], v[10:11]
	v_pk_fma_f32 v[12:13], v[168:169], v[120:121], v[12:13]
	v_pk_fma_f32 v[14:15], v[170:171], v[122:123], v[14:15]
	v_pk_fma_f32 v[16:17], v[172:173], v[124:125], v[16:17]
	v_pk_fma_f32 v[18:19], v[174:175], v[100:101], v[18:19]
	s_lshl_b32 s60, s55, 12
	s_add_u32 s72, s84, s60
	s_addc_u32 s73, s85, 0
	global_store_dwordx4 v0, v[4:7], s[72:73]
	global_store_dwordx4 v0, v[8:11], s[72:73] offset:1024
	global_store_dwordx4 v0, v[12:15], s[72:73] offset:2048
	global_store_dwordx4 v0, v[16:19], s[72:73] offset:3072
	v_pk_mul_f32 v[102:103], v[4:5], v[4:5]
	v_pk_mul_f32 v[106:107], v[6:7], v[6:7]
	v_pk_fma_f32 v[102:103], v[8:9], v[8:9], v[102:103]
	v_pk_fma_f32 v[106:107], v[10:11], v[10:11], v[106:107]
	v_pk_fma_f32 v[102:103], v[12:13], v[12:13], v[102:103]
	v_pk_fma_f32 v[106:107], v[14:15], v[14:15], v[106:107]
	v_pk_fma_f32 v[102:103], v[16:17], v[16:17], v[102:103]
	v_pk_fma_f32 v[106:107], v[18:19], v[18:19], v[106:107]
	v_pk_add_f32 v[102:103], v[102:103], v[106:107]
	v_add_f32_e32 v102, v102, v103
	s_nop 1
	v_add_f32_dpp v102, v102, v102 quad_perm:[1,0,3,2] row_mask:0xf bank_mask:0xf
	s_nop 1
	v_add_f32_dpp v102, v102, v102 quad_perm:[2,3,0,1] row_mask:0xf bank_mask:0xf
	s_nop 1
	v_add_f32_dpp v102, v102, v102 row_half_mirror row_mask:0xf bank_mask:0xf
	s_nop 1
	v_add_f32_dpp v102, v102, v102 row_mirror row_mask:0xf bank_mask:0xf
	s_nop 1
	v_add_f32_dpp v102, v102, v102 row_bcast:15 row_mask:0xa bank_mask:0xf
	s_nop 1
	v_add_f32_dpp v102, v102, v102 row_bcast:31 row_mask:0xc bank_mask:0xf
	s_nop 1
	v_readlane_b32 s74, v102, 63
	s_nop 2
	v_mov_b32_e32 v102, s74
	v_fmamk_f32 v102, v102, 0x3a800000, v2
	v_mul_f32_e32 v103, 0x4f800000, v102
	v_cmp_gt_f32_e32 vcc, 0xf800000, v102
	s_nop 1
	v_cndmask_b32_e32 v102, v102, v103, vcc
	v_sqrt_f32_e32 v103, v102
	s_nop 0
	v_add_u32_e32 v104, -1, v103
	v_add_u32_e32 v106, 1, v103
	v_fma_f32 v107, -v104, v103, v102
	v_fma_f32 v108, -v106, v103, v102
	v_cmp_ge_f32_e64 s[76:77], 0, v107
	s_nop 1
	v_cndmask_b32_e64 v103, v103, v104, s[76:77]
	v_cmp_lt_f32_e64 s[76:77], 0, v108
	s_nop 1
	v_cndmask_b32_e64 v103, v103, v106, s[76:77]
	v_mul_f32_e32 v104, 0x37800000, v103
	v_cndmask_b32_e32 v103, v103, v104, vcc
	v_cmp_class_f32_e32 vcc, v102, v3
	s_nop 1
	v_cndmask_b32_e32 v102, v103, v102, vcc
	v_div_scale_f32 v103, s[76:77], v102, v102, 1.0
	v_rcp_f32_e32 v104, v103
	v_div_scale_f32 v106, vcc, 1.0, v102, 1.0
	v_fma_f32 v107, -v103, v104, 1.0
	v_fmac_f32_e32 v104, v107, v104
	v_mul_f32_e32 v107, v106, v104
	v_fma_f32 v108, -v103, v107, v106
	v_fmac_f32_e32 v107, v108, v104
	v_fma_f32 v103, -v103, v107, v106
	v_div_fmas_f32 v103, v103, v104, v107
	v_div_fixup_f32 v110, v103, v102, 1.0
	s_lshl_b32 s60, s55, 11
	s_add_u32 s70, s78, s60
	s_addc_u32 s71, s79, 0
	v_pk_mul_f32 v[112:113], v[4:5], v[110:111] op_sel_hi:[1,0]
	v_pk_mul_f32 v[114:115], v[6:7], v[110:111] op_sel_hi:[1,0]
	v_pk_mul_f32 v[116:117], v[8:9], v[110:111] op_sel_hi:[1,0]
	v_pk_mul_f32 v[118:119], v[10:11], v[110:111] op_sel_hi:[1,0]
	v_pk_mul_f32 v[120:121], v[12:13], v[110:111] op_sel_hi:[1,0]
	v_pk_mul_f32 v[122:123], v[14:15], v[110:111] op_sel_hi:[1,0]
	v_pk_mul_f32 v[124:125], v[16:17], v[110:111] op_sel_hi:[1,0]
	v_pk_mul_f32 v[100:101], v[18:19], v[110:111] op_sel_hi:[1,0]
	v_pk_mul_f32 v[112:113], v[192:193], v[112:113]
	v_pk_mul_f32 v[114:115], v[194:195], v[114:115]
	v_pk_mul_f32 v[116:117], v[196:197], v[116:117]
	v_pk_mul_f32 v[118:119], v[198:199], v[118:119]
	v_pk_mul_f32 v[120:121], v[200:201], v[120:121]
	v_pk_mul_f32 v[122:123], v[202:203], v[122:123]
	v_pk_mul_f32 v[124:125], v[204:205], v[124:125]
	v_pk_mul_f32 v[100:101], v[206:207], v[100:101]
	v_pk_fma_f32 v[112:113], v[208:209], v[112:113], v[224:225]
	v_pk_fma_f32 v[114:115], v[210:211], v[114:115], v[226:227]
	v_pk_fma_f32 v[116:117], v[212:213], v[116:117], v[228:229]
	v_pk_fma_f32 v[118:119], v[214:215], v[118:119], v[230:231]
	v_pk_fma_f32 v[120:121], v[216:217], v[120:121], v[232:233]
	v_pk_fma_f32 v[122:123], v[218:219], v[122:123], v[234:235]
	v_pk_fma_f32 v[124:125], v[220:221], v[124:125], v[236:237]
	v_pk_fma_f32 v[100:101], v[222:223], v[100:101], v[238:239]
	v_cvt_pk_bf16_f32 v240, v112, v113
	v_cvt_pk_bf16_f32 v241, v114, v115
	v_cvt_pk_bf16_f32 v242, v116, v117
	v_cvt_pk_bf16_f32 v243, v118, v119
	v_cvt_pk_bf16_f32 v244, v120, v121
	v_cvt_pk_bf16_f32 v245, v122, v123
	v_cvt_pk_bf16_f32 v246, v124, v125
	v_cvt_pk_bf16_f32 v247, v100, v101
	global_store_dwordx2 v1, v[240:241], s[70:71]
	global_store_dwordx2 v1, v[242:243], s[70:71] offset:512
	global_store_dwordx2 v1, v[244:245], s[70:71] offset:1024
	global_store_dwordx2 v1, v[246:247], s[70:71] offset:1536
	s_add_u32 s55, s55, 8
	s_add_u32 s57, s55, 16
	s_min_u32 s57, s57, s54
	s_cmp_lt_u32 s57, 0x8000
	s_cselect_b32 s64, s8, s10
	s_cselect_b32 s65, s9, s11
	s_cselect_b32 s60, 0, 0x8000
	s_sub_u32 s60, s57, s60
	s_lshl_b32 s60, s60, 12
	s_add_u32 s64, s64, s60
	s_addc_u32 s65, s65, 0
	s_lshl_b32 s60, s57, 11
	s_add_u32 s66, s82, s60
	s_addc_u32 s67, s83, 0
	global_load_dwordx4 v[4:7], v0, s[64:65] nt
	global_load_dwordx4 v[8:11], v0, s[64:65] offset:1024 nt
	global_load_dwordx4 v[12:15], v0, s[64:65] offset:2048 nt
	global_load_dwordx4 v[16:19], v0, s[64:65] offset:3072 nt
	global_load_dwordx2 v[20:21], v1, s[66:67] nt
	global_load_dwordx2 v[22:23], v1, s[66:67] offset:512 nt
	global_load_dwordx2 v[24:25], v1, s[66:67] offset:1024 nt
	global_load_dwordx2 v[26:27], v1, s[66:67] offset:1536 nt
	s_lshr_b32 s60, s55, 11
	s_sub_u32 s61, s55, 0x8000
	s_lshr_b32 s61, s61, 12
	s_add_u32 s61, s61, 16
	s_cmp_lt_u32 s55, 0x8000
	s_cselect_b32 s63, s60, s61
	s_cmp_eq_u32 s63, s56
	s_cbranch_scc1 .Lrp4_pk8
; __device__ __forceinline__ float lo_bf(unsigned w) { return __uint_as_float(w << 16); }
; __device__ __forceinline__ float hi_bf(unsigned w) { return __uint_as_float(w & 0xffff0000u); }
; template <bool HAS_F, bool HAS_H>
; __device__ __forceinline__ void phase_rows(const Params& p, int sp, int sn, float resw, bool from_input, bool write_x = true) {
;     ...
;             f32x4 f[4]; float ss = 0.f;
; #pragma unroll
;             for (int j = 0; j < 4; ++j) { const u32x2 w = *(const u32x2*)(F + (size_t)row * D + 4 * lane + 256 * j);
;                 f[j] = (f32x4){lo_bf(w.x), hi_bf(w.x), lo_bf(w.y), hi_bf(w.y)}; ss += (f[j].x * f[j].x + f[j].y * f[j].y) + (f[j].z * f[j].z + f[j].w * f[j].w); }
;             const float rs = 1.0f / sqrtf(wave_sum(ss) * (1.0f / D) + EPS) * resw;
;             const float* gate = mod + b * 9216 + sp * 3072 + 2048; const float* gp = p.in[7] + sp * D;
; #pragma unroll
;             for (int j = 0; j < 4; ++j) { const f32x4 g = *(const f32x4*)(gate + 4 * lane + 256 * j), q = *(const f32x4*)(gp + 4 * lane + 256 * j);
;                 v[j] = v[j] + g * (f[j] * rs * q);
;                 if (write_x) *(f32x4*)(p.out + (size_t)row * D + 4 * lane + 256 * j) = v[j]; }
;         }
;         if (HAS_H) {
;             float ss = 0.f;
; #pragma unroll
;             for (int j = 0; j < 4; ++j) ss += (v[j].x * v[j].x + v[j].y * v[j].y) + (v[j].z * v[j].z + v[j].w * v[j].w);
;             const float rs = 1.0f / sqrtf(wave_sum(ss) * (1.0f / D) + EPS);
;             const float* sh = mod + b * 9216 + sn * 3072; const float* scl = sh + 1024; const float* gq = p.in[6] + sn * D;
; #pragma unroll
;             for (int j = 0; j < 4; ++j) { const f32x4 a = *(const f32x4*)(sh + 4 * lane + 256 * j), s = *(const f32x4*)(scl + 4 * lane + 256 * j), q = *(const f32x4*)(gq + 4 * lane + 256 * j);
	s_mov_b32 s56, s63
	s_mul_i32 s60, s56, 0x9000
	s_add_u32 s60, s60, 0x3182000
	s_add_u32 s0, s92, s60
	s_addc_u32 s1, s93, 0
	global_load_dwordx4 v[160:163], v0, s[0:1]
	global_load_dwordx4 v[164:167], v0, s[0:1] offset:1024
	global_load_dwordx4 v[168:171], v0, s[0:1] offset:2048
	global_load_dwordx4 v[172:175], v0, s[0:1] offset:3072
	s_add_u32 s0, s22, 0x0
	s_addc_u32 s1, s23, 0
	global_load_dwordx4 v[176:179], v0, s[0:1]
	global_load_dwordx4 v[180:183], v0, s[0:1] offset:1024
	global_load_dwordx4 v[184:187], v0, s[0:1] offset:2048
	global_load_dwordx4 v[188:191], v0, s[0:1] offset:3072
	s_add_u32 s0, s20, 0x1000
	s_addc_u32 s1, s21, 0
	global_load_dwordx4 v[192:195], v0, s[0:1]
	global_load_dwordx4 v[196:199], v0, s[0:1] offset:1024
	global_load_dwordx4 v[200:203], v0, s[0:1] offset:2048
	global_load_dwordx4 v[204:207], v0, s[0:1] offset:3072
	s_mul_i32 s60, s56, 0x9000
	s_add_u32 s60, s60, 0x3184000
	s_add_u32 s0, s92, s60
	s_addc_u32 s1, s93, 0
	global_load_dwordx4 v[208:211], v0, s[0:1]
	global_load_dwordx4 v[212:215], v0, s[0:1] offset:1024
	global_load_dwordx4 v[216:219], v0, s[0:1] offset:2048
	global_load_dwordx4 v[220:223], v0, s[0:1] offset:3072
	s_mul_i32 s60, s56, 0x9000
	s_add_u32 s60, s60, 0x3183000
	s_add_u32 s0, s92, s60
	s_addc_u32 s1, s93, 0
	global_load_dwordx4 v[224:227], v0, s[0:1]
	global_load_dwordx4 v[228:231], v0, s[0:1] offset:1024
	global_load_dwordx4 v[232:235], v0, s[0:1] offset:2048
	global_load_dwordx4 v[236:239], v0, s[0:1] offset:3072
	s_waitcnt vmcnt(0)
	v_pk_add_f32 v[208:209], v[208:209], 1.0 op_sel_hi:[1,0]
	v_pk_add_f32 v[210:211], v[210:211], 1.0 op_sel_hi:[1,0]
	v_pk_add_f32 v[212:213], v[212:213], 1.0 op_sel_hi:[1,0]
	v_pk_add_f32 v[214:215], v[214:215], 1.0 op_sel_hi:[1,0]
	v_pk_add_f32 v[216:217], v[216:217], 1.0 op_sel_hi:[1,0]
	v_pk_add_f32 v[218:219], v[218:219], 1.0 op_sel_hi:[1,0]
	v_pk_add_f32 v[220:221], v[220:221], 1.0 op_sel_hi:[1,0]
	v_pk_add_f32 v[222:223], v[222:223], 1.0 op_sel_hi:[1,0]
.Lrp4_pk8:
	s_waitcnt vmcnt(32)
	v_lshlrev_b32_e32 v112, 16, v52
	v_and_b32_e32 v113, 0xffff0000, v52
	v_lshlrev_b32_e32 v114, 16, v53
	v_and_b32_e32 v115, 0xffff0000, v53
	v_lshlrev_b32_e32 v116, 16, v54
	v_and_b32_e32 v117, 0xffff0000, v54
	v_lshlrev_b32_e32 v118, 16, v55
	v_and_b32_e32 v119, 0xffff0000, v55
	v_lshlrev_b32_e32 v120, 16, v56
	v_and_b32_e32 v121, 0xffff0000, v56
	v_lshlrev_b32_e32 v122, 16, v57
	v_and_b32_e32 v123, 0xffff0000, v57
	v_lshlrev_b32_e32 v124, 16, v58
	v_and_b32_e32 v125, 0xffff0000, v58
	v_lshlrev_b32_e32 v100, 16, v59
	v_and_b32_e32 v101, 0xffff0000, v59
	v_pk_mul_f32 v[102:103], v[112:113], v[112:113]
	v_pk_mul_f32 v[106:107], v[114:115], v[114:115]
	v_pk_fma_f32 v[102:103], v[116:117], v[116:117], v[102:103]
	v_pk_fma_f32 v[106:107], v[118:119], v[118:119], v[106:107]
	v_pk_fma_f32 v[102:103], v[120:121], v[120:121], v[102:103]
	v_pk_fma_f32 v[106:107], v[122:123], v[122:123], v[106:107]
	v_pk_fma_f32 v[102:103], v[124:125], v[124:125], v[102:103]
	v_pk_fma_f32 v[106:107], v[100:101], v[100:101], v[106:107]
	v_pk_add_f32 v[102:103], v[102:103], v[106:107]
	v_add_f32_e32 v102, v102, v103
	s_nop 1
	v_add_f32_dpp v102, v102, v102 quad_perm:[1,0,3,2] row_mask:0xf bank_mask:0xf
	s_nop 1
	v_add_f32_dpp v102, v102, v102 quad_perm:[2,3,0,1] row_mask:0xf bank_mask:0xf
	s_nop 1
	v_add_f32_dpp v102, v102, v102 row_half_mirror row_mask:0xf bank_mask:0xf
	s_nop 1
	v_add_f32_dpp v102, v102, v102 row_mirror row_mask:0xf bank_mask:0xf
	s_nop 1
	v_add_f32_dpp v102, v102, v102 row_bcast:15 row_mask:0xa bank_mask:0xf
	s_nop 1
	v_add_f32_dpp v102, v102, v102 row_bcast:31 row_mask:0xc bank_mask:0xf
	s_nop 1
	v_readlane_b32 s74, v102, 63
	s_nop 2
	v_mov_b32_e32 v102, s74
	v_fmamk_f32 v102, v102, 0x3a800000, v2
	v_mul_f32_e32 v103, 0x4f800000, v102
	v_cmp_gt_f32_e32 vcc, 0xf800000, v102
	s_nop 1
	v_cndmask_b32_e32 v102, v102, v103, vcc
	v_sqrt_f32_e32 v103, v102
	s_nop 0
	v_add_u32_e32 v104, -1, v103
	v_add_u32_e32 v106, 1, v103
	v_fma_f32 v107, -v104, v103, v102
	v_fma_f32 v108, -v106, v103, v102
	v_cmp_ge_f32_e64 s[76:77], 0, v107
	s_nop 1
	v_cndmask_b32_e64 v103, v103, v104, s[76:77]
	v_cmp_lt_f32_e64 s[76:77], 0, v108
	s_nop 1
	v_cndmask_b32_e64 v103, v103, v106, s[76:77]
	v_mul_f32_e32 v104, 0x37800000, v103
	v_cndmask_b32_e32 v103, v103, v104, vcc
	v_cmp_class_f32_e32 vcc, v102, v3
	s_nop 1
	v_cndmask_b32_e32 v102, v103, v102, vcc
	v_div_scale_f32 v103, s[76:77], v102, v102, 1.0
	v_rcp_f32_e32 v104, v103
	v_div_scale_f32 v106, vcc, 1.0, v102, 1.0
	v_fma_f32 v107, -v103, v104, 1.0
	v_fmac_f32_e32 v104, v107, v104
	v_mul_f32_e32 v107, v106, v104
	v_fma_f32 v108, -v103, v107, v106
	v_fmac_f32_e32 v107, v108, v104
	v_fma_f32 v103, -v103, v107, v106
	v_div_fmas_f32 v103, v103, v104, v107
	v_div_fixup_f32 v110, v103, v102, 1.0
	v_mul_f32_e32 v110, 0.5, v110
	v_pk_mul_f32 v[112:113], v[112:113], v[110:111] op_sel_hi:[1,0]
	v_pk_mul_f32 v[114:115], v[114:115], v[110:111] op_sel_hi:[1,0]
	v_pk_mul_f32 v[116:117], v[116:117], v[110:111] op_sel_hi:[1,0]
	v_pk_mul_f32 v[118:119], v[118:119], v[110:111] op_sel_hi:[1,0]
	v_pk_mul_f32 v[120:121], v[120:121], v[110:111] op_sel_hi:[1,0]
	v_pk_mul_f32 v[122:123], v[122:123], v[110:111] op_sel_hi:[1,0]
	v_pk_mul_f32 v[124:125], v[124:125], v[110:111] op_sel_hi:[1,0]
	v_pk_mul_f32 v[100:101], v[100:101], v[110:111] op_sel_hi:[1,0]
	v_pk_mul_f32 v[112:113], v[176:177], v[112:113]
	v_pk_mul_f32 v[114:115], v[178:179], v[114:115]
	v_pk_mul_f32 v[116:117], v[180:181], v[116:117]
	v_pk_mul_f32 v[118:119], v[182:183], v[118:119]
	v_pk_mul_f32 v[120:121], v[184:185], v[120:121]
	v_pk_mul_f32 v[122:123], v[186:187], v[122:123]
	v_pk_mul_f32 v[124:125], v[188:189], v[124:125]
; __device__ __forceinline__ unsigned pk_bf16(float lo, float hi) { const f32x2 v = {lo, hi}; const bf16x2_t b = __builtin_convertvector(v, bf16x2_t); return __builtin_bit_cast(unsigned, b); }
; template <bool HAS_F, bool HAS_H>
; __device__ __forceinline__ void phase_rows(const Params& p, int sp, int sn, float resw, bool from_input, bool write_x = true) {
;     ...
;             for (int j = 0; j < 4; ++j) { const f32x4 g = *(const f32x4*)(gate + 4 * lane + 256 * j), q = *(const f32x4*)(gp + 4 * lane + 256 * j);
;                 v[j] = v[j] + g * (f[j] * rs * q);
;                 if (write_x) *(f32x4*)(p.out + (size_t)row * D + 4 * lane + 256 * j) = v[j]; }
;         }
;         if (HAS_H) {
;             float ss = 0.f;
; #pragma unroll
;             for (int j = 0; j < 4; ++j) ss += (v[j].x * v[j].x + v[j].y * v[j].y) + (v[j].z * v[j].z + v[j].w * v[j].w);
;             const float rs = 1.0f / sqrtf(wave_sum(ss) * (1.0f / D) + EPS);
;             const float* sh = mod + b * 9216 + sn * 3072; const float* scl = sh + 1024; const float* gq = p.in[6] + sn * D;
; #pragma unroll
;             for (int j = 0; j < 4; ++j) { const f32x4 a = *(const f32x4*)(sh + 4 * lane + 256 * j), s = *(const f32x4*)(scl + 4 * lane + 256 * j), q = *(const f32x4*)(gq + 4 * lane + 256 * j);
;                 const f32x4 h = (v[j] * rs * q) * (s + 1.0f) + a;
;                 u32x2 w; w.x = pk_bf16(h.x, h.y); w.y = pk_bf16(h.z, h.w);
;                 *(u32x2*)(H + (size_t)row * D + 4 * lane + 256 * j) = w; }
	v_pk_mul_f32 v[100:101], v[190:191], v[100:101]
	v_pk_fma_f32 v[36:37], v[160:161], v[112:113], v[36:37]
	v_pk_fma_f32 v[38:39], v[162:163], v[114:115], v[38:39]
	v_pk_fma_f32 v[40:41], v[164:165], v[116:117], v[40:41]
	v_pk_fma_f32 v[42:43], v[166:167], v[118:119], v[42:43]
	v_pk_fma_f32 v[44:45], v[168:169], v[120:121], v[44:45]
	v_pk_fma_f32 v[46:47], v[170:171], v[122:123], v[46:47]
	v_pk_fma_f32 v[48:49], v[172:173], v[124:125], v[48:49]
	v_pk_fma_f32 v[50:51], v[174:175], v[100:101], v[50:51]
	s_lshl_b32 s60, s55, 12
	s_add_u32 s72, s84, s60
	s_addc_u32 s73, s85, 0
	global_store_dwordx4 v0, v[36:39], s[72:73]
	global_store_dwordx4 v0, v[40:43], s[72:73] offset:1024
	global_store_dwordx4 v0, v[44:47], s[72:73] offset:2048
	global_store_dwordx4 v0, v[48:51], s[72:73] offset:3072
	v_pk_mul_f32 v[102:103], v[36:37], v[36:37]
	v_pk_mul_f32 v[106:107], v[38:39], v[38:39]
	v_pk_fma_f32 v[102:103], v[40:41], v[40:41], v[102:103]
	v_pk_fma_f32 v[106:107], v[42:43], v[42:43], v[106:107]
	v_pk_fma_f32 v[102:103], v[44:45], v[44:45], v[102:103]
	v_pk_fma_f32 v[106:107], v[46:47], v[46:47], v[106:107]
	v_pk_fma_f32 v[102:103], v[48:49], v[48:49], v[102:103]
	v_pk_fma_f32 v[106:107], v[50:51], v[50:51], v[106:107]
	v_pk_add_f32 v[102:103], v[102:103], v[106:107]
	v_add_f32_e32 v102, v102, v103
	s_nop 1
	v_add_f32_dpp v102, v102, v102 quad_perm:[1,0,3,2] row_mask:0xf bank_mask:0xf
	s_nop 1
	v_add_f32_dpp v102, v102, v102 quad_perm:[2,3,0,1] row_mask:0xf bank_mask:0xf
	s_nop 1
	v_add_f32_dpp v102, v102, v102 row_half_mirror row_mask:0xf bank_mask:0xf
	s_nop 1
	v_add_f32_dpp v102, v102, v102 row_mirror row_mask:0xf bank_mask:0xf
	s_nop 1
	v_add_f32_dpp v102, v102, v102 row_bcast:15 row_mask:0xa bank_mask:0xf
	s_nop 1
	v_add_f32_dpp v102, v102, v102 row_bcast:31 row_mask:0xc bank_mask:0xf
	s_nop 1
	v_readlane_b32 s74, v102, 63
	s_nop 2
	v_mov_b32_e32 v102, s74
	v_fmamk_f32 v102, v102, 0x3a800000, v2
	v_mul_f32_e32 v103, 0x4f800000, v102
	v_cmp_gt_f32_e32 vcc, 0xf800000, v102
	s_nop 1
	v_cndmask_b32_e32 v102, v102, v103, vcc
	v_sqrt_f32_e32 v103, v102
	s_nop 0
	v_add_u32_e32 v104, -1, v103
	v_add_u32_e32 v106, 1, v103
	v_fma_f32 v107, -v104, v103, v102
	v_fma_f32 v108, -v106, v103, v102
	v_cmp_ge_f32_e64 s[76:77], 0, v107
	s_nop 1
	v_cndmask_b32_e64 v103, v103, v104, s[76:77]
	v_cmp_lt_f32_e64 s[76:77], 0, v108
	s_nop 1
	v_cndmask_b32_e64 v103, v103, v106, s[76:77]
	v_mul_f32_e32 v104, 0x37800000, v103
	v_cndmask_b32_e32 v103, v103, v104, vcc
	v_cmp_class_f32_e32 vcc, v102, v3
	s_nop 1
	v_cndmask_b32_e32 v102, v103, v102, vcc
	v_div_scale_f32 v103, s[76:77], v102, v102, 1.0
	v_rcp_f32_e32 v104, v103
	v_div_scale_f32 v106, vcc, 1.0, v102, 1.0
	v_fma_f32 v107, -v103, v104, 1.0
	v_fmac_f32_e32 v104, v107, v104
	v_mul_f32_e32 v107, v106, v104
	v_fma_f32 v108, -v103, v107, v106
	v_fmac_f32_e32 v107, v108, v104
	v_fma_f32 v103, -v103, v107, v106
	v_div_fmas_f32 v103, v103, v104, v107
	v_div_fixup_f32 v110, v103, v102, 1.0
	s_lshl_b32 s60, s55, 11
	s_add_u32 s70, s78, s60
	s_addc_u32 s71, s79, 0
	v_pk_mul_f32 v[112:113], v[36:37], v[110:111] op_sel_hi:[1,0]
	v_pk_mul_f32 v[114:115], v[38:39], v[110:111] op_sel_hi:[1,0]
	v_pk_mul_f32 v[116:117], v[40:41], v[110:111] op_sel_hi:[1,0]
	v_pk_mul_f32 v[118:119], v[42:43], v[110:111] op_sel_hi:[1,0]
	v_pk_mul_f32 v[120:121], v[44:45], v[110:111] op_sel_hi:[1,0]
	v_pk_mul_f32 v[122:123], v[46:47], v[110:111] op_sel_hi:[1,0]
	v_pk_mul_f32 v[124:125], v[48:49], v[110:111] op_sel_hi:[1,0]
	v_pk_mul_f32 v[100:101], v[50:51], v[110:111] op_sel_hi:[1,0]
	v_pk_mul_f32 v[112:113], v[192:193], v[112:113]
	v_pk_mul_f32 v[114:115], v[194:195], v[114:115]
	v_pk_mul_f32 v[116:117], v[196:197], v[116:117]
	v_pk_mul_f32 v[118:119], v[198:199], v[118:119]
	v_pk_mul_f32 v[120:121], v[200:201], v[120:121]
	v_pk_mul_f32 v[122:123], v[202:203], v[122:123]
	v_pk_mul_f32 v[124:125], v[204:205], v[124:125]
	v_pk_mul_f32 v[100:101], v[206:207], v[100:101]
	v_pk_fma_f32 v[112:113], v[208:209], v[112:113], v[224:225]
	v_pk_fma_f32 v[114:115], v[210:211], v[114:115], v[226:227]
	v_pk_fma_f32 v[116:117], v[212:213], v[116:117], v[228:229]
	v_pk_fma_f32 v[118:119], v[214:215], v[118:119], v[230:231]
	v_pk_fma_f32 v[120:121], v[216:217], v[120:121], v[232:233]
	v_pk_fma_f32 v[122:123], v[218:219], v[122:123], v[234:235]
	v_pk_fma_f32 v[124:125], v[220:221], v[124:125], v[236:237]
	v_pk_fma_f32 v[100:101], v[222:223], v[100:101], v[238:239]
	v_cvt_pk_bf16_f32 v240, v112, v113
	v_cvt_pk_bf16_f32 v241, v114, v115
	v_cvt_pk_bf16_f32 v242, v116, v117
	v_cvt_pk_bf16_f32 v243, v118, v119
	v_cvt_pk_bf16_f32 v244, v120, v121
	v_cvt_pk_bf16_f32 v245, v122, v123
	v_cvt_pk_bf16_f32 v246, v124, v125
	v_cvt_pk_bf16_f32 v247, v100, v101
	global_store_dwordx2 v1, v[240:241], s[70:71]
	global_store_dwordx2 v1, v[242:243], s[70:71] offset:512
	global_store_dwordx2 v1, v[244:245], s[70:71] offset:1024
	global_store_dwordx2 v1, v[246:247], s[70:71] offset:1536
	s_add_u32 s55, s55, 8
	s_add_u32 s57, s55, 16
	s_min_u32 s57, s57, s54
	s_cmp_lt_u32 s57, 0x8000
	s_cselect_b32 s64, s8, s10
	s_cselect_b32 s65, s9, s11
	s_cselect_b32 s60, 0, 0x8000
	s_sub_u32 s60, s57, s60
	s_lshl_b32 s60, s60, 12
	s_add_u32 s64, s64, s60
	s_addc_u32 s65, s65, 0
	s_lshl_b32 s60, s57, 11
	s_add_u32 s66, s82, s60
	s_addc_u32 s67, s83, 0
	global_load_dwordx4 v[36:39], v0, s[64:65] nt
	global_load_dwordx4 v[40:43], v0, s[64:65] offset:1024 nt
	global_load_dwordx4 v[44:47], v0, s[64:65] offset:2048 nt
	global_load_dwordx4 v[48:51], v0, s[64:65] offset:3072 nt
	global_load_dwordx2 v[52:53], v1, s[66:67] nt
	global_load_dwordx2 v[54:55], v1, s[66:67] offset:512 nt
	global_load_dwordx2 v[56:57], v1, s[66:67] offset:1024 nt
	global_load_dwordx2 v[58:59], v1, s[66:67] offset:1536 nt
	s_lshr_b32 s60, s55, 11
	s_sub_u32 s61, s55, 0x8000
	s_lshr_b32 s61, s61, 12
	s_add_u32 s61, s61, 16
	s_cmp_lt_u32 s55, 0x8000
	s_cselect_b32 s63, s60, s61
	s_cmp_eq_u32 s63, s56
	s_cbranch_scc1 .Lrp4_pk9
; template <bool HAS_F, bool HAS_H>
; __device__ __forceinline__ void phase_rows(const Params& p, int sp, int sn, float resw, bool from_input, bool write_x = true) {
;     ...
;             const float* gate = mod + b * 9216 + sp * 3072 + 2048; const float* gp = p.in[7] + sp * D;
; #pragma unroll
;             for (int j = 0; j < 4; ++j) { const f32x4 g = *(const f32x4*)(gate + 4 * lane + 256 * j), q = *(const f32x4*)(gp + 4 * lane + 256 * j);
;     ...
;             const float* sh = mod + b * 9216 + sn * 3072; const float* scl = sh + 1024; const float* gq = p.in[6] + sn * D;
; #pragma unroll
;             for (int j = 0; j < 4; ++j) { const f32x4 a = *(const f32x4*)(sh + 4 * lane + 256 * j), s = *(const f32x4*)(scl + 4 * lane + 256 * j), q = *(const f32x4*)(gq + 4 * lane + 256 * j);
	s_mov_b32 s56, s63
	s_mul_i32 s60, s56, 0x9000
	s_add_u32 s60, s60, 0x3182000
	s_add_u32 s0, s92, s60
	s_addc_u32 s1, s93, 0
	global_load_dwordx4 v[160:163], v0, s[0:1]
	global_load_dwordx4 v[164:167], v0, s[0:1] offset:1024
	global_load_dwordx4 v[168:171], v0, s[0:1] offset:2048
	global_load_dwordx4 v[172:175], v0, s[0:1] offset:3072
	s_add_u32 s0, s22, 0x0
	s_addc_u32 s1, s23, 0
	global_load_dwordx4 v[176:179], v0, s[0:1]
	global_load_dwordx4 v[180:183], v0, s[0:1] offset:1024
	global_load_dwordx4 v[184:187], v0, s[0:1] offset:2048
	global_load_dwordx4 v[188:191], v0, s[0:1] offset:3072
	s_add_u32 s0, s20, 0x1000
	s_addc_u32 s1, s21, 0
	global_load_dwordx4 v[192:195], v0, s[0:1]
	global_load_dwordx4 v[196:199], v0, s[0:1] offset:1024
	global_load_dwordx4 v[200:203], v0, s[0:1] offset:2048
	global_load_dwordx4 v[204:207], v0, s[0:1] offset:3072
	s_mul_i32 s60, s56, 0x9000
	s_add_u32 s60, s60, 0x3184000
	s_add_u32 s0, s92, s60
	s_addc_u32 s1, s93, 0
	global_load_dwordx4 v[208:211], v0, s[0:1]
	global_load_dwordx4 v[212:215], v0, s[0:1] offset:1024
	global_load_dwordx4 v[216:219], v0, s[0:1] offset:2048
	global_load_dwordx4 v[220:223], v0, s[0:1] offset:3072
	s_mul_i32 s60, s56, 0x9000
	s_add_u32 s60, s60, 0x3183000
	s_add_u32 s0, s92, s60
	s_addc_u32 s1, s93, 0
	global_load_dwordx4 v[224:227], v0, s[0:1]
	global_load_dwordx4 v[228:231], v0, s[0:1] offset:1024
	global_load_dwordx4 v[232:235], v0, s[0:1] offset:2048
	global_load_dwordx4 v[236:239], v0, s[0:1] offset:3072
	s_waitcnt vmcnt(0)
	v_pk_add_f32 v[208:209], v[208:209], 1.0 op_sel_hi:[1,0]
	v_pk_add_f32 v[210:211], v[210:211], 1.0 op_sel_hi:[1,0]
	v_pk_add_f32 v[212:213], v[212:213], 1.0 op_sel_hi:[1,0]
	v_pk_add_f32 v[214:215], v[214:215], 1.0 op_sel_hi:[1,0]
	v_pk_add_f32 v[216:217], v[216:217], 1.0 op_sel_hi:[1,0]
	v_pk_add_f32 v[218:219], v[218:219], 1.0 op_sel_hi:[1,0]
	v_pk_add_f32 v[220:221], v[220:221], 1.0 op_sel_hi:[1,0]
	v_pk_add_f32 v[222:223], v[222:223], 1.0 op_sel_hi:[1,0]

; __device__ __forceinline__ float lo_bf(unsigned w) { return __uint_as_float(w << 16); }
; __device__ __forceinline__ float hi_bf(unsigned w) { return __uint_as_float(w & 0xffff0000u); }
; template <bool HAS_F, bool HAS_H>
; __device__ __forceinline__ void phase_rows(const Params& p, int sp, int sn, float resw, bool from_input, bool write_x = true) {
;     ...
;     for (int row = gw; row < T; row += NGW) {
;         const int b = row_batch(row);
;         const float* xin = !from_input ? p.out + (size_t)row * D : (row < TP ? p.in[0] + (size_t)row * D : p.in[1] + (size_t)(row - TP) * D);
;         f32x4 v[4];
; #pragma unroll
;         for (int j = 0; j < 4; ++j) v[j] = *(const f32x4*)(xin + 4 * lane + 256 * j);
;         if (HAS_F) {
;             f32x4 f[4]; float ss = 0.f;
; #pragma unroll
;             for (int j = 0; j < 4; ++j) { const u32x2 w = *(const u32x2*)(F + (size_t)row * D + 4 * lane + 256 * j);
;                 f[j] = (f32x4){lo_bf(w.x), hi_bf(w.x), lo_bf(w.y), hi_bf(w.y)}; ss += (f[j].x * f[j].x + f[j].y * f[j].y) + (f[j].z * f[j].z + f[j].w * f[j].w); }
;             const float rs = 1.0f / sqrtf(wave_sum(ss) * (1.0f / D) + EPS) * resw;
;             const float* gate = mod + b * 9216 + sp * 3072 + 2048; const float* gp = p.in[7] + sp * D;
; #pragma unroll
;             for (int j = 0; j < 4; ++j) { const f32x4 g = *(const f32x4*)(gate + 4 * lane + 256 * j), q = *(const f32x4*)(gp + 4 * lane + 256 * j);
;                 v[j] = v[j] + g * (f[j] * rs * q);
;                 if (write_x) *(f32x4*)(p.out + (size_t)row * D + 4 * lane + 256 * j) = v[j]; }
;         }
;         if (HAS_H) {
;             float ss = 0.f;
; #pragma unroll
;             for (int j = 0; j < 4; ++j) ss += (v[j].x * v[j].x + v[j].y * v[j].y) + (v[j].z * v[j].z + v[j].w * v[j].w);
;             const float rs = 1.0f / sqrtf(wave_sum(ss) * (1.0f / D) + EPS);
;             const float* sh = mod + b * 9216 + sn * 3072; const float* scl = sh + 1024; const float* gq = p.in[6] + sn * D;
; #pragma unroll
;             for (int j = 0; j < 4; ++j) { const f32x4 a = *(const f32x4*)(sh + 4 * lane + 256 * j), s = *(const f32x4*)(scl + 4 * lane + 256 * j), q = *(const f32x4*)(gq + 4 * lane + 256 * j);
.Lrp12_chunk1:
	s_mul_i32 s53, s51, 384
	s_cmp_ge_u32 s53, 0x18000
	s_cbranch_scc1 .Lrp12_done2
	s_add_u32 s53, s53, s50
	s_add_u32 s54, s53, 376
	s_mov_b32 s56, -1
	s_mov_b32 s55, s53
	s_add_u32 s57, s53, 0
	s_lshl_b32 s60, s57, 12
	s_add_u32 s64, s84, s60
	s_addc_u32 s65, s85, 0
	s_lshl_b32 s60, s57, 11
	s_add_u32 s66, s82, s60
	s_addc_u32 s67, s83, 0
	global_load_dwordx4 v[4:7], v0, s[64:65] nt
	global_load_dwordx4 v[8:11], v0, s[64:65] offset:1024 nt
	global_load_dwordx4 v[12:15], v0, s[64:65] offset:2048 nt
	global_load_dwordx4 v[16:19], v0, s[64:65] offset:3072 nt
	global_load_dwordx2 v[20:21], v1, s[66:67] nt
	global_load_dwordx2 v[22:23], v1, s[66:67] offset:512 nt
	global_load_dwordx2 v[24:25], v1, s[66:67] offset:1024 nt
	global_load_dwordx2 v[26:27], v1, s[66:67] offset:1536 nt
	s_add_u32 s57, s53, 8
	s_lshl_b32 s60, s57, 12
	s_add_u32 s64, s84, s60
	s_addc_u32 s65, s85, 0
	s_lshl_b32 s60, s57, 11
	s_add_u32 s66, s82, s60
	s_addc_u32 s67, s83, 0
	global_load_dwordx4 v[36:39], v0, s[64:65] nt
	global_load_dwordx4 v[40:43], v0, s[64:65] offset:1024 nt
	global_load_dwordx4 v[44:47], v0, s[64:65] offset:2048 nt
	global_load_dwordx4 v[48:51], v0, s[64:65] offset:3072 nt
	global_load_dwordx2 v[52:53], v1, s[66:67] nt
	global_load_dwordx2 v[54:55], v1, s[66:67] offset:512 nt
	global_load_dwordx2 v[56:57], v1, s[66:67] offset:1024 nt
	global_load_dwordx2 v[58:59], v1, s[66:67] offset:1536 nt
	s_add_u32 s57, s55, 16
	s_min_u32 s57, s57, s54
	s_lshl_b32 s60, s57, 12
	s_add_u32 s64, s84, s60
	s_addc_u32 s65, s85, 0
	s_lshl_b32 s60, s57, 11
	s_add_u32 s66, s82, s60
	s_addc_u32 s67, s83, 0
	global_load_dwordx4 v[68:71], v0, s[64:65] nt
	global_load_dwordx4 v[72:75], v0, s[64:65] offset:1024 nt
	global_load_dwordx4 v[76:79], v0, s[64:65] offset:2048 nt
	global_load_dwordx4 v[80:83], v0, s[64:65] offset:3072 nt
	global_load_dwordx2 v[84:85], v1, s[66:67] nt
	global_load_dwordx2 v[86:87], v1, s[66:67] offset:512 nt
	global_load_dwordx2 v[88:89], v1, s[66:67] offset:1024 nt
	global_load_dwordx2 v[90:91], v1, s[66:67] offset:1536 nt
	s_lshr_b32 s60, s55, 11
	s_sub_u32 s61, s55, 0x8000
	s_lshr_b32 s61, s61, 12
	s_add_u32 s61, s61, 16
	s_cmp_lt_u32 s55, 0x8000
	s_cselect_b32 s63, s60, s61
	s_cmp_eq_u32 s63, s56
	s_cbranch_scc1 .Lrp12_pk4
	s_mov_b32 s56, s63
	s_mul_i32 s60, s56, 0x9000
	s_add_u32 s60, s60, 0x3185000
	s_add_u32 s0, s92, s60
	s_addc_u32 s1, s93, 0
	global_load_dwordx4 v[160:163], v0, s[0:1]
	global_load_dwordx4 v[164:167], v0, s[0:1] offset:1024
	global_load_dwordx4 v[168:171], v0, s[0:1] offset:2048
	global_load_dwordx4 v[172:175], v0, s[0:1] offset:3072
	s_add_u32 s0, s22, 0x1000
	s_addc_u32 s1, s23, 0
	global_load_dwordx4 v[176:179], v0, s[0:1]
	global_load_dwordx4 v[180:183], v0, s[0:1] offset:1024
	global_load_dwordx4 v[184:187], v0, s[0:1] offset:2048
	global_load_dwordx4 v[188:191], v0, s[0:1] offset:3072
	s_add_u32 s0, s20, 0x2000
	s_addc_u32 s1, s21, 0
	global_load_dwordx4 v[192:195], v0, s[0:1]
	global_load_dwordx4 v[196:199], v0, s[0:1] offset:1024
	global_load_dwordx4 v[200:203], v0, s[0:1] offset:2048
	global_load_dwordx4 v[204:207], v0, s[0:1] offset:3072
	s_mul_i32 s60, s56, 0x9000
	s_add_u32 s60, s60, 0x3187000
	s_add_u32 s0, s92, s60
	s_addc_u32 s1, s93, 0
	global_load_dwordx4 v[208:211], v0, s[0:1]
	global_load_dwordx4 v[212:215], v0, s[0:1] offset:1024
	global_load_dwordx4 v[216:219], v0, s[0:1] offset:2048
	global_load_dwordx4 v[220:223], v0, s[0:1] offset:3072
	s_mul_i32 s60, s56, 0x9000
	s_add_u32 s60, s60, 0x3186000
	s_add_u32 s0, s92, s60
	s_addc_u32 s1, s93, 0
	global_load_dwordx4 v[224:227], v0, s[0:1]
	global_load_dwordx4 v[228:231], v0, s[0:1] offset:1024
	global_load_dwordx4 v[232:235], v0, s[0:1] offset:2048
	global_load_dwordx4 v[236:239], v0, s[0:1] offset:3072
	s_waitcnt vmcnt(0)
	v_pk_add_f32 v[208:209], v[208:209], 1.0 op_sel_hi:[1,0]
	v_pk_add_f32 v[210:211], v[210:211], 1.0 op_sel_hi:[1,0]
	v_pk_add_f32 v[212:213], v[212:213], 1.0 op_sel_hi:[1,0]
	v_pk_add_f32 v[214:215], v[214:215], 1.0 op_sel_hi:[1,0]
	v_pk_add_f32 v[216:217], v[216:217], 1.0 op_sel_hi:[1,0]
	v_pk_add_f32 v[218:219], v[218:219], 1.0 op_sel_hi:[1,0]
	v_pk_add_f32 v[220:221], v[220:221], 1.0 op_sel_hi:[1,0]
	v_pk_add_f32 v[222:223], v[222:223], 1.0 op_sel_hi:[1,0]
; __device__ __forceinline__ float lo_bf(unsigned w) { return __uint_as_float(w << 16); }
; __device__ __forceinline__ float hi_bf(unsigned w) { return __uint_as_float(w & 0xffff0000u); }
; template <bool HAS_F, bool HAS_H>
; __device__ __forceinline__ void phase_rows(const Params& p, int sp, int sn, float resw, bool from_input, bool write_x = true) {
;     ...
;             f32x4 f[4]; float ss = 0.f;
; #pragma unroll
;             for (int j = 0; j < 4; ++j) { const u32x2 w = *(const u32x2*)(F + (size_t)row * D + 4 * lane + 256 * j);
;                 f[j] = (f32x4){lo_bf(w.x), hi_bf(w.x), lo_bf(w.y), hi_bf(w.y)}; ss += (f[j].x * f[j].x + f[j].y * f[j].y) + (f[j].z * f[j].z + f[j].w * f[j].w); }
;             const float rs = 1.0f / sqrtf(wave_sum(ss) * (1.0f / D) + EPS) * resw;
;             const float* gate = mod + b * 9216 + sp * 3072 + 2048; const float* gp = p.in[7] + sp * D;
; #pragma unroll
;             for (int j = 0; j < 4; ++j) { const f32x4 g = *(const f32x4*)(gate + 4 * lane + 256 * j), q = *(const f32x4*)(gp + 4 * lane + 256 * j);
;                 v[j] = v[j] + g * (f[j] * rs * q);
;                 if (write_x) *(f32x4*)(p.out + (size_t)row * D + 4 * lane + 256 * j) = v[j]; }
;         }
;         if (HAS_H) {
;             float ss = 0.f;
; #pragma unroll
;             for (int j = 0; j < 4; ++j) ss += (v[j].x * v[j].x + v[j].y * v[j].y) + (v[j].z * v[j].z + v[j].w * v[j].w);
;             const float rs = 1.0f / sqrtf(wave_sum(ss) * (1.0f / D) + EPS);
.Lrp12_pk4:
	s_waitcnt vmcnt(16)
	v_lshlrev_b32_e32 v112, 16, v20
	v_and_b32_e32 v113, 0xffff0000, v20
	v_lshlrev_b32_e32 v114, 16, v21
	v_and_b32_e32 v115, 0xffff0000, v21
	v_lshlrev_b32_e32 v116, 16, v22
	v_and_b32_e32 v117, 0xffff0000, v22
	v_lshlrev_b32_e32 v118, 16, v23
	v_and_b32_e32 v119, 0xffff0000, v23
	v_lshlrev_b32_e32 v120, 16, v24
	v_and_b32_e32 v121, 0xffff0000, v24
	v_lshlrev_b32_e32 v122, 16, v25
	v_and_b32_e32 v123, 0xffff0000, v25
	v_lshlrev_b32_e32 v124, 16, v26
	v_and_b32_e32 v125, 0xffff0000, v26
	v_lshlrev_b32_e32 v100, 16, v27
	v_and_b32_e32 v101, 0xffff0000, v27
	v_pk_mul_f32 v[102:103], v[112:113], v[112:113]
	v_pk_mul_f32 v[106:107], v[114:115], v[114:115]
	v_pk_fma_f32 v[102:103], v[116:117], v[116:117], v[102:103]
	v_pk_fma_f32 v[106:107], v[118:119], v[118:119], v[106:107]
	v_pk_fma_f32 v[102:103], v[120:121], v[120:121], v[102:103]
	v_pk_fma_f32 v[106:107], v[122:123], v[122:123], v[106:107]
	v_pk_fma_f32 v[102:103], v[124:125], v[124:125], v[102:103]
	v_pk_fma_f32 v[106:107], v[100:101], v[100:101], v[106:107]
	v_pk_add_f32 v[102:103], v[102:103], v[106:107]
	v_add_f32_e32 v102, v102, v103
	s_nop 1
	v_add_f32_dpp v102, v102, v102 quad_perm:[1,0,3,2] row_mask:0xf bank_mask:0xf
	s_nop 1
	v_add_f32_dpp v102, v102, v102 quad_perm:[2,3,0,1] row_mask:0xf bank_mask:0xf
	s_nop 1
	v_add_f32_dpp v102, v102, v102 row_half_mirror row_mask:0xf bank_mask:0xf
	s_nop 1
	v_add_f32_dpp v102, v102, v102 row_mirror row_mask:0xf bank_mask:0xf
	s_nop 1
	v_add_f32_dpp v102, v102, v102 row_bcast:15 row_mask:0xa bank_mask:0xf
	s_nop 1
	v_add_f32_dpp v102, v102, v102 row_bcast:31 row_mask:0xc bank_mask:0xf
	s_nop 1
	v_readlane_b32 s74, v102, 63
	s_nop 2
	v_mov_b32_e32 v102, s74
	v_fmamk_f32 v102, v102, 0x3a800000, v2
	v_mul_f32_e32 v103, 0x4f800000, v102
	v_cmp_gt_f32_e32 vcc, 0xf800000, v102
	s_nop 1
	v_cndmask_b32_e32 v102, v102, v103, vcc
	v_sqrt_f32_e32 v103, v102
	s_nop 0
	v_add_u32_e32 v104, -1, v103
	v_add_u32_e32 v106, 1, v103
	v_fma_f32 v107, -v104, v103, v102
	v_fma_f32 v108, -v106, v103, v102
	v_cmp_ge_f32_e64 s[76:77], 0, v107
	s_nop 1
	v_cndmask_b32_e64 v103, v103, v104, s[76:77]
	v_cmp_lt_f32_e64 s[76:77], 0, v108
	s_nop 1
	v_cndmask_b32_e64 v103, v103, v106, s[76:77]
	v_mul_f32_e32 v104, 0x37800000, v103
	v_cndmask_b32_e32 v103, v103, v104, vcc
	v_cmp_class_f32_e32 vcc, v102, v3
	s_nop 1
	v_cndmask_b32_e32 v102, v103, v102, vcc
	v_div_scale_f32 v103, s[76:77], v102, v102, 1.0
	v_rcp_f32_e32 v104, v103
	v_div_scale_f32 v106, vcc, 1.0, v102, 1.0
	v_fma_f32 v107, -v103, v104, 1.0
	v_fmac_f32_e32 v104, v107, v104
	v_mul_f32_e32 v107, v106, v104
	v_fma_f32 v108, -v103, v107, v106
	v_fmac_f32_e32 v107, v108, v104
	v_fma_f32 v103, -v103, v107, v106
	v_div_fmas_f32 v103, v103, v104, v107
	v_div_fixup_f32 v110, v103, v102, 1.0
	v_pk_mul_f32 v[112:113], v[112:113], v[110:111] op_sel_hi:[1,0]
	v_pk_mul_f32 v[114:115], v[114:115], v[110:111] op_sel_hi:[1,0]
	v_pk_mul_f32 v[116:117], v[116:117], v[110:111] op_sel_hi:[1,0]
	v_pk_mul_f32 v[118:119], v[118:119], v[110:111] op_sel_hi:[1,0]
	v_pk_mul_f32 v[120:121], v[120:121], v[110:111] op_sel_hi:[1,0]
	v_pk_mul_f32 v[122:123], v[122:123], v[110:111] op_sel_hi:[1,0]
	v_pk_mul_f32 v[124:125], v[124:125], v[110:111] op_sel_hi:[1,0]
	v_pk_mul_f32 v[100:101], v[100:101], v[110:111] op_sel_hi:[1,0]
	v_pk_mul_f32 v[112:113], v[176:177], v[112:113]
	v_pk_mul_f32 v[114:115], v[178:179], v[114:115]
	v_pk_mul_f32 v[116:117], v[180:181], v[116:117]
	v_pk_mul_f32 v[118:119], v[182:183], v[118:119]
	v_pk_mul_f32 v[120:121], v[184:185], v[120:121]
	v_pk_mul_f32 v[122:123], v[186:187], v[122:123]
	v_pk_mul_f32 v[124:125], v[188:189], v[124:125]
	v_pk_mul_f32 v[100:101], v[190:191], v[100:101]
	v_pk_fma_f32 v[4:5], v[160:161], v[112:113], v[4:5]
	v_pk_fma_f32 v[6:7], v[162:163], v[114:115], v[6:7]
	v_pk_fma_f32 v[8:9], v[164:165], v[116:117], v[8:9]
	v_pk_fma_f32 v[10:11], v[166:167], v[118:119], v[10:11]
	v_pk_fma_f32 v[12:13], v[168:169], v[120:121], v[12:13]
	v_pk_fma_f32 v[14:15], v[170:171], v[122:123], v[14:15]
	v_pk_fma_f32 v[16:17], v[172:173], v[124:125], v[16:17]
	v_pk_fma_f32 v[18:19], v[174:175], v[100:101], v[18:19]
	v_pk_mul_f32 v[102:103], v[4:5], v[4:5]
	v_pk_mul_f32 v[106:107], v[6:7], v[6:7]
	v_pk_fma_f32 v[102:103], v[8:9], v[8:9], v[102:103]
	v_pk_fma_f32 v[106:107], v[10:11], v[10:11], v[106:107]
	v_pk_fma_f32 v[102:103], v[12:13], v[12:13], v[102:103]
	v_pk_fma_f32 v[106:107], v[14:15], v[14:15], v[106:107]
	v_pk_fma_f32 v[102:103], v[16:17], v[16:17], v[102:103]
	v_pk_fma_f32 v[106:107], v[18:19], v[18:19], v[106:107]
	v_pk_add_f32 v[102:103], v[102:103], v[106:107]
	v_add_f32_e32 v102, v102, v103
	s_nop 1
	v_add_f32_dpp v102, v102, v102 quad_perm:[1,0,3,2] row_mask:0xf bank_mask:0xf
	s_nop 1
	v_add_f32_dpp v102, v102, v102 quad_perm:[2,3,0,1] row_mask:0xf bank_mask:0xf
	s_nop 1
	v_add_f32_dpp v102, v102, v102 row_half_mirror row_mask:0xf bank_mask:0xf
	s_nop 1
	v_add_f32_dpp v102, v102, v102 row_mirror row_mask:0xf bank_mask:0xf
	s_nop 1
	v_add_f32_dpp v102, v102, v102 row_bcast:15 row_mask:0xa bank_mask:0xf
	s_nop 1
	v_add_f32_dpp v102, v102, v102 row_bcast:31 row_mask:0xc bank_mask:0xf
	s_nop 1
	v_readlane_b32 s74, v102, 63
	s_nop 2
	v_mov_b32_e32 v102, s74
	v_fmamk_f32 v102, v102, 0x3a800000, v2
	v_mul_f32_e32 v103, 0x4f800000, v102
	v_cmp_gt_f32_e32 vcc, 0xf800000, v102
	s_nop 1
	v_cndmask_b32_e32 v102, v102, v103, vcc
	v_sqrt_f32_e32 v103, v102
	s_nop 0
	v_add_u32_e32 v104, -1, v103
	v_add_u32_e32 v106, 1, v103
	v_fma_f32 v107, -v104, v103, v102
	v_fma_f32 v108, -v106, v103, v102
	v_cmp_ge_f32_e64 s[76:77], 0, v107
	s_nop 1
	v_cndmask_b32_e64 v103, v103, v104, s[76:77]
; __device__ __forceinline__ unsigned pk_bf16(float lo, float hi) { const f32x2 v = {lo, hi}; const bf16x2_t b = __builtin_convertvector(v, bf16x2_t); return __builtin_bit_cast(unsigned, b); }
; template <bool HAS_F, bool HAS_H>
; __device__ __forceinline__ void phase_rows(const Params& p, int sp, int sn, float resw, bool from_input, bool write_x = true) {
;     ...
;     for (int row = gw; row < T; row += NGW) {
;         const int b = row_batch(row);
;         const float* xin = !from_input ? p.out + (size_t)row * D : (row < TP ? p.in[0] + (size_t)row * D : p.in[1] + (size_t)(row - TP) * D);
;         f32x4 v[4];
; #pragma unroll
;         for (int j = 0; j < 4; ++j) v[j] = *(const f32x4*)(xin + 4 * lane + 256 * j);
;     ...
;             const float rs = 1.0f / sqrtf(wave_sum(ss) * (1.0f / D) + EPS);
;             const float* sh = mod + b * 9216 + sn * 3072; const float* scl = sh + 1024; const float* gq = p.in[6] + sn * D;
; #pragma unroll
;             for (int j = 0; j < 4; ++j) { const f32x4 a = *(const f32x4*)(sh + 4 * lane + 256 * j), s = *(const f32x4*)(scl + 4 * lane + 256 * j), q = *(const f32x4*)(gq + 4 * lane + 256 * j);
;                 const f32x4 h = (v[j] * rs * q) * (s + 1.0f) + a;
;                 u32x2 w; w.x = pk_bf16(h.x, h.y); w.y = pk_bf16(h.z, h.w);
;                 *(u32x2*)(H + (size_t)row * D + 4 * lane + 256 * j) = w; }
	v_cmp_lt_f32_e64 s[76:77], 0, v108
	s_nop 1
	v_cndmask_b32_e64 v103, v103, v106, s[76:77]
	v_mul_f32_e32 v104, 0x37800000, v103
	v_cndmask_b32_e32 v103, v103, v104, vcc
	v_cmp_class_f32_e32 vcc, v102, v3
	s_nop 1
	v_cndmask_b32_e32 v102, v103, v102, vcc
	v_div_scale_f32 v103, s[76:77], v102, v102, 1.0
	v_rcp_f32_e32 v104, v103
	v_div_scale_f32 v106, vcc, 1.0, v102, 1.0
	v_fma_f32 v107, -v103, v104, 1.0
	v_fmac_f32_e32 v104, v107, v104
	v_mul_f32_e32 v107, v106, v104
	v_fma_f32 v108, -v103, v107, v106
	v_fmac_f32_e32 v107, v108, v104
	v_fma_f32 v103, -v103, v107, v106
	v_div_fmas_f32 v103, v103, v104, v107
	v_div_fixup_f32 v110, v103, v102, 1.0
	s_lshl_b32 s60, s55, 11
	s_add_u32 s70, s78, s60
	s_addc_u32 s71, s79, 0
	v_pk_mul_f32 v[112:113], v[4:5], v[110:111] op_sel_hi:[1,0]
	v_pk_mul_f32 v[114:115], v[6:7], v[110:111] op_sel_hi:[1,0]
	v_pk_mul_f32 v[116:117], v[8:9], v[110:111] op_sel_hi:[1,0]
	v_pk_mul_f32 v[118:119], v[10:11], v[110:111] op_sel_hi:[1,0]
	v_pk_mul_f32 v[120:121], v[12:13], v[110:111] op_sel_hi:[1,0]
	v_pk_mul_f32 v[122:123], v[14:15], v[110:111] op_sel_hi:[1,0]
	v_pk_mul_f32 v[124:125], v[16:17], v[110:111] op_sel_hi:[1,0]
	v_pk_mul_f32 v[100:101], v[18:19], v[110:111] op_sel_hi:[1,0]
	v_pk_mul_f32 v[112:113], v[192:193], v[112:113]
	v_pk_mul_f32 v[114:115], v[194:195], v[114:115]
	v_pk_mul_f32 v[116:117], v[196:197], v[116:117]
	v_pk_mul_f32 v[118:119], v[198:199], v[118:119]
	v_pk_mul_f32 v[120:121], v[200:201], v[120:121]
	v_pk_mul_f32 v[122:123], v[202:203], v[122:123]
	v_pk_mul_f32 v[124:125], v[204:205], v[124:125]
	v_pk_mul_f32 v[100:101], v[206:207], v[100:101]
	v_pk_fma_f32 v[112:113], v[208:209], v[112:113], v[224:225]
	v_pk_fma_f32 v[114:115], v[210:211], v[114:115], v[226:227]
	v_pk_fma_f32 v[116:117], v[212:213], v[116:117], v[228:229]
	v_pk_fma_f32 v[118:119], v[214:215], v[118:119], v[230:231]
	v_pk_fma_f32 v[120:121], v[216:217], v[120:121], v[232:233]
	v_pk_fma_f32 v[122:123], v[218:219], v[122:123], v[234:235]
	v_pk_fma_f32 v[124:125], v[220:221], v[124:125], v[236:237]
	v_pk_fma_f32 v[100:101], v[222:223], v[100:101], v[238:239]
	v_cvt_pk_bf16_f32 v240, v112, v113
	v_cvt_pk_bf16_f32 v241, v114, v115
	v_cvt_pk_bf16_f32 v242, v116, v117
	v_cvt_pk_bf16_f32 v243, v118, v119
	v_cvt_pk_bf16_f32 v244, v120, v121
	v_cvt_pk_bf16_f32 v245, v122, v123
	v_cvt_pk_bf16_f32 v246, v124, v125
	v_cvt_pk_bf16_f32 v247, v100, v101
	global_store_dwordx2 v1, v[240:241], s[70:71]
	global_store_dwordx2 v1, v[242:243], s[70:71] offset:512
	global_store_dwordx2 v1, v[244:245], s[70:71] offset:1024
	global_store_dwordx2 v1, v[246:247], s[70:71] offset:1536
	s_add_u32 s55, s55, 8
	s_add_u32 s57, s55, 16
	s_min_u32 s57, s57, s54
	s_lshl_b32 s60, s57, 12
	s_add_u32 s64, s84, s60
	s_addc_u32 s65, s85, 0
	s_lshl_b32 s60, s57, 11
	s_add_u32 s66, s82, s60
	s_addc_u32 s67, s83, 0
	global_load_dwordx4 v[4:7], v0, s[64:65] nt
	global_load_dwordx4 v[8:11], v0, s[64:65] offset:1024 nt
	global_load_dwordx4 v[12:15], v0, s[64:65] offset:2048 nt
	global_load_dwordx4 v[16:19], v0, s[64:65] offset:3072 nt
	global_load_dwordx2 v[20:21], v1, s[66:67] nt
	global_load_dwordx2 v[22:23], v1, s[66:67] offset:512 nt
	global_load_dwordx2 v[24:25], v1, s[66:67] offset:1024 nt
	global_load_dwordx2 v[26:27], v1, s[66:67] offset:1536 nt
	s_lshr_b32 s60, s55, 11
	s_sub_u32 s61, s55, 0x8000
	s_lshr_b32 s61, s61, 12
	s_add_u32 s61, s61, 16
	s_cmp_lt_u32 s55, 0x8000
	s_cselect_b32 s63, s60, s61
	s_cmp_eq_u32 s63, s56
	s_cbranch_scc1 .Lrp12_pk5
	s_mov_b32 s56, s63
	s_mul_i32 s60, s56, 0x9000
	s_add_u32 s60, s60, 0x3185000
	s_add_u32 s0, s92, s60
	s_addc_u32 s1, s93, 0
	global_load_dwordx4 v[160:163], v0, s[0:1]
	global_load_dwordx4 v[164:167], v0, s[0:1] offset:1024
	global_load_dwordx4 v[168:171], v0, s[0:1] offset:2048
	global_load_dwordx4 v[172:175], v0, s[0:1] offset:3072
	s_add_u32 s0, s22, 0x1000
	s_addc_u32 s1, s23, 0
	global_load_dwordx4 v[176:179], v0, s[0:1]
	global_load_dwordx4 v[180:183], v0, s[0:1] offset:1024
	global_load_dwordx4 v[184:187], v0, s[0:1] offset:2048
	global_load_dwordx4 v[188:191], v0, s[0:1] offset:3072
	s_add_u32 s0, s20, 0x2000
	s_addc_u32 s1, s21, 0
	global_load_dwordx4 v[192:195], v0, s[0:1]
	global_load_dwordx4 v[196:199], v0, s[0:1] offset:1024
	global_load_dwordx4 v[200:203], v0, s[0:1] offset:2048
	global_load_dwordx4 v[204:207], v0, s[0:1] offset:3072
	s_mul_i32 s60, s56, 0x9000
	s_add_u32 s60, s60, 0x3187000
	s_add_u32 s0, s92, s60
	s_addc_u32 s1, s93, 0
	global_load_dwordx4 v[208:211], v0, s[0:1]
	global_load_dwordx4 v[212:215], v0, s[0:1] offset:1024
	global_load_dwordx4 v[216:219], v0, s[0:1] offset:2048
	global_load_dwordx4 v[220:223], v0, s[0:1] offset:3072
	s_mul_i32 s60, s56, 0x9000
	s_add_u32 s60, s60, 0x3186000
	s_add_u32 s0, s92, s60
	s_addc_u32 s1, s93, 0
	global_load_dwordx4 v[224:227], v0, s[0:1]
	global_load_dwordx4 v[228:231], v0, s[0:1] offset:1024
	global_load_dwordx4 v[232:235], v0, s[0:1] offset:2048
	global_load_dwordx4 v[236:239], v0, s[0:1] offset:3072
	s_waitcnt vmcnt(0)
	v_pk_add_f32 v[208:209], v[208:209], 1.0 op_sel_hi:[1,0]
	v_pk_add_f32 v[210:211], v[210:211], 1.0 op_sel_hi:[1,0]
	v_pk_add_f32 v[212:213], v[212:213], 1.0 op_sel_hi:[1,0]
	v_pk_add_f32 v[214:215], v[214:215], 1.0 op_sel_hi:[1,0]
	v_pk_add_f32 v[216:217], v[216:217], 1.0 op_sel_hi:[1,0]
	v_pk_add_f32 v[218:219], v[218:219], 1.0 op_sel_hi:[1,0]
	v_pk_add_f32 v[220:221], v[220:221], 1.0 op_sel_hi:[1,0]
	v_pk_add_f32 v[222:223], v[222:223], 1.0 op_sel_hi:[1,0]
; __device__ __forceinline__ float lo_bf(unsigned w) { return __uint_as_float(w << 16); }
; __device__ __forceinline__ float hi_bf(unsigned w) { return __uint_as_float(w & 0xffff0000u); }
; template <bool HAS_F, bool HAS_H>
; __device__ __forceinline__ void phase_rows(const Params& p, int sp, int sn, float resw, bool from_input, bool write_x = true) {
;     ...
;             f32x4 f[4]; float ss = 0.f;
; #pragma unroll
;             for (int j = 0; j < 4; ++j) { const u32x2 w = *(const u32x2*)(F + (size_t)row * D + 4 * lane + 256 * j);
;                 f[j] = (f32x4){lo_bf(w.x), hi_bf(w.x), lo_bf(w.y), hi_bf(w.y)}; ss += (f[j].x * f[j].x + f[j].y * f[j].y) + (f[j].z * f[j].z + f[j].w * f[j].w); }
;             const float rs = 1.0f / sqrtf(wave_sum(ss) * (1.0f / D) + EPS) * resw;
;             const float* gate = mod + b * 9216 + sp * 3072 + 2048; const float* gp = p.in[7] + sp * D;
; #pragma unroll
;             for (int j = 0; j < 4; ++j) { const f32x4 g = *(const f32x4*)(gate + 4 * lane + 256 * j), q = *(const f32x4*)(gp + 4 * lane + 256 * j);
;                 v[j] = v[j] + g * (f[j] * rs * q);
;                 if (write_x) *(f32x4*)(p.out + (size_t)row * D + 4 * lane + 256 * j) = v[j]; }
;         }
;         if (HAS_H) {
;             float ss = 0.f;
; #pragma unroll
;             for (int j = 0; j < 4; ++j) ss += (v[j].x * v[j].x + v[j].y * v[j].y) + (v[j].z * v[j].z + v[j].w * v[j].w);
;             const float rs = 1.0f / sqrtf(wave_sum(ss) * (1.0f / D) + EPS);
.Lrp12_pk5:
	s_waitcnt vmcnt(20)
	v_lshlrev_b32_e32 v112, 16, v52
	v_and_b32_e32 v113, 0xffff0000, v52
	v_lshlrev_b32_e32 v114, 16, v53
	v_and_b32_e32 v115, 0xffff0000, v53
	v_lshlrev_b32_e32 v116, 16, v54
	v_and_b32_e32 v117, 0xffff0000, v54
	v_lshlrev_b32_e32 v118, 16, v55
	v_and_b32_e32 v119, 0xffff0000, v55
	v_lshlrev_b32_e32 v120, 16, v56
	v_and_b32_e32 v121, 0xffff0000, v56
	v_lshlrev_b32_e32 v122, 16, v57
	v_and_b32_e32 v123, 0xffff0000, v57
	v_lshlrev_b32_e32 v124, 16, v58
	v_and_b32_e32 v125, 0xffff0000, v58
	v_lshlrev_b32_e32 v100, 16, v59
	v_and_b32_e32 v101, 0xffff0000, v59
	v_pk_mul_f32 v[102:103], v[112:113], v[112:113]
	v_pk_mul_f32 v[106:107], v[114:115], v[114:115]
	v_pk_fma_f32 v[102:103], v[116:117], v[116:117], v[102:103]
	v_pk_fma_f32 v[106:107], v[118:119], v[118:119], v[106:107]
	v_pk_fma_f32 v[102:103], v[120:121], v[120:121], v[102:103]
	v_pk_fma_f32 v[106:107], v[122:123], v[122:123], v[106:107]
	v_pk_fma_f32 v[102:103], v[124:125], v[124:125], v[102:103]
	v_pk_fma_f32 v[106:107], v[100:101], v[100:101], v[106:107]
	v_pk_add_f32 v[102:103], v[102:103], v[106:107]
	v_add_f32_e32 v102, v102, v103
	s_nop 1
	v_add_f32_dpp v102, v102, v102 quad_perm:[1,0,3,2] row_mask:0xf bank_mask:0xf
	s_nop 1
	v_add_f32_dpp v102, v102, v102 quad_perm:[2,3,0,1] row_mask:0xf bank_mask:0xf
	s_nop 1
	v_add_f32_dpp v102, v102, v102 row_half_mirror row_mask:0xf bank_mask:0xf
	s_nop 1
	v_add_f32_dpp v102, v102, v102 row_mirror row_mask:0xf bank_mask:0xf
	s_nop 1
	v_add_f32_dpp v102, v102, v102 row_bcast:15 row_mask:0xa bank_mask:0xf
	s_nop 1
	v_add_f32_dpp v102, v102, v102 row_bcast:31 row_mask:0xc bank_mask:0xf
	s_nop 1
	v_readlane_b32 s74, v102, 63
	s_nop 2
	v_mov_b32_e32 v102, s74
	v_fmamk_f32 v102, v102, 0x3a800000, v2
	v_mul_f32_e32 v103, 0x4f800000, v102
	v_cmp_gt_f32_e32 vcc, 0xf800000, v102
	s_nop 1
	v_cndmask_b32_e32 v102, v102, v103, vcc
	v_sqrt_f32_e32 v103, v102
	s_nop 0
	v_add_u32_e32 v104, -1, v103
	v_add_u32_e32 v106, 1, v103
	v_fma_f32 v107, -v104, v103, v102
	v_fma_f32 v108, -v106, v103, v102
	v_cmp_ge_f32_e64 s[76:77], 0, v107
	s_nop 1
	v_cndmask_b32_e64 v103, v103, v104, s[76:77]
	v_cmp_lt_f32_e64 s[76:77], 0, v108
	s_nop 1
	v_cndmask_b32_e64 v103, v103, v106, s[76:77]
	v_mul_f32_e32 v104, 0x37800000, v103
	v_cndmask_b32_e32 v103, v103, v104, vcc
	v_cmp_class_f32_e32 vcc, v102, v3
	s_nop 1
	v_cndmask_b32_e32 v102, v103, v102, vcc
	v_div_scale_f32 v103, s[76:77], v102, v102, 1.0
	v_rcp_f32_e32 v104, v103
	v_div_scale_f32 v106, vcc, 1.0, v102, 1.0
	v_fma_f32 v107, -v103, v104, 1.0
	v_fmac_f32_e32 v104, v107, v104
	v_mul_f32_e32 v107, v106, v104
	v_fma_f32 v108, -v103, v107, v106
	v_fmac_f32_e32 v107, v108, v104
	v_fma_f32 v103, -v103, v107, v106
	v_div_fmas_f32 v103, v103, v104, v107
	v_div_fixup_f32 v110, v103, v102, 1.0
	v_pk_mul_f32 v[112:113], v[112:113], v[110:111] op_sel_hi:[1,0]
	v_pk_mul_f32 v[114:115], v[114:115], v[110:111] op_sel_hi:[1,0]
	v_pk_mul_f32 v[116:117], v[116:117], v[110:111] op_sel_hi:[1,0]
	v_pk_mul_f32 v[118:119], v[118:119], v[110:111] op_sel_hi:[1,0]
	v_pk_mul_f32 v[120:121], v[120:121], v[110:111] op_sel_hi:[1,0]
	v_pk_mul_f32 v[122:123], v[122:123], v[110:111] op_sel_hi:[1,0]
	v_pk_mul_f32 v[124:125], v[124:125], v[110:111] op_sel_hi:[1,0]
	v_pk_mul_f32 v[100:101], v[100:101], v[110:111] op_sel_hi:[1,0]
	v_pk_mul_f32 v[112:113], v[176:177], v[112:113]
	v_pk_mul_f32 v[114:115], v[178:179], v[114:115]
	v_pk_mul_f32 v[116:117], v[180:181], v[116:117]
	v_pk_mul_f32 v[118:119], v[182:183], v[118:119]
	v_pk_mul_f32 v[120:121], v[184:185], v[120:121]
	v_pk_mul_f32 v[122:123], v[186:187], v[122:123]
	v_pk_mul_f32 v[124:125], v[188:189], v[124:125]
	v_pk_mul_f32 v[100:101], v[190:191], v[100:101]
	v_pk_fma_f32 v[36:37], v[160:161], v[112:113], v[36:37]
	v_pk_fma_f32 v[38:39], v[162:163], v[114:115], v[38:39]
	v_pk_fma_f32 v[40:41], v[164:165], v[116:117], v[40:41]
	v_pk_fma_f32 v[42:43], v[166:167], v[118:119], v[42:43]
	v_pk_fma_f32 v[44:45], v[168:169], v[120:121], v[44:45]
	v_pk_fma_f32 v[46:47], v[170:171], v[122:123], v[46:47]
	v_pk_fma_f32 v[48:49], v[172:173], v[124:125], v[48:49]
	v_pk_fma_f32 v[50:51], v[174:175], v[100:101], v[50:51]
	v_pk_mul_f32 v[102:103], v[36:37], v[36:37]
	v_pk_mul_f32 v[106:107], v[38:39], v[38:39]
	v_pk_fma_f32 v[102:103], v[40:41], v[40:41], v[102:103]
	v_pk_fma_f32 v[106:107], v[42:43], v[42:43], v[106:107]
	v_pk_fma_f32 v[102:103], v[44:45], v[44:45], v[102:103]
	v_pk_fma_f32 v[106:107], v[46:47], v[46:47], v[106:107]
	v_pk_fma_f32 v[102:103], v[48:49], v[48:49], v[102:103]
	v_pk_fma_f32 v[106:107], v[50:51], v[50:51], v[106:107]
	v_pk_add_f32 v[102:103], v[102:103], v[106:107]
	v_add_f32_e32 v102, v102, v103
	s_nop 1
	v_add_f32_dpp v102, v102, v102 quad_perm:[1,0,3,2] row_mask:0xf bank_mask:0xf
	s_nop 1
	v_add_f32_dpp v102, v102, v102 quad_perm:[2,3,0,1] row_mask:0xf bank_mask:0xf
	s_nop 1
	v_add_f32_dpp v102, v102, v102 row_half_mirror row_mask:0xf bank_mask:0xf
	s_nop 1
	v_add_f32_dpp v102, v102, v102 row_mirror row_mask:0xf bank_mask:0xf
	s_nop 1
	v_add_f32_dpp v102, v102, v102 row_bcast:15 row_mask:0xa bank_mask:0xf
	s_nop 1
	v_add_f32_dpp v102, v102, v102 row_bcast:31 row_mask:0xc bank_mask:0xf
	s_nop 1
	v_readlane_b32 s74, v102, 63
	s_nop 2
	v_mov_b32_e32 v102, s74
	v_fmamk_f32 v102, v102, 0x3a800000, v2
	v_mul_f32_e32 v103, 0x4f800000, v102
	v_cmp_gt_f32_e32 vcc, 0xf800000, v102
	s_nop 1
	v_cndmask_b32_e32 v102, v102, v103, vcc
	v_sqrt_f32_e32 v103, v102
	s_nop 0
	v_add_u32_e32 v104, -1, v103
	v_add_u32_e32 v106, 1, v103
	v_fma_f32 v107, -v104, v103, v102
	v_fma_f32 v108, -v106, v103, v102
; __device__ __forceinline__ unsigned pk_bf16(float lo, float hi) { const f32x2 v = {lo, hi}; const bf16x2_t b = __builtin_convertvector(v, bf16x2_t); return __builtin_bit_cast(unsigned, b); }
; template <bool HAS_F, bool HAS_H>
; __device__ __forceinline__ void phase_rows(const Params& p, int sp, int sn, float resw, bool from_input, bool write_x = true) {
;     ...
;     for (int row = gw; row < T; row += NGW) {
;         const int b = row_batch(row);
;         const float* xin = !from_input ? p.out + (size_t)row * D : (row < TP ? p.in[0] + (size_t)row * D : p.in[1] + (size_t)(row - TP) * D);
;         f32x4 v[4];
; #pragma unroll
;         for (int j = 0; j < 4; ++j) v[j] = *(const f32x4*)(xin + 4 * lane + 256 * j);
;     ...
;             const float rs = 1.0f / sqrtf(wave_sum(ss) * (1.0f / D) + EPS);
;             const float* sh = mod + b * 9216 + sn * 3072; const float* scl = sh + 1024; const float* gq = p.in[6] + sn * D;
; #pragma unroll
;             for (int j = 0; j < 4; ++j) { const f32x4 a = *(const f32x4*)(sh + 4 * lane + 256 * j), s = *(const f32x4*)(scl + 4 * lane + 256 * j), q = *(const f32x4*)(gq + 4 * lane + 256 * j);
;                 const f32x4 h = (v[j] * rs * q) * (s + 1.0f) + a;
;                 u32x2 w; w.x = pk_bf16(h.x, h.y); w.y = pk_bf16(h.z, h.w);
;                 *(u32x2*)(H + (size_t)row * D + 4 * lane + 256 * j) = w; }
	v_cmp_ge_f32_e64 s[76:77], 0, v107
	s_nop 1
	v_cndmask_b32_e64 v103, v103, v104, s[76:77]
	v_cmp_lt_f32_e64 s[76:77], 0, v108
	s_nop 1
	v_cndmask_b32_e64 v103, v103, v106, s[76:77]
	v_mul_f32_e32 v104, 0x37800000, v103
	v_cndmask_b32_e32 v103, v103, v104, vcc
	v_cmp_class_f32_e32 vcc, v102, v3
	s_nop 1
	v_cndmask_b32_e32 v102, v103, v102, vcc
	v_div_scale_f32 v103, s[76:77], v102, v102, 1.0
	v_rcp_f32_e32 v104, v103
	v_div_scale_f32 v106, vcc, 1.0, v102, 1.0
	v_fma_f32 v107, -v103, v104, 1.0
	v_fmac_f32_e32 v104, v107, v104
	v_mul_f32_e32 v107, v106, v104
	v_fma_f32 v108, -v103, v107, v106
	v_fmac_f32_e32 v107, v108, v104
	v_fma_f32 v103, -v103, v107, v106
	v_div_fmas_f32 v103, v103, v104, v107
	v_div_fixup_f32 v110, v103, v102, 1.0
	s_lshl_b32 s60, s55, 11
	s_add_u32 s70, s78, s60
	s_addc_u32 s71, s79, 0
	v_pk_mul_f32 v[112:113], v[36:37], v[110:111] op_sel_hi:[1,0]
	v_pk_mul_f32 v[114:115], v[38:39], v[110:111] op_sel_hi:[1,0]
	v_pk_mul_f32 v[116:117], v[40:41], v[110:111] op_sel_hi:[1,0]
	v_pk_mul_f32 v[118:119], v[42:43], v[110:111] op_sel_hi:[1,0]
	v_pk_mul_f32 v[120:121], v[44:45], v[110:111] op_sel_hi:[1,0]
	v_pk_mul_f32 v[122:123], v[46:47], v[110:111] op_sel_hi:[1,0]
	v_pk_mul_f32 v[124:125], v[48:49], v[110:111] op_sel_hi:[1,0]
	v_pk_mul_f32 v[100:101], v[50:51], v[110:111] op_sel_hi:[1,0]
	v_pk_mul_f32 v[112:113], v[192:193], v[112:113]
	v_pk_mul_f32 v[114:115], v[194:195], v[114:115]
	v_pk_mul_f32 v[116:117], v[196:197], v[116:117]
	v_pk_mul_f32 v[118:119], v[198:199], v[118:119]
	v_pk_mul_f32 v[120:121], v[200:201], v[120:121]
	v_pk_mul_f32 v[122:123], v[202:203], v[122:123]
	v_pk_mul_f32 v[124:125], v[204:205], v[124:125]
	v_pk_mul_f32 v[100:101], v[206:207], v[100:101]
	v_pk_fma_f32 v[112:113], v[208:209], v[112:113], v[224:225]
	v_pk_fma_f32 v[114:115], v[210:211], v[114:115], v[226:227]
	v_pk_fma_f32 v[116:117], v[212:213], v[116:117], v[228:229]
	v_pk_fma_f32 v[118:119], v[214:215], v[118:119], v[230:231]
	v_pk_fma_f32 v[120:121], v[216:217], v[120:121], v[232:233]
	v_pk_fma_f32 v[122:123], v[218:219], v[122:123], v[234:235]
	v_pk_fma_f32 v[124:125], v[220:221], v[124:125], v[236:237]
	v_pk_fma_f32 v[100:101], v[222:223], v[100:101], v[238:239]
	v_cvt_pk_bf16_f32 v240, v112, v113
	v_cvt_pk_bf16_f32 v241, v114, v115
	v_cvt_pk_bf16_f32 v242, v116, v117
	v_cvt_pk_bf16_f32 v243, v118, v119
	v_cvt_pk_bf16_f32 v244, v120, v121
	v_cvt_pk_bf16_f32 v245, v122, v123
	v_cvt_pk_bf16_f32 v246, v124, v125
	v_cvt_pk_bf16_f32 v247, v100, v101
	global_store_dwordx2 v1, v[240:241], s[70:71]
	global_store_dwordx2 v1, v[242:243], s[70:71] offset:512
	global_store_dwordx2 v1, v[244:245], s[70:71] offset:1024
	global_store_dwordx2 v1, v[246:247], s[70:71] offset:1536
	s_add_u32 s55, s55, 8
	s_add_u32 s57, s55, 16
	s_min_u32 s57, s57, s54
	s_lshl_b32 s60, s57, 12
	s_add_u32 s64, s84, s60
	s_addc_u32 s65, s85, 0
	s_lshl_b32 s60, s57, 11
	s_add_u32 s66, s82, s60
	s_addc_u32 s67, s83, 0
	global_load_dwordx4 v[36:39], v0, s[64:65] nt
	global_load_dwordx4 v[40:43], v0, s[64:65] offset:1024 nt
	global_load_dwordx4 v[44:47], v0, s[64:65] offset:2048 nt
	global_load_dwordx4 v[48:51], v0, s[64:65] offset:3072 nt
	global_load_dwordx2 v[52:53], v1, s[66:67] nt
	global_load_dwordx2 v[54:55], v1, s[66:67] offset:512 nt
	global_load_dwordx2 v[56:57], v1, s[66:67] offset:1024 nt
	global_load_dwordx2 v[58:59], v1, s[66:67] offset:1536 nt
	s_lshr_b32 s60, s55, 11
	s_sub_u32 s61, s55, 0x8000
	s_lshr_b32 s61, s61, 12
	s_add_u32 s61, s61, 16
	s_cmp_lt_u32 s55, 0x8000
	s_cselect_b32 s63, s60, s61
	s_cmp_eq_u32 s63, s56
	s_cbranch_scc1 .Lrp12_pk6
	s_mov_b32 s56, s63
	s_mul_i32 s60, s56, 0x9000
	s_add_u32 s60, s60, 0x3185000
	s_add_u32 s0, s92, s60
	s_addc_u32 s1, s93, 0
	global_load_dwordx4 v[160:163], v0, s[0:1]
	global_load_dwordx4 v[164:167], v0, s[0:1] offset:1024
	global_load_dwordx4 v[168:171], v0, s[0:1] offset:2048
	global_load_dwordx4 v[172:175], v0, s[0:1] offset:3072
	s_add_u32 s0, s22, 0x1000
	s_addc_u32 s1, s23, 0
	global_load_dwordx4 v[176:179], v0, s[0:1]
	global_load_dwordx4 v[180:183], v0, s[0:1] offset:1024
	global_load_dwordx4 v[184:187], v0, s[0:1] offset:2048
	global_load_dwordx4 v[188:191], v0, s[0:1] offset:3072
	s_add_u32 s0, s20, 0x2000
	s_addc_u32 s1, s21, 0
	global_load_dwordx4 v[192:195], v0, s[0:1]
	global_load_dwordx4 v[196:199], v0, s[0:1] offset:1024
	global_load_dwordx4 v[200:203], v0, s[0:1] offset:2048
	global_load_dwordx4 v[204:207], v0, s[0:1] offset:3072
	s_mul_i32 s60, s56, 0x9000
	s_add_u32 s60, s60, 0x3187000
	s_add_u32 s0, s92, s60
	s_addc_u32 s1, s93, 0
	global_load_dwordx4 v[208:211], v0, s[0:1]
	global_load_dwordx4 v[212:215], v0, s[0:1] offset:1024
	global_load_dwordx4 v[216:219], v0, s[0:1] offset:2048
	global_load_dwordx4 v[220:223], v0, s[0:1] offset:3072
	s_mul_i32 s60, s56, 0x9000
	s_add_u32 s60, s60, 0x3186000
	s_add_u32 s0, s92, s60
	s_addc_u32 s1, s93, 0
	global_load_dwordx4 v[224:227], v0, s[0:1]
	global_load_dwordx4 v[228:231], v0, s[0:1] offset:1024
	global_load_dwordx4 v[232:235], v0, s[0:1] offset:2048
	global_load_dwordx4 v[236:239], v0, s[0:1] offset:3072
	s_waitcnt vmcnt(0)
	v_pk_add_f32 v[208:209], v[208:209], 1.0 op_sel_hi:[1,0]
	v_pk_add_f32 v[210:211], v[210:211], 1.0 op_sel_hi:[1,0]
	v_pk_add_f32 v[212:213], v[212:213], 1.0 op_sel_hi:[1,0]
	v_pk_add_f32 v[214:215], v[214:215], 1.0 op_sel_hi:[1,0]
	v_pk_add_f32 v[216:217], v[216:217], 1.0 op_sel_hi:[1,0]
	v_pk_add_f32 v[218:219], v[218:219], 1.0 op_sel_hi:[1,0]
	v_pk_add_f32 v[220:221], v[220:221], 1.0 op_sel_hi:[1,0]
	v_pk_add_f32 v[222:223], v[222:223], 1.0 op_sel_hi:[1,0]

; __device__ __forceinline__ float lo_bf(unsigned w) { return __uint_as_float(w << 16); }
; __device__ __forceinline__ float hi_bf(unsigned w) { return __uint_as_float(w & 0xffff0000u); }
; template <bool HAS_F, bool HAS_H>
; __device__ __forceinline__ void phase_rows(const Params& p, int sp, int sn, float resw, bool from_input, bool write_x = true) {
;     ...
;     for (int row = gw; row < T; row += NGW) {
;         const int b = row_batch(row);
;         const float* xin = !from_input ? p.out + (size_t)row * D : (row < TP ? p.in[0] + (size_t)row * D : p.in[1] + (size_t)(row - TP) * D);
;         f32x4 v[4];
; #pragma unroll
;         for (int j = 0; j < 4; ++j) v[j] = *(const f32x4*)(xin + 4 * lane + 256 * j);
;         if (HAS_F) {
;             f32x4 f[4]; float ss = 0.f;
; #pragma unroll
;             for (int j = 0; j < 4; ++j) { const u32x2 w = *(const u32x2*)(F + (size_t)row * D + 4 * lane + 256 * j);
;                 f[j] = (f32x4){lo_bf(w.x), hi_bf(w.x), lo_bf(w.y), hi_bf(w.y)}; ss += (f[j].x * f[j].x + f[j].y * f[j].y) + (f[j].z * f[j].z + f[j].w * f[j].w); }
;             const float rs = 1.0f / sqrtf(wave_sum(ss) * (1.0f / D) + EPS) * resw;
.Lrp12_loop3:
	s_add_u32 s57, s55, 16
	s_min_u32 s57, s57, s54
	s_lshl_b32 s60, s57, 12
	s_add_u32 s64, s84, s60
	s_addc_u32 s65, s85, 0
	s_lshl_b32 s60, s57, 11
	s_add_u32 s66, s82, s60
	s_addc_u32 s67, s83, 0
	global_load_dwordx4 v[68:71], v0, s[64:65] nt
	global_load_dwordx4 v[72:75], v0, s[64:65] offset:1024 nt
	global_load_dwordx4 v[76:79], v0, s[64:65] offset:2048 nt
	global_load_dwordx4 v[80:83], v0, s[64:65] offset:3072 nt
	global_load_dwordx2 v[84:85], v1, s[66:67] nt
	global_load_dwordx2 v[86:87], v1, s[66:67] offset:512 nt
	global_load_dwordx2 v[88:89], v1, s[66:67] offset:1024 nt
	global_load_dwordx2 v[90:91], v1, s[66:67] offset:1536 nt
	s_lshr_b32 s60, s55, 11
	s_sub_u32 s61, s55, 0x8000
	s_lshr_b32 s61, s61, 12
	s_add_u32 s61, s61, 16
	s_cmp_lt_u32 s55, 0x8000
	s_cselect_b32 s63, s60, s61
	s_cmp_eq_u32 s63, s56
	s_cbranch_scc1 .Lrp12_pk7
	s_mov_b32 s56, s63
	s_mul_i32 s60, s56, 0x9000
	s_add_u32 s60, s60, 0x3185000
	s_add_u32 s0, s92, s60
	s_addc_u32 s1, s93, 0
	global_load_dwordx4 v[160:163], v0, s[0:1]
	global_load_dwordx4 v[164:167], v0, s[0:1] offset:1024
	global_load_dwordx4 v[168:171], v0, s[0:1] offset:2048
	global_load_dwordx4 v[172:175], v0, s[0:1] offset:3072
	s_add_u32 s0, s22, 0x1000
	s_addc_u32 s1, s23, 0
	global_load_dwordx4 v[176:179], v0, s[0:1]
	global_load_dwordx4 v[180:183], v0, s[0:1] offset:1024
	global_load_dwordx4 v[184:187], v0, s[0:1] offset:2048
	global_load_dwordx4 v[188:191], v0, s[0:1] offset:3072
	s_add_u32 s0, s20, 0x2000
	s_addc_u32 s1, s21, 0
	global_load_dwordx4 v[192:195], v0, s[0:1]
	global_load_dwordx4 v[196:199], v0, s[0:1] offset:1024
	global_load_dwordx4 v[200:203], v0, s[0:1] offset:2048
	global_load_dwordx4 v[204:207], v0, s[0:1] offset:3072
	s_mul_i32 s60, s56, 0x9000
	s_add_u32 s60, s60, 0x3187000
	s_add_u32 s0, s92, s60
	s_addc_u32 s1, s93, 0
	global_load_dwordx4 v[208:211], v0, s[0:1]
	global_load_dwordx4 v[212:215], v0, s[0:1] offset:1024
	global_load_dwordx4 v[216:219], v0, s[0:1] offset:2048
	global_load_dwordx4 v[220:223], v0, s[0:1] offset:3072
	s_mul_i32 s60, s56, 0x9000
	s_add_u32 s60, s60, 0x3186000
	s_add_u32 s0, s92, s60
	s_addc_u32 s1, s93, 0
	global_load_dwordx4 v[224:227], v0, s[0:1]
	global_load_dwordx4 v[228:231], v0, s[0:1] offset:1024
	global_load_dwordx4 v[232:235], v0, s[0:1] offset:2048
	global_load_dwordx4 v[236:239], v0, s[0:1] offset:3072
	s_waitcnt vmcnt(0)
	v_pk_add_f32 v[208:209], v[208:209], 1.0 op_sel_hi:[1,0]
	v_pk_add_f32 v[210:211], v[210:211], 1.0 op_sel_hi:[1,0]
	v_pk_add_f32 v[212:213], v[212:213], 1.0 op_sel_hi:[1,0]
	v_pk_add_f32 v[214:215], v[214:215], 1.0 op_sel_hi:[1,0]
	v_pk_add_f32 v[216:217], v[216:217], 1.0 op_sel_hi:[1,0]
	v_pk_add_f32 v[218:219], v[218:219], 1.0 op_sel_hi:[1,0]
	v_pk_add_f32 v[220:221], v[220:221], 1.0 op_sel_hi:[1,0]
	v_pk_add_f32 v[222:223], v[222:223], 1.0 op_sel_hi:[1,0]
.Lrp12_pk7:
	s_waitcnt vmcnt(24)
	v_lshlrev_b32_e32 v112, 16, v20
	v_and_b32_e32 v113, 0xffff0000, v20
	v_lshlrev_b32_e32 v114, 16, v21
	v_and_b32_e32 v115, 0xffff0000, v21
	v_lshlrev_b32_e32 v116, 16, v22
	v_and_b32_e32 v117, 0xffff0000, v22
	v_lshlrev_b32_e32 v118, 16, v23
	v_and_b32_e32 v119, 0xffff0000, v23
	v_lshlrev_b32_e32 v120, 16, v24
	v_and_b32_e32 v121, 0xffff0000, v24
	v_lshlrev_b32_e32 v122, 16, v25
	v_and_b32_e32 v123, 0xffff0000, v25
	v_lshlrev_b32_e32 v124, 16, v26
	v_and_b32_e32 v125, 0xffff0000, v26
	v_lshlrev_b32_e32 v100, 16, v27
	v_and_b32_e32 v101, 0xffff0000, v27
	v_pk_mul_f32 v[102:103], v[112:113], v[112:113]
	v_pk_mul_f32 v[106:107], v[114:115], v[114:115]
	v_pk_fma_f32 v[102:103], v[116:117], v[116:117], v[102:103]
	v_pk_fma_f32 v[106:107], v[118:119], v[118:119], v[106:107]
	v_pk_fma_f32 v[102:103], v[120:121], v[120:121], v[102:103]
	v_pk_fma_f32 v[106:107], v[122:123], v[122:123], v[106:107]
	v_pk_fma_f32 v[102:103], v[124:125], v[124:125], v[102:103]
	v_pk_fma_f32 v[106:107], v[100:101], v[100:101], v[106:107]
	v_pk_add_f32 v[102:103], v[102:103], v[106:107]
	v_add_f32_e32 v102, v102, v103
	s_nop 1
	v_add_f32_dpp v102, v102, v102 quad_perm:[1,0,3,2] row_mask:0xf bank_mask:0xf
	s_nop 1
	v_add_f32_dpp v102, v102, v102 quad_perm:[2,3,0,1] row_mask:0xf bank_mask:0xf
	s_nop 1
	v_add_f32_dpp v102, v102, v102 row_half_mirror row_mask:0xf bank_mask:0xf
	s_nop 1
	v_add_f32_dpp v102, v102, v102 row_mirror row_mask:0xf bank_mask:0xf
	s_nop 1
	v_add_f32_dpp v102, v102, v102 row_bcast:15 row_mask:0xa bank_mask:0xf
	s_nop 1
	v_add_f32_dpp v102, v102, v102 row_bcast:31 row_mask:0xc bank_mask:0xf
	s_nop 1
	v_readlane_b32 s74, v102, 63
	s_nop 2
	v_mov_b32_e32 v102, s74
	v_fmamk_f32 v102, v102, 0x3a800000, v2
	v_mul_f32_e32 v103, 0x4f800000, v102
	v_cmp_gt_f32_e32 vcc, 0xf800000, v102
	s_nop 1
	v_cndmask_b32_e32 v102, v102, v103, vcc
	v_sqrt_f32_e32 v103, v102
	s_nop 0
	v_add_u32_e32 v104, -1, v103
	v_add_u32_e32 v106, 1, v103
	v_fma_f32 v107, -v104, v103, v102
	v_fma_f32 v108, -v106, v103, v102
	v_cmp_ge_f32_e64 s[76:77], 0, v107
	s_nop 1
	v_cndmask_b32_e64 v103, v103, v104, s[76:77]
	v_cmp_lt_f32_e64 s[76:77], 0, v108
	s_nop 1
	v_cndmask_b32_e64 v103, v103, v106, s[76:77]
	v_mul_f32_e32 v104, 0x37800000, v103
	v_cndmask_b32_e32 v103, v103, v104, vcc
	v_cmp_class_f32_e32 vcc, v102, v3
	s_nop 1
	v_cndmask_b32_e32 v102, v103, v102, vcc
	v_div_scale_f32 v103, s[76:77], v102, v102, 1.0
	v_rcp_f32_e32 v104, v103
	v_div_scale_f32 v106, vcc, 1.0, v102, 1.0
	v_fma_f32 v107, -v103, v104, 1.0
	v_fmac_f32_e32 v104, v107, v104
	v_mul_f32_e32 v107, v106, v104
	v_fma_f32 v108, -v103, v107, v106
	v_fmac_f32_e32 v107, v108, v104
	v_fma_f32 v103, -v103, v107, v106
	v_div_fmas_f32 v103, v103, v104, v107
	v_div_fixup_f32 v110, v103, v102, 1.0
; __device__ __forceinline__ unsigned pk_bf16(float lo, float hi) { const f32x2 v = {lo, hi}; const bf16x2_t b = __builtin_convertvector(v, bf16x2_t); return __builtin_bit_cast(unsigned, b); }
; template <bool HAS_F, bool HAS_H>
; __device__ __forceinline__ void phase_rows(const Params& p, int sp, int sn, float resw, bool from_input, bool write_x = true) {
;     ...
;             for (int j = 0; j < 4; ++j) { const f32x4 g = *(const f32x4*)(gate + 4 * lane + 256 * j), q = *(const f32x4*)(gp + 4 * lane + 256 * j);
;                 v[j] = v[j] + g * (f[j] * rs * q);
;                 if (write_x) *(f32x4*)(p.out + (size_t)row * D + 4 * lane + 256 * j) = v[j]; }
;         }
;         if (HAS_H) {
;             float ss = 0.f;
; #pragma unroll
;             for (int j = 0; j < 4; ++j) ss += (v[j].x * v[j].x + v[j].y * v[j].y) + (v[j].z * v[j].z + v[j].w * v[j].w);
;             const float rs = 1.0f / sqrtf(wave_sum(ss) * (1.0f / D) + EPS);
;             const float* sh = mod + b * 9216 + sn * 3072; const float* scl = sh + 1024; const float* gq = p.in[6] + sn * D;
; #pragma unroll
;             for (int j = 0; j < 4; ++j) { const f32x4 a = *(const f32x4*)(sh + 4 * lane + 256 * j), s = *(const f32x4*)(scl + 4 * lane + 256 * j), q = *(const f32x4*)(gq + 4 * lane + 256 * j);
;                 const f32x4 h = (v[j] * rs * q) * (s + 1.0f) + a;
;                 u32x2 w; w.x = pk_bf16(h.x, h.y); w.y = pk_bf16(h.z, h.w);
;                 *(u32x2*)(H + (size_t)row * D + 4 * lane + 256 * j) = w; }
	v_pk_mul_f32 v[112:113], v[112:113], v[110:111] op_sel_hi:[1,0]
	v_pk_mul_f32 v[114:115], v[114:115], v[110:111] op_sel_hi:[1,0]
	v_pk_mul_f32 v[116:117], v[116:117], v[110:111] op_sel_hi:[1,0]
	v_pk_mul_f32 v[118:119], v[118:119], v[110:111] op_sel_hi:[1,0]
	v_pk_mul_f32 v[120:121], v[120:121], v[110:111] op_sel_hi:[1,0]
	v_pk_mul_f32 v[122:123], v[122:123], v[110:111] op_sel_hi:[1,0]
	v_pk_mul_f32 v[124:125], v[124:125], v[110:111] op_sel_hi:[1,0]
	v_pk_mul_f32 v[100:101], v[100:101], v[110:111] op_sel_hi:[1,0]
	v_pk_mul_f32 v[112:113], v[176:177], v[112:113]
	v_pk_mul_f32 v[114:115], v[178:179], v[114:115]
	v_pk_mul_f32 v[116:117], v[180:181], v[116:117]
	v_pk_mul_f32 v[118:119], v[182:183], v[118:119]
	v_pk_mul_f32 v[120:121], v[184:185], v[120:121]
	v_pk_mul_f32 v[122:123], v[186:187], v[122:123]
	v_pk_mul_f32 v[124:125], v[188:189], v[124:125]
	v_pk_mul_f32 v[100:101], v[190:191], v[100:101]
	v_pk_fma_f32 v[4:5], v[160:161], v[112:113], v[4:5]
	v_pk_fma_f32 v[6:7], v[162:163], v[114:115], v[6:7]
	v_pk_fma_f32 v[8:9], v[164:165], v[116:117], v[8:9]
	v_pk_fma_f32 v[10:11], v[166:167], v[118:119], v[10:11]
	v_pk_fma_f32 v[12:13], v[168:169], v[120:121], v[12:13]
	v_pk_fma_f32 v[14:15], v[170:171], v[122:123], v[14:15]
	v_pk_fma_f32 v[16:17], v[172:173], v[124:125], v[16:17]
	v_pk_fma_f32 v[18:19], v[174:175], v[100:101], v[18:19]
	v_pk_mul_f32 v[102:103], v[4:5], v[4:5]
	v_pk_mul_f32 v[106:107], v[6:7], v[6:7]
	v_pk_fma_f32 v[102:103], v[8:9], v[8:9], v[102:103]
	v_pk_fma_f32 v[106:107], v[10:11], v[10:11], v[106:107]
	v_pk_fma_f32 v[102:103], v[12:13], v[12:13], v[102:103]
	v_pk_fma_f32 v[106:107], v[14:15], v[14:15], v[106:107]
	v_pk_fma_f32 v[102:103], v[16:17], v[16:17], v[102:103]
	v_pk_fma_f32 v[106:107], v[18:19], v[18:19], v[106:107]
	v_pk_add_f32 v[102:103], v[102:103], v[106:107]
	v_add_f32_e32 v102, v102, v103
	s_nop 1
	v_add_f32_dpp v102, v102, v102 quad_perm:[1,0,3,2] row_mask:0xf bank_mask:0xf
	s_nop 1
	v_add_f32_dpp v102, v102, v102 quad_perm:[2,3,0,1] row_mask:0xf bank_mask:0xf
	s_nop 1
	v_add_f32_dpp v102, v102, v102 row_half_mirror row_mask:0xf bank_mask:0xf
	s_nop 1
	v_add_f32_dpp v102, v102, v102 row_mirror row_mask:0xf bank_mask:0xf
	s_nop 1
	v_add_f32_dpp v102, v102, v102 row_bcast:15 row_mask:0xa bank_mask:0xf
	s_nop 1
	v_add_f32_dpp v102, v102, v102 row_bcast:31 row_mask:0xc bank_mask:0xf
	s_nop 1
	v_readlane_b32 s74, v102, 63
	s_nop 2
	v_mov_b32_e32 v102, s74
	v_fmamk_f32 v102, v102, 0x3a800000, v2
	v_mul_f32_e32 v103, 0x4f800000, v102
	v_cmp_gt_f32_e32 vcc, 0xf800000, v102
	s_nop 1
	v_cndmask_b32_e32 v102, v102, v103, vcc
	v_sqrt_f32_e32 v103, v102
	s_nop 0
	v_add_u32_e32 v104, -1, v103
	v_add_u32_e32 v106, 1, v103
	v_fma_f32 v107, -v104, v103, v102
	v_fma_f32 v108, -v106, v103, v102
	v_cmp_ge_f32_e64 s[76:77], 0, v107
	s_nop 1
	v_cndmask_b32_e64 v103, v103, v104, s[76:77]
	v_cmp_lt_f32_e64 s[76:77], 0, v108
	s_nop 1
	v_cndmask_b32_e64 v103, v103, v106, s[76:77]
	v_mul_f32_e32 v104, 0x37800000, v103
	v_cndmask_b32_e32 v103, v103, v104, vcc
	v_cmp_class_f32_e32 vcc, v102, v3
	s_nop 1
	v_cndmask_b32_e32 v102, v103, v102, vcc
	v_div_scale_f32 v103, s[76:77], v102, v102, 1.0
	v_rcp_f32_e32 v104, v103
	v_div_scale_f32 v106, vcc, 1.0, v102, 1.0
	v_fma_f32 v107, -v103, v104, 1.0
	v_fmac_f32_e32 v104, v107, v104
	v_mul_f32_e32 v107, v106, v104
	v_fma_f32 v108, -v103, v107, v106
	v_fmac_f32_e32 v107, v108, v104
	v_fma_f32 v103, -v103, v107, v106
	v_div_fmas_f32 v103, v103, v104, v107
	v_div_fixup_f32 v110, v103, v102, 1.0
	s_lshl_b32 s60, s55, 11
	s_add_u32 s70, s78, s60
	s_addc_u32 s71, s79, 0
	v_pk_mul_f32 v[112:113], v[4:5], v[110:111] op_sel_hi:[1,0]
	v_pk_mul_f32 v[114:115], v[6:7], v[110:111] op_sel_hi:[1,0]
	v_pk_mul_f32 v[116:117], v[8:9], v[110:111] op_sel_hi:[1,0]
	v_pk_mul_f32 v[118:119], v[10:11], v[110:111] op_sel_hi:[1,0]
	v_pk_mul_f32 v[120:121], v[12:13], v[110:111] op_sel_hi:[1,0]
	v_pk_mul_f32 v[122:123], v[14:15], v[110:111] op_sel_hi:[1,0]
	v_pk_mul_f32 v[124:125], v[16:17], v[110:111] op_sel_hi:[1,0]
	v_pk_mul_f32 v[100:101], v[18:19], v[110:111] op_sel_hi:[1,0]
	v_pk_mul_f32 v[112:113], v[192:193], v[112:113]
	v_pk_mul_f32 v[114:115], v[194:195], v[114:115]
	v_pk_mul_f32 v[116:117], v[196:197], v[116:117]
	v_pk_mul_f32 v[118:119], v[198:199], v[118:119]
	v_pk_mul_f32 v[120:121], v[200:201], v[120:121]
	v_pk_mul_f32 v[122:123], v[202:203], v[122:123]
	v_pk_mul_f32 v[124:125], v[204:205], v[124:125]
	v_pk_mul_f32 v[100:101], v[206:207], v[100:101]
	v_pk_fma_f32 v[112:113], v[208:209], v[112:113], v[224:225]
	v_pk_fma_f32 v[114:115], v[210:211], v[114:115], v[226:227]
	v_pk_fma_f32 v[116:117], v[212:213], v[116:117], v[228:229]
	v_pk_fma_f32 v[118:119], v[214:215], v[118:119], v[230:231]
	v_pk_fma_f32 v[120:121], v[216:217], v[120:121], v[232:233]
	v_pk_fma_f32 v[122:123], v[218:219], v[122:123], v[234:235]
	v_pk_fma_f32 v[124:125], v[220:221], v[124:125], v[236:237]
	v_pk_fma_f32 v[100:101], v[222:223], v[100:101], v[238:239]
	v_cvt_pk_bf16_f32 v240, v112, v113
	v_cvt_pk_bf16_f32 v241, v114, v115
	v_cvt_pk_bf16_f32 v242, v116, v117
	v_cvt_pk_bf16_f32 v243, v118, v119
	v_cvt_pk_bf16_f32 v244, v120, v121
	v_cvt_pk_bf16_f32 v245, v122, v123
	v_cvt_pk_bf16_f32 v246, v124, v125
	v_cvt_pk_bf16_f32 v247, v100, v101
	global_store_dwordx2 v1, v[240:241], s[70:71]
	global_store_dwordx2 v1, v[242:243], s[70:71] offset:512
	global_store_dwordx2 v1, v[244:245], s[70:71] offset:1024
	global_store_dwordx2 v1, v[246:247], s[70:71] offset:1536
	s_add_u32 s55, s55, 8
	s_add_u32 s57, s55, 16
	s_min_u32 s57, s57, s54
	s_lshl_b32 s60, s57, 12
	s_add_u32 s64, s84, s60
	s_addc_u32 s65, s85, 0
	s_lshl_b32 s60, s57, 11
	s_add_u32 s66, s82, s60
	s_addc_u32 s67, s83, 0
	global_load_dwordx4 v[4:7], v0, s[64:65] nt
	global_load_dwordx4 v[8:11], v0, s[64:65] offset:1024 nt
	global_load_dwordx4 v[12:15], v0, s[64:65] offset:2048 nt
	global_load_dwordx4 v[16:19], v0, s[64:65] offset:3072 nt
	global_load_dwordx2 v[20:21], v1, s[66:67] nt
	global_load_dwordx2 v[22:23], v1, s[66:67] offset:512 nt
	global_load_dwordx2 v[24:25], v1, s[66:67] offset:1024 nt
	global_load_dwordx2 v[26:27], v1, s[66:67] offset:1536 nt
	s_lshr_b32 s60, s55, 11
	s_sub_u32 s61, s55, 0x8000
	s_lshr_b32 s61, s61, 12
	s_add_u32 s61, s61, 16
	s_cmp_lt_u32 s55, 0x8000
	s_cselect_b32 s63, s60, s61
	s_cmp_eq_u32 s63, s56
	s_cbranch_scc1 .Lrp12_pk8
; __device__ __forceinline__ float lo_bf(unsigned w) { return __uint_as_float(w << 16); }
; __device__ __forceinline__ float hi_bf(unsigned w) { return __uint_as_float(w & 0xffff0000u); }
; template <bool HAS_F, bool HAS_H>
; __device__ __forceinline__ void phase_rows(const Params& p, int sp, int sn, float resw, bool from_input, bool write_x = true) {
;     ...
;             f32x4 f[4]; float ss = 0.f;
; #pragma unroll
;             for (int j = 0; j < 4; ++j) { const u32x2 w = *(const u32x2*)(F + (size_t)row * D + 4 * lane + 256 * j);
;                 f[j] = (f32x4){lo_bf(w.x), hi_bf(w.x), lo_bf(w.y), hi_bf(w.y)}; ss += (f[j].x * f[j].x + f[j].y * f[j].y) + (f[j].z * f[j].z + f[j].w * f[j].w); }
;             const float rs = 1.0f / sqrtf(wave_sum(ss) * (1.0f / D) + EPS) * resw;
;             const float* gate = mod + b * 9216 + sp * 3072 + 2048; const float* gp = p.in[7] + sp * D;
; #pragma unroll
;             for (int j = 0; j < 4; ++j) { const f32x4 g = *(const f32x4*)(gate + 4 * lane + 256 * j), q = *(const f32x4*)(gp + 4 * lane + 256 * j);
	s_mov_b32 s56, s63
	s_mul_i32 s60, s56, 0x9000
	s_add_u32 s60, s60, 0x3185000
	s_add_u32 s0, s92, s60
	s_addc_u32 s1, s93, 0
	global_load_dwordx4 v[160:163], v0, s[0:1]
	global_load_dwordx4 v[164:167], v0, s[0:1] offset:1024
	global_load_dwordx4 v[168:171], v0, s[0:1] offset:2048
	global_load_dwordx4 v[172:175], v0, s[0:1] offset:3072
	s_add_u32 s0, s22, 0x1000
	s_addc_u32 s1, s23, 0
	global_load_dwordx4 v[176:179], v0, s[0:1]
	global_load_dwordx4 v[180:183], v0, s[0:1] offset:1024
	global_load_dwordx4 v[184:187], v0, s[0:1] offset:2048
	global_load_dwordx4 v[188:191], v0, s[0:1] offset:3072
	s_add_u32 s0, s20, 0x2000
	s_addc_u32 s1, s21, 0
	global_load_dwordx4 v[192:195], v0, s[0:1]
	global_load_dwordx4 v[196:199], v0, s[0:1] offset:1024
	global_load_dwordx4 v[200:203], v0, s[0:1] offset:2048
	global_load_dwordx4 v[204:207], v0, s[0:1] offset:3072
	s_mul_i32 s60, s56, 0x9000
	s_add_u32 s60, s60, 0x3187000
	s_add_u32 s0, s92, s60
	s_addc_u32 s1, s93, 0
	global_load_dwordx4 v[208:211], v0, s[0:1]
	global_load_dwordx4 v[212:215], v0, s[0:1] offset:1024
	global_load_dwordx4 v[216:219], v0, s[0:1] offset:2048
	global_load_dwordx4 v[220:223], v0, s[0:1] offset:3072
	s_mul_i32 s60, s56, 0x9000
	s_add_u32 s60, s60, 0x3186000
	s_add_u32 s0, s92, s60
	s_addc_u32 s1, s93, 0
	global_load_dwordx4 v[224:227], v0, s[0:1]
	global_load_dwordx4 v[228:231], v0, s[0:1] offset:1024
	global_load_dwordx4 v[232:235], v0, s[0:1] offset:2048
	global_load_dwordx4 v[236:239], v0, s[0:1] offset:3072
	s_waitcnt vmcnt(0)
	v_pk_add_f32 v[208:209], v[208:209], 1.0 op_sel_hi:[1,0]
	v_pk_add_f32 v[210:211], v[210:211], 1.0 op_sel_hi:[1,0]
	v_pk_add_f32 v[212:213], v[212:213], 1.0 op_sel_hi:[1,0]
	v_pk_add_f32 v[214:215], v[214:215], 1.0 op_sel_hi:[1,0]
	v_pk_add_f32 v[216:217], v[216:217], 1.0 op_sel_hi:[1,0]
	v_pk_add_f32 v[218:219], v[218:219], 1.0 op_sel_hi:[1,0]
	v_pk_add_f32 v[220:221], v[220:221], 1.0 op_sel_hi:[1,0]
	v_pk_add_f32 v[222:223], v[222:223], 1.0 op_sel_hi:[1,0]
.Lrp12_pk8:
	s_waitcnt vmcnt(24)
	v_lshlrev_b32_e32 v112, 16, v52
	v_and_b32_e32 v113, 0xffff0000, v52
	v_lshlrev_b32_e32 v114, 16, v53
	v_and_b32_e32 v115, 0xffff0000, v53
	v_lshlrev_b32_e32 v116, 16, v54
	v_and_b32_e32 v117, 0xffff0000, v54
	v_lshlrev_b32_e32 v118, 16, v55
	v_and_b32_e32 v119, 0xffff0000, v55
	v_lshlrev_b32_e32 v120, 16, v56
	v_and_b32_e32 v121, 0xffff0000, v56
	v_lshlrev_b32_e32 v122, 16, v57
	v_and_b32_e32 v123, 0xffff0000, v57
	v_lshlrev_b32_e32 v124, 16, v58
	v_and_b32_e32 v125, 0xffff0000, v58
	v_lshlrev_b32_e32 v100, 16, v59
	v_and_b32_e32 v101, 0xffff0000, v59
	v_pk_mul_f32 v[102:103], v[112:113], v[112:113]
	v_pk_mul_f32 v[106:107], v[114:115], v[114:115]
	v_pk_fma_f32 v[102:103], v[116:117], v[116:117], v[102:103]
	v_pk_fma_f32 v[106:107], v[118:119], v[118:119], v[106:107]
	v_pk_fma_f32 v[102:103], v[120:121], v[120:121], v[102:103]
	v_pk_fma_f32 v[106:107], v[122:123], v[122:123], v[106:107]
	v_pk_fma_f32 v[102:103], v[124:125], v[124:125], v[102:103]
	v_pk_fma_f32 v[106:107], v[100:101], v[100:101], v[106:107]
	v_pk_add_f32 v[102:103], v[102:103], v[106:107]
	v_add_f32_e32 v102, v102, v103
	s_nop 1
	v_add_f32_dpp v102, v102, v102 quad_perm:[1,0,3,2] row_mask:0xf bank_mask:0xf
	s_nop 1
	v_add_f32_dpp v102, v102, v102 quad_perm:[2,3,0,1] row_mask:0xf bank_mask:0xf
	s_nop 1
	v_add_f32_dpp v102, v102, v102 row_half_mirror row_mask:0xf bank_mask:0xf
	s_nop 1
	v_add_f32_dpp v102, v102, v102 row_mirror row_mask:0xf bank_mask:0xf
	s_nop 1
	v_add_f32_dpp v102, v102, v102 row_bcast:15 row_mask:0xa bank_mask:0xf
	s_nop 1
	v_add_f32_dpp v102, v102, v102 row_bcast:31 row_mask:0xc bank_mask:0xf
	s_nop 1
	v_readlane_b32 s74, v102, 63
	s_nop 2
	v_mov_b32_e32 v102, s74
	v_fmamk_f32 v102, v102, 0x3a800000, v2
	v_mul_f32_e32 v103, 0x4f800000, v102
	v_cmp_gt_f32_e32 vcc, 0xf800000, v102
	s_nop 1
	v_cndmask_b32_e32 v102, v102, v103, vcc
	v_sqrt_f32_e32 v103, v102
	s_nop 0
	v_add_u32_e32 v104, -1, v103
	v_add_u32_e32 v106, 1, v103
	v_fma_f32 v107, -v104, v103, v102
	v_fma_f32 v108, -v106, v103, v102
	v_cmp_ge_f32_e64 s[76:77], 0, v107
	s_nop 1
	v_cndmask_b32_e64 v103, v103, v104, s[76:77]
	v_cmp_lt_f32_e64 s[76:77], 0, v108
	s_nop 1
	v_cndmask_b32_e64 v103, v103, v106, s[76:77]
	v_mul_f32_e32 v104, 0x37800000, v103
	v_cndmask_b32_e32 v103, v103, v104, vcc
	v_cmp_class_f32_e32 vcc, v102, v3
	s_nop 1
	v_cndmask_b32_e32 v102, v103, v102, vcc
	v_div_scale_f32 v103, s[76:77], v102, v102, 1.0
	v_rcp_f32_e32 v104, v103
	v_div_scale_f32 v106, vcc, 1.0, v102, 1.0
	v_fma_f32 v107, -v103, v104, 1.0
	v_fmac_f32_e32 v104, v107, v104
	v_mul_f32_e32 v107, v106, v104
	v_fma_f32 v108, -v103, v107, v106
	v_fmac_f32_e32 v107, v108, v104
	v_fma_f32 v103, -v103, v107, v106
	v_div_fmas_f32 v103, v103, v104, v107
	v_div_fixup_f32 v110, v103, v102, 1.0
	v_pk_mul_f32 v[112:113], v[112:113], v[110:111] op_sel_hi:[1,0]
	v_pk_mul_f32 v[114:115], v[114:115], v[110:111] op_sel_hi:[1,0]
	v_pk_mul_f32 v[116:117], v[116:117], v[110:111] op_sel_hi:[1,0]
	v_pk_mul_f32 v[118:119], v[118:119], v[110:111] op_sel_hi:[1,0]
	v_pk_mul_f32 v[120:121], v[120:121], v[110:111] op_sel_hi:[1,0]
	v_pk_mul_f32 v[122:123], v[122:123], v[110:111] op_sel_hi:[1,0]
	v_pk_mul_f32 v[124:125], v[124:125], v[110:111] op_sel_hi:[1,0]
	v_pk_mul_f32 v[100:101], v[100:101], v[110:111] op_sel_hi:[1,0]
	v_pk_mul_f32 v[112:113], v[176:177], v[112:113]
	v_pk_mul_f32 v[114:115], v[178:179], v[114:115]
	v_pk_mul_f32 v[116:117], v[180:181], v[116:117]
	v_pk_mul_f32 v[118:119], v[182:183], v[118:119]
	v_pk_mul_f32 v[120:121], v[184:185], v[120:121]
	v_pk_mul_f32 v[122:123], v[186:187], v[122:123]
	v_pk_mul_f32 v[124:125], v[188:189], v[124:125]
; __device__ __forceinline__ unsigned pk_bf16(float lo, float hi) { const f32x2 v = {lo, hi}; const bf16x2_t b = __builtin_convertvector(v, bf16x2_t); return __builtin_bit_cast(unsigned, b); }
; template <bool HAS_F, bool HAS_H>
; __device__ __forceinline__ void phase_rows(const Params& p, int sp, int sn, float resw, bool from_input, bool write_x = true) {
;     ...
;             for (int j = 0; j < 4; ++j) { const f32x4 g = *(const f32x4*)(gate + 4 * lane + 256 * j), q = *(const f32x4*)(gp + 4 * lane + 256 * j);
;                 v[j] = v[j] + g * (f[j] * rs * q);
;                 if (write_x) *(f32x4*)(p.out + (size_t)row * D + 4 * lane + 256 * j) = v[j]; }
;         }
;         if (HAS_H) {
;             float ss = 0.f;
; #pragma unroll
;             for (int j = 0; j < 4; ++j) ss += (v[j].x * v[j].x + v[j].y * v[j].y) + (v[j].z * v[j].z + v[j].w * v[j].w);
;             const float rs = 1.0f / sqrtf(wave_sum(ss) * (1.0f / D) + EPS);
;             const float* sh = mod + b * 9216 + sn * 3072; const float* scl = sh + 1024; const float* gq = p.in[6] + sn * D;
; #pragma unroll
;             for (int j = 0; j < 4; ++j) { const f32x4 a = *(const f32x4*)(sh + 4 * lane + 256 * j), s = *(const f32x4*)(scl + 4 * lane + 256 * j), q = *(const f32x4*)(gq + 4 * lane + 256 * j);
;                 const f32x4 h = (v[j] * rs * q) * (s + 1.0f) + a;
;                 u32x2 w; w.x = pk_bf16(h.x, h.y); w.y = pk_bf16(h.z, h.w);
;                 *(u32x2*)(H + (size_t)row * D + 4 * lane + 256 * j) = w; }
	v_pk_mul_f32 v[100:101], v[190:191], v[100:101]
	v_pk_fma_f32 v[36:37], v[160:161], v[112:113], v[36:37]
	v_pk_fma_f32 v[38:39], v[162:163], v[114:115], v[38:39]
	v_pk_fma_f32 v[40:41], v[164:165], v[116:117], v[40:41]
	v_pk_fma_f32 v[42:43], v[166:167], v[118:119], v[42:43]
	v_pk_fma_f32 v[44:45], v[168:169], v[120:121], v[44:45]
	v_pk_fma_f32 v[46:47], v[170:171], v[122:123], v[46:47]
	v_pk_fma_f32 v[48:49], v[172:173], v[124:125], v[48:49]
	v_pk_fma_f32 v[50:51], v[174:175], v[100:101], v[50:51]
	v_pk_mul_f32 v[102:103], v[36:37], v[36:37]
	v_pk_mul_f32 v[106:107], v[38:39], v[38:39]
	v_pk_fma_f32 v[102:103], v[40:41], v[40:41], v[102:103]
	v_pk_fma_f32 v[106:107], v[42:43], v[42:43], v[106:107]
	v_pk_fma_f32 v[102:103], v[44:45], v[44:45], v[102:103]
	v_pk_fma_f32 v[106:107], v[46:47], v[46:47], v[106:107]
	v_pk_fma_f32 v[102:103], v[48:49], v[48:49], v[102:103]
	v_pk_fma_f32 v[106:107], v[50:51], v[50:51], v[106:107]
	v_pk_add_f32 v[102:103], v[102:103], v[106:107]
	v_add_f32_e32 v102, v102, v103
	s_nop 1
	v_add_f32_dpp v102, v102, v102 quad_perm:[1,0,3,2] row_mask:0xf bank_mask:0xf
	s_nop 1
	v_add_f32_dpp v102, v102, v102 quad_perm:[2,3,0,1] row_mask:0xf bank_mask:0xf
	s_nop 1
	v_add_f32_dpp v102, v102, v102 row_half_mirror row_mask:0xf bank_mask:0xf
	s_nop 1
	v_add_f32_dpp v102, v102, v102 row_mirror row_mask:0xf bank_mask:0xf
	s_nop 1
	v_add_f32_dpp v102, v102, v102 row_bcast:15 row_mask:0xa bank_mask:0xf
	s_nop 1
	v_add_f32_dpp v102, v102, v102 row_bcast:31 row_mask:0xc bank_mask:0xf
	s_nop 1
	v_readlane_b32 s74, v102, 63
	s_nop 2
	v_mov_b32_e32 v102, s74
	v_fmamk_f32 v102, v102, 0x3a800000, v2
	v_mul_f32_e32 v103, 0x4f800000, v102
	v_cmp_gt_f32_e32 vcc, 0xf800000, v102
	s_nop 1
	v_cndmask_b32_e32 v102, v102, v103, vcc
	v_sqrt_f32_e32 v103, v102
	s_nop 0
	v_add_u32_e32 v104, -1, v103
	v_add_u32_e32 v106, 1, v103
	v_fma_f32 v107, -v104, v103, v102
	v_fma_f32 v108, -v106, v103, v102
	v_cmp_ge_f32_e64 s[76:77], 0, v107
	s_nop 1
	v_cndmask_b32_e64 v103, v103, v104, s[76:77]
	v_cmp_lt_f32_e64 s[76:77], 0, v108
	s_nop 1
	v_cndmask_b32_e64 v103, v103, v106, s[76:77]
	v_mul_f32_e32 v104, 0x37800000, v103
	v_cndmask_b32_e32 v103, v103, v104, vcc
	v_cmp_class_f32_e32 vcc, v102, v3
	s_nop 1
	v_cndmask_b32_e32 v102, v103, v102, vcc
	v_div_scale_f32 v103, s[76:77], v102, v102, 1.0
	v_rcp_f32_e32 v104, v103
	v_div_scale_f32 v106, vcc, 1.0, v102, 1.0
	v_fma_f32 v107, -v103, v104, 1.0
	v_fmac_f32_e32 v104, v107, v104
	v_mul_f32_e32 v107, v106, v104
	v_fma_f32 v108, -v103, v107, v106
	v_fmac_f32_e32 v107, v108, v104
	v_fma_f32 v103, -v103, v107, v106
	v_div_fmas_f32 v103, v103, v104, v107
	v_div_fixup_f32 v110, v103, v102, 1.0
	s_lshl_b32 s60, s55, 11
	s_add_u32 s70, s78, s60
	s_addc_u32 s71, s79, 0
	v_pk_mul_f32 v[112:113], v[36:37], v[110:111] op_sel_hi:[1,0]
	v_pk_mul_f32 v[114:115], v[38:39], v[110:111] op_sel_hi:[1,0]
	v_pk_mul_f32 v[116:117], v[40:41], v[110:111] op_sel_hi:[1,0]
	v_pk_mul_f32 v[118:119], v[42:43], v[110:111] op_sel_hi:[1,0]
	v_pk_mul_f32 v[120:121], v[44:45], v[110:111] op_sel_hi:[1,0]
	v_pk_mul_f32 v[122:123], v[46:47], v[110:111] op_sel_hi:[1,0]
	v_pk_mul_f32 v[124:125], v[48:49], v[110:111] op_sel_hi:[1,0]
	v_pk_mul_f32 v[100:101], v[50:51], v[110:111] op_sel_hi:[1,0]
	v_pk_mul_f32 v[112:113], v[192:193], v[112:113]
	v_pk_mul_f32 v[114:115], v[194:195], v[114:115]
	v_pk_mul_f32 v[116:117], v[196:197], v[116:117]
	v_pk_mul_f32 v[118:119], v[198:199], v[118:119]
	v_pk_mul_f32 v[120:121], v[200:201], v[120:121]
	v_pk_mul_f32 v[122:123], v[202:203], v[122:123]
	v_pk_mul_f32 v[124:125], v[204:205], v[124:125]
	v_pk_mul_f32 v[100:101], v[206:207], v[100:101]
	v_pk_fma_f32 v[112:113], v[208:209], v[112:113], v[224:225]
	v_pk_fma_f32 v[114:115], v[210:211], v[114:115], v[226:227]
	v_pk_fma_f32 v[116:117], v[212:213], v[116:117], v[228:229]
	v_pk_fma_f32 v[118:119], v[214:215], v[118:119], v[230:231]
	v_pk_fma_f32 v[120:121], v[216:217], v[120:121], v[232:233]
	v_pk_fma_f32 v[122:123], v[218:219], v[122:123], v[234:235]
	v_pk_fma_f32 v[124:125], v[220:221], v[124:125], v[236:237]
	v_pk_fma_f32 v[100:101], v[222:223], v[100:101], v[238:239]
	v_cvt_pk_bf16_f32 v240, v112, v113
	v_cvt_pk_bf16_f32 v241, v114, v115
	v_cvt_pk_bf16_f32 v242, v116, v117
	v_cvt_pk_bf16_f32 v243, v118, v119
	v_cvt_pk_bf16_f32 v244, v120, v121
	v_cvt_pk_bf16_f32 v245, v122, v123
	v_cvt_pk_bf16_f32 v246, v124, v125
	v_cvt_pk_bf16_f32 v247, v100, v101
	global_store_dwordx2 v1, v[240:241], s[70:71]
	global_store_dwordx2 v1, v[242:243], s[70:71] offset:512
	global_store_dwordx2 v1, v[244:245], s[70:71] offset:1024
	global_store_dwordx2 v1, v[246:247], s[70:71] offset:1536
	s_add_u32 s55, s55, 8
	s_add_u32 s57, s55, 16
	s_min_u32 s57, s57, s54
	s_lshl_b32 s60, s57, 12
	s_add_u32 s64, s84, s60
	s_addc_u32 s65, s85, 0
	s_lshl_b32 s60, s57, 11
	s_add_u32 s66, s82, s60
	s_addc_u32 s67, s83, 0
	global_load_dwordx4 v[36:39], v0, s[64:65] nt
	global_load_dwordx4 v[40:43], v0, s[64:65] offset:1024 nt
	global_load_dwordx4 v[44:47], v0, s[64:65] offset:2048 nt
	global_load_dwordx4 v[48:51], v0, s[64:65] offset:3072 nt
	global_load_dwordx2 v[52:53], v1, s[66:67] nt
	global_load_dwordx2 v[54:55], v1, s[66:67] offset:512 nt
	global_load_dwordx2 v[56:57], v1, s[66:67] offset:1024 nt
	global_load_dwordx2 v[58:59], v1, s[66:67] offset:1536 nt
	s_lshr_b32 s60, s55, 11
	s_sub_u32 s61, s55, 0x8000
	s_lshr_b32 s61, s61, 12
	s_add_u32 s61, s61, 16
	s_cmp_lt_u32 s55, 0x8000
	s_cselect_b32 s63, s60, s61
	s_cmp_eq_u32 s63, s56
	s_cbranch_scc1 .Lrp12_pk9
; template <bool HAS_F, bool HAS_H>
; __device__ __forceinline__ void phase_rows(const Params& p, int sp, int sn, float resw, bool from_input, bool write_x = true) {
;     ...
;             const float* gate = mod + b * 9216 + sp * 3072 + 2048; const float* gp = p.in[7] + sp * D;
; #pragma unroll
;             for (int j = 0; j < 4; ++j) { const f32x4 g = *(const f32x4*)(gate + 4 * lane + 256 * j), q = *(const f32x4*)(gp + 4 * lane + 256 * j);
;     ...
;             const float* sh = mod + b * 9216 + sn * 3072; const float* scl = sh + 1024; const float* gq = p.in[6] + sn * D;
; #pragma unroll
;             for (int j = 0; j < 4; ++j) { const f32x4 a = *(const f32x4*)(sh + 4 * lane + 256 * j), s = *(const f32x4*)(scl + 4 * lane + 256 * j), q = *(const f32x4*)(gq + 4 * lane + 256 * j);
	s_mov_b32 s56, s63
	s_mul_i32 s60, s56, 0x9000
	s_add_u32 s60, s60, 0x3185000
	s_add_u32 s0, s92, s60
	s_addc_u32 s1, s93, 0
	global_load_dwordx4 v[160:163], v0, s[0:1]
	global_load_dwordx4 v[164:167], v0, s[0:1] offset:1024
	global_load_dwordx4 v[168:171], v0, s[0:1] offset:2048
	global_load_dwordx4 v[172:175], v0, s[0:1] offset:3072
	s_add_u32 s0, s22, 0x1000
	s_addc_u32 s1, s23, 0
	global_load_dwordx4 v[176:179], v0, s[0:1]
	global_load_dwordx4 v[180:183], v0, s[0:1] offset:1024
	global_load_dwordx4 v[184:187], v0, s[0:1] offset:2048
	global_load_dwordx4 v[188:191], v0, s[0:1] offset:3072
	s_add_u32 s0, s20, 0x2000
	s_addc_u32 s1, s21, 0
	global_load_dwordx4 v[192:195], v0, s[0:1]
	global_load_dwordx4 v[196:199], v0, s[0:1] offset:1024
	global_load_dwordx4 v[200:203], v0, s[0:1] offset:2048
	global_load_dwordx4 v[204:207], v0, s[0:1] offset:3072
	s_mul_i32 s60, s56, 0x9000
	s_add_u32 s60, s60, 0x3187000
	s_add_u32 s0, s92, s60
	s_addc_u32 s1, s93, 0
	global_load_dwordx4 v[208:211], v0, s[0:1]
	global_load_dwordx4 v[212:215], v0, s[0:1] offset:1024
	global_load_dwordx4 v[216:219], v0, s[0:1] offset:2048
	global_load_dwordx4 v[220:223], v0, s[0:1] offset:3072
	s_mul_i32 s60, s56, 0x9000
	s_add_u32 s60, s60, 0x3186000
	s_add_u32 s0, s92, s60
	s_addc_u32 s1, s93, 0
	global_load_dwordx4 v[224:227], v0, s[0:1]
	global_load_dwordx4 v[228:231], v0, s[0:1] offset:1024
	global_load_dwordx4 v[232:235], v0, s[0:1] offset:2048
	global_load_dwordx4 v[236:239], v0, s[0:1] offset:3072
	s_waitcnt vmcnt(0)
	v_pk_add_f32 v[208:209], v[208:209], 1.0 op_sel_hi:[1,0]
	v_pk_add_f32 v[210:211], v[210:211], 1.0 op_sel_hi:[1,0]
	v_pk_add_f32 v[212:213], v[212:213], 1.0 op_sel_hi:[1,0]
	v_pk_add_f32 v[214:215], v[214:215], 1.0 op_sel_hi:[1,0]
	v_pk_add_f32 v[216:217], v[216:217], 1.0 op_sel_hi:[1,0]
	v_pk_add_f32 v[218:219], v[218:219], 1.0 op_sel_hi:[1,0]
	v_pk_add_f32 v[220:221], v[220:221], 1.0 op_sel_hi:[1,0]
	v_pk_add_f32 v[222:223], v[222:223], 1.0 op_sel_hi:[1,0]

; __device__ __forceinline__ float lo_bf(unsigned w) { return __uint_as_float(w << 16); }
; __device__ __forceinline__ float hi_bf(unsigned w) { return __uint_as_float(w & 0xffff0000u); }
; __device__ __forceinline__ void phase_final(const Params& p) {
;     ...
;     for (int row = gw; row < T; row += NGW) {
;         const int b = row_batch(row);
;         f32x4 v[4], m[4], f[4]; float sm = 0.f, sf = 0.f;
; #pragma unroll
;         for (int j = 0; j < 4; ++j) { v[j] = *(const f32x4*)(p.out + (size_t)row * D + 4 * lane + 256 * j);
;             const u32x2 wm = *(const u32x2*)(Fm + (size_t)row * D + 4 * lane + 256 * j), wf = *(const u32x2*)(F2 + (size_t)row * D + 4 * lane + 256 * j);
;             m[j] = (f32x4){lo_bf(wm.x), hi_bf(wm.x), lo_bf(wm.y), hi_bf(wm.y)}; f[j] = (f32x4){lo_bf(wf.x), hi_bf(wf.x), lo_bf(wf.y), hi_bf(wf.y)};
;             sm += (m[j].x * m[j].x + m[j].y * m[j].y) + (m[j].z * m[j].z + m[j].w * m[j].w); sf += (f[j].x * f[j].x + f[j].y * f[j].y) + (f[j].z * f[j].z + f[j].w * f[j].w); }
;         const float rm = 1.0f / sqrtf(wave_sum(sm) * (1.0f / D) + EPS), rf = 1.0f / sqrtf(wave_sum(sf) * (1.0f / D) + EPS) * 0.5f;
;         const float* g1 = mod + b * 9216 + 1 * 3072 + 2048; const float* g2 = mod + b * 9216 + 2 * 3072 + 2048;
;         const float* q1 = p.in[7] + 1 * D; const float* q2 = p.in[7] + 2 * D;
.Lrp15_chunk1:
	s_mul_i32 s53, s51, 384
	s_cmp_ge_u32 s53, 0x18000
	s_cbranch_scc1 .Lrp15_done2
	s_add_u32 s53, s53, s50
	s_add_u32 s54, s53, 376
	s_mov_b32 s56, -1
	s_mov_b32 s55, s53
	s_add_u32 s57, s53, 0
	s_lshl_b32 s60, s57, 12
	s_add_u32 s64, s84, s60
	s_addc_u32 s65, s85, 0
	s_lshl_b32 s60, s57, 11
	s_add_u32 s66, s82, s60
	s_addc_u32 s67, s83, 0
	s_lshl_b32 s60, s57, 11
	s_add_u32 s68, s78, s60
	s_addc_u32 s69, s79, 0
	global_load_dwordx4 v[4:7], v0, s[64:65] nt
	global_load_dwordx4 v[8:11], v0, s[64:65] offset:1024 nt
	global_load_dwordx4 v[12:15], v0, s[64:65] offset:2048 nt
	global_load_dwordx4 v[16:19], v0, s[64:65] offset:3072 nt
	global_load_dwordx2 v[20:21], v1, s[66:67] nt
	global_load_dwordx2 v[22:23], v1, s[66:67] offset:512 nt
	global_load_dwordx2 v[24:25], v1, s[66:67] offset:1024 nt
	global_load_dwordx2 v[26:27], v1, s[66:67] offset:1536 nt
	global_load_dwordx2 v[28:29], v1, s[68:69] nt
	global_load_dwordx2 v[30:31], v1, s[68:69] offset:512 nt
	global_load_dwordx2 v[32:33], v1, s[68:69] offset:1024 nt
	global_load_dwordx2 v[34:35], v1, s[68:69] offset:1536 nt
	s_add_u32 s57, s53, 8
	s_lshl_b32 s60, s57, 12
	s_add_u32 s64, s84, s60
	s_addc_u32 s65, s85, 0
	s_lshl_b32 s60, s57, 11
	s_add_u32 s66, s82, s60
	s_addc_u32 s67, s83, 0
	s_lshl_b32 s60, s57, 11
	s_add_u32 s68, s78, s60
	s_addc_u32 s69, s79, 0
	global_load_dwordx4 v[36:39], v0, s[64:65] nt
	global_load_dwordx4 v[40:43], v0, s[64:65] offset:1024 nt
	global_load_dwordx4 v[44:47], v0, s[64:65] offset:2048 nt
	global_load_dwordx4 v[48:51], v0, s[64:65] offset:3072 nt
	global_load_dwordx2 v[52:53], v1, s[66:67] nt
	global_load_dwordx2 v[54:55], v1, s[66:67] offset:512 nt
	global_load_dwordx2 v[56:57], v1, s[66:67] offset:1024 nt
	global_load_dwordx2 v[58:59], v1, s[66:67] offset:1536 nt
	global_load_dwordx2 v[60:61], v1, s[68:69] nt
	global_load_dwordx2 v[62:63], v1, s[68:69] offset:512 nt
	global_load_dwordx2 v[64:65], v1, s[68:69] offset:1024 nt
	global_load_dwordx2 v[66:67], v1, s[68:69] offset:1536 nt
	s_add_u32 s57, s55, 16
	s_min_u32 s57, s57, s54
	s_lshl_b32 s60, s57, 12
	s_add_u32 s64, s84, s60
	s_addc_u32 s65, s85, 0
	s_lshl_b32 s60, s57, 11
	s_add_u32 s66, s82, s60
	s_addc_u32 s67, s83, 0
	s_lshl_b32 s60, s57, 11
	s_add_u32 s68, s78, s60
	s_addc_u32 s69, s79, 0
	global_load_dwordx4 v[68:71], v0, s[64:65] nt
	global_load_dwordx4 v[72:75], v0, s[64:65] offset:1024 nt
	global_load_dwordx4 v[76:79], v0, s[64:65] offset:2048 nt
	global_load_dwordx4 v[80:83], v0, s[64:65] offset:3072 nt
	global_load_dwordx2 v[84:85], v1, s[66:67] nt
	global_load_dwordx2 v[86:87], v1, s[66:67] offset:512 nt
	global_load_dwordx2 v[88:89], v1, s[66:67] offset:1024 nt
	global_load_dwordx2 v[90:91], v1, s[66:67] offset:1536 nt
	global_load_dwordx2 v[92:93], v1, s[68:69] nt
	global_load_dwordx2 v[94:95], v1, s[68:69] offset:512 nt
	global_load_dwordx2 v[96:97], v1, s[68:69] offset:1024 nt
	global_load_dwordx2 v[98:99], v1, s[68:69] offset:1536 nt
	s_lshr_b32 s60, s55, 11
	s_sub_u32 s61, s55, 0x8000
	s_lshr_b32 s61, s61, 12
	s_add_u32 s61, s61, 16
	s_cmp_lt_u32 s55, 0x8000
	s_cselect_b32 s63, s60, s61
	s_cmp_eq_u32 s63, s56
	s_cbranch_scc1 .Lrp15_pk4
	s_mov_b32 s56, s63
	s_mul_i32 s60, s56, 0x9000
	s_add_u32 s60, s60, 0x3185000
	s_add_u32 s0, s92, s60
	s_addc_u32 s1, s93, 0
	global_load_dwordx4 v[160:163], v0, s[0:1]
	global_load_dwordx4 v[164:167], v0, s[0:1] offset:1024
	global_load_dwordx4 v[168:171], v0, s[0:1] offset:2048
	global_load_dwordx4 v[172:175], v0, s[0:1] offset:3072
	s_add_u32 s0, s22, 0x1000
	s_addc_u32 s1, s23, 0
	global_load_dwordx4 v[176:179], v0, s[0:1]
	global_load_dwordx4 v[180:183], v0, s[0:1] offset:1024
	global_load_dwordx4 v[184:187], v0, s[0:1] offset:2048
	global_load_dwordx4 v[188:191], v0, s[0:1] offset:3072
	s_mul_i32 s60, s56, 0x9000
	s_add_u32 s60, s60, 0x3188000
	s_add_u32 s0, s92, s60
	s_addc_u32 s1, s93, 0
	global_load_dwordx4 v[192:195], v0, s[0:1]
	global_load_dwordx4 v[196:199], v0, s[0:1] offset:1024
	global_load_dwordx4 v[200:203], v0, s[0:1] offset:2048
	global_load_dwordx4 v[204:207], v0, s[0:1] offset:3072
	s_add_u32 s0, s22, 0x2000
	s_addc_u32 s1, s23, 0
	global_load_dwordx4 v[208:211], v0, s[0:1]
	global_load_dwordx4 v[212:215], v0, s[0:1] offset:1024
	global_load_dwordx4 v[216:219], v0, s[0:1] offset:2048
	global_load_dwordx4 v[220:223], v0, s[0:1] offset:3072
	s_waitcnt vmcnt(0)
; __device__ __forceinline__ float lo_bf(unsigned w) { return __uint_as_float(w << 16); }
; __device__ __forceinline__ float hi_bf(unsigned w) { return __uint_as_float(w & 0xffff0000u); }
; __device__ __forceinline__ void phase_final(const Params& p) {
;     ...
;         for (int j = 0; j < 4; ++j) { v[j] = *(const f32x4*)(p.out + (size_t)row * D + 4 * lane + 256 * j);
;             const u32x2 wm = *(const u32x2*)(Fm + (size_t)row * D + 4 * lane + 256 * j), wf = *(const u32x2*)(F2 + (size_t)row * D + 4 * lane + 256 * j);
;             m[j] = (f32x4){lo_bf(wm.x), hi_bf(wm.x), lo_bf(wm.y), hi_bf(wm.y)}; f[j] = (f32x4){lo_bf(wf.x), hi_bf(wf.x), lo_bf(wf.y), hi_bf(wf.y)};
;             sm += (m[j].x * m[j].x + m[j].y * m[j].y) + (m[j].z * m[j].z + m[j].w * m[j].w); sf += (f[j].x * f[j].x + f[j].y * f[j].y) + (f[j].z * f[j].z + f[j].w * f[j].w); }
;         const float rm = 1.0f / sqrtf(wave_sum(sm) * (1.0f / D) + EPS), rf = 1.0f / sqrtf(wave_sum(sf) * (1.0f / D) + EPS) * 0.5f;
.Lrp15_pk4:
	s_waitcnt vmcnt(24)
	v_lshlrev_b32_e32 v112, 16, v20
	v_and_b32_e32 v113, 0xffff0000, v20
	v_lshlrev_b32_e32 v114, 16, v21
	v_and_b32_e32 v115, 0xffff0000, v21
	v_lshlrev_b32_e32 v116, 16, v22
	v_and_b32_e32 v117, 0xffff0000, v22
	v_lshlrev_b32_e32 v118, 16, v23
	v_and_b32_e32 v119, 0xffff0000, v23
	v_lshlrev_b32_e32 v120, 16, v24
	v_and_b32_e32 v121, 0xffff0000, v24
	v_lshlrev_b32_e32 v122, 16, v25
	v_and_b32_e32 v123, 0xffff0000, v25
	v_lshlrev_b32_e32 v124, 16, v26
	v_and_b32_e32 v125, 0xffff0000, v26
	v_lshlrev_b32_e32 v100, 16, v27
	v_and_b32_e32 v101, 0xffff0000, v27
	v_pk_mul_f32 v[102:103], v[112:113], v[112:113]
	v_pk_mul_f32 v[106:107], v[114:115], v[114:115]
	v_pk_fma_f32 v[102:103], v[116:117], v[116:117], v[102:103]
	v_pk_fma_f32 v[106:107], v[118:119], v[118:119], v[106:107]
	v_pk_fma_f32 v[102:103], v[120:121], v[120:121], v[102:103]
	v_pk_fma_f32 v[106:107], v[122:123], v[122:123], v[106:107]
	v_pk_fma_f32 v[102:103], v[124:125], v[124:125], v[102:103]
	v_pk_fma_f32 v[106:107], v[100:101], v[100:101], v[106:107]
	v_pk_add_f32 v[102:103], v[102:103], v[106:107]
	v_add_f32_e32 v102, v102, v103
	v_mov_b32_e32 v104, v102
	v_lshlrev_b32_e32 v112, 16, v28
	v_and_b32_e32 v113, 0xffff0000, v28
	v_lshlrev_b32_e32 v114, 16, v29
	v_and_b32_e32 v115, 0xffff0000, v29
	v_lshlrev_b32_e32 v116, 16, v30
	v_and_b32_e32 v117, 0xffff0000, v30
	v_lshlrev_b32_e32 v118, 16, v31
	v_and_b32_e32 v119, 0xffff0000, v31
	v_lshlrev_b32_e32 v120, 16, v32
	v_and_b32_e32 v121, 0xffff0000, v32
	v_lshlrev_b32_e32 v122, 16, v33
	v_and_b32_e32 v123, 0xffff0000, v33
	v_lshlrev_b32_e32 v124, 16, v34
	v_and_b32_e32 v125, 0xffff0000, v34
	v_lshlrev_b32_e32 v100, 16, v35
	v_and_b32_e32 v101, 0xffff0000, v35
	v_pk_mul_f32 v[102:103], v[112:113], v[112:113]
	v_pk_mul_f32 v[106:107], v[114:115], v[114:115]
	v_pk_fma_f32 v[102:103], v[116:117], v[116:117], v[102:103]
	v_pk_fma_f32 v[106:107], v[118:119], v[118:119], v[106:107]
	v_pk_fma_f32 v[102:103], v[120:121], v[120:121], v[102:103]
	v_pk_fma_f32 v[106:107], v[122:123], v[122:123], v[106:107]
	v_pk_fma_f32 v[102:103], v[124:125], v[124:125], v[102:103]
	v_pk_fma_f32 v[106:107], v[100:101], v[100:101], v[106:107]
	v_pk_add_f32 v[102:103], v[102:103], v[106:107]
	v_add_f32_e32 v102, v102, v103
	s_nop 1
	v_add_f32_dpp v104, v104, v104 quad_perm:[1,0,3,2] row_mask:0xf bank_mask:0xf
	v_add_f32_dpp v102, v102, v102 quad_perm:[1,0,3,2] row_mask:0xf bank_mask:0xf
	s_nop 1
	v_add_f32_dpp v104, v104, v104 quad_perm:[2,3,0,1] row_mask:0xf bank_mask:0xf
	v_add_f32_dpp v102, v102, v102 quad_perm:[2,3,0,1] row_mask:0xf bank_mask:0xf
	s_nop 1
	v_add_f32_dpp v104, v104, v104 row_half_mirror row_mask:0xf bank_mask:0xf
	v_add_f32_dpp v102, v102, v102 row_half_mirror row_mask:0xf bank_mask:0xf
	s_nop 1
	v_add_f32_dpp v104, v104, v104 row_mirror row_mask:0xf bank_mask:0xf
	v_add_f32_dpp v102, v102, v102 row_mirror row_mask:0xf bank_mask:0xf
	s_nop 1
	v_add_f32_dpp v104, v104, v104 row_bcast:15 row_mask:0xa bank_mask:0xf
	v_add_f32_dpp v102, v102, v102 row_bcast:15 row_mask:0xa bank_mask:0xf
	s_nop 1
	v_add_f32_dpp v104, v104, v104 row_bcast:31 row_mask:0xc bank_mask:0xf
	v_add_f32_dpp v102, v102, v102 row_bcast:31 row_mask:0xc bank_mask:0xf
	s_nop 1
	v_readlane_b32 s74, v104, 63
	v_readlane_b32 s75, v102, 63
	s_nop 2
	v_mov_b32_e32 v102, s74
	v_fmamk_f32 v102, v102, 0x3a800000, v2
	v_mul_f32_e32 v103, 0x4f800000, v102
	v_cmp_gt_f32_e32 vcc, 0xf800000, v102
	s_nop 1
	v_cndmask_b32_e32 v102, v102, v103, vcc
	v_sqrt_f32_e32 v103, v102
	s_nop 0
	v_add_u32_e32 v104, -1, v103
	v_add_u32_e32 v106, 1, v103
	v_fma_f32 v107, -v104, v103, v102
	v_fma_f32 v108, -v106, v103, v102
	v_cmp_ge_f32_e64 s[76:77], 0, v107
	s_nop 1
	v_cndmask_b32_e64 v103, v103, v104, s[76:77]
	v_cmp_lt_f32_e64 s[76:77], 0, v108
	s_nop 1
	v_cndmask_b32_e64 v103, v103, v106, s[76:77]
	v_mul_f32_e32 v104, 0x37800000, v103
	v_cndmask_b32_e32 v103, v103, v104, vcc
	v_cmp_class_f32_e32 vcc, v102, v3
	s_nop 1
	v_cndmask_b32_e32 v102, v103, v102, vcc
	v_div_scale_f32 v103, s[76:77], v102, v102, 1.0
	v_rcp_f32_e32 v104, v103
	v_div_scale_f32 v106, vcc, 1.0, v102, 1.0
	v_fma_f32 v107, -v103, v104, 1.0
	v_fmac_f32_e32 v104, v107, v104
	v_mul_f32_e32 v107, v106, v104
	v_fma_f32 v108, -v103, v107, v106
	v_fmac_f32_e32 v107, v108, v104
	v_fma_f32 v103, -v103, v107, v106
	v_div_fmas_f32 v103, v103, v104, v107
	v_div_fixup_f32 v110, v103, v102, 1.0
	v_mov_b32_e32 v102, s75
	v_fmamk_f32 v102, v102, 0x3a800000, v2
	v_mul_f32_e32 v103, 0x4f800000, v102
	v_cmp_gt_f32_e32 vcc, 0xf800000, v102
	s_nop 1
	v_cndmask_b32_e32 v102, v102, v103, vcc
	v_sqrt_f32_e32 v103, v102
	s_nop 0
	v_add_u32_e32 v104, -1, v103
	v_add_u32_e32 v106, 1, v103
	v_fma_f32 v107, -v104, v103, v102
	v_fma_f32 v108, -v106, v103, v102
	v_cmp_ge_f32_e64 s[76:77], 0, v107
	s_nop 1
	v_cndmask_b32_e64 v103, v103, v104, s[76:77]
	v_cmp_lt_f32_e64 s[76:77], 0, v108
	s_nop 1
	v_cndmask_b32_e64 v103, v103, v106, s[76:77]
	v_mul_f32_e32 v104, 0x37800000, v103
	v_cndmask_b32_e32 v103, v103, v104, vcc
	v_cmp_class_f32_e32 vcc, v102, v3
	s_nop 1
	v_cndmask_b32_e32 v102, v103, v102, vcc
	v_div_scale_f32 v103, s[76:77], v102, v102, 1.0
	v_rcp_f32_e32 v104, v103
	v_div_scale_f32 v106, vcc, 1.0, v102, 1.0
	v_fma_f32 v107, -v103, v104, 1.0
	v_fmac_f32_e32 v104, v107, v104
	v_mul_f32_e32 v107, v106, v104
	v_fma_f32 v108, -v103, v107, v106
	v_fmac_f32_e32 v107, v108, v104
	v_fma_f32 v103, -v103, v107, v106
	v_div_fmas_f32 v103, v103, v104, v107
	v_div_fixup_f32 v108, v103, v102, 1.0
	v_mul_f32_e32 v108, 0.5, v108
	v_pk_mul_f32 v[112:113], v[112:113], v[108:109] op_sel_hi:[1,0]
	v_pk_mul_f32 v[114:115], v[114:115], v[108:109] op_sel_hi:[1,0]
; __device__ __forceinline__ void phase_final(const Params& p) {
;     ...
;     for (int row = gw; row < T; row += NGW) {
;         const int b = row_batch(row);
;         f32x4 v[4], m[4], f[4]; float sm = 0.f, sf = 0.f;
; #pragma unroll
;         for (int j = 0; j < 4; ++j) { v[j] = *(const f32x4*)(p.out + (size_t)row * D + 4 * lane + 256 * j);
;             const u32x2 wm = *(const u32x2*)(Fm + (size_t)row * D + 4 * lane + 256 * j), wf = *(const u32x2*)(F2 + (size_t)row * D + 4 * lane + 256 * j);
;     ...
;         const float rm = 1.0f / sqrtf(wave_sum(sm) * (1.0f / D) + EPS), rf = 1.0f / sqrtf(wave_sum(sf) * (1.0f / D) + EPS) * 0.5f;
;         const float* g1 = mod + b * 9216 + 1 * 3072 + 2048; const float* g2 = mod + b * 9216 + 2 * 3072 + 2048;
;         const float* q1 = p.in[7] + 1 * D; const float* q2 = p.in[7] + 2 * D;
; #pragma unroll
;         for (int j = 0; j < 4; ++j) { const int c = 4 * lane + 256 * j;
;             const f32x4 x2 = v[j] + *(const f32x4*)(g1 + c) * (m[j] * rm * *(const f32x4*)(q1 + c));
;             *(f32x4*)(p.out + (size_t)row * D + c) = x2 + *(const f32x4*)(g2 + c) * (f[j] * rf * *(const f32x4*)(q2 + c)); }
	v_pk_mul_f32 v[116:117], v[116:117], v[108:109] op_sel_hi:[1,0]
	v_pk_mul_f32 v[118:119], v[118:119], v[108:109] op_sel_hi:[1,0]
	v_pk_mul_f32 v[120:121], v[120:121], v[108:109] op_sel_hi:[1,0]
	v_pk_mul_f32 v[122:123], v[122:123], v[108:109] op_sel_hi:[1,0]
	v_pk_mul_f32 v[124:125], v[124:125], v[108:109] op_sel_hi:[1,0]
	v_pk_mul_f32 v[100:101], v[100:101], v[108:109] op_sel_hi:[1,0]
	v_pk_mul_f32 v[112:113], v[112:113], v[208:209]
	v_pk_mul_f32 v[114:115], v[114:115], v[210:211]
	v_pk_mul_f32 v[116:117], v[116:117], v[212:213]
	v_pk_mul_f32 v[118:119], v[118:119], v[214:215]
	v_pk_mul_f32 v[120:121], v[120:121], v[216:217]
	v_pk_mul_f32 v[122:123], v[122:123], v[218:219]
	v_pk_mul_f32 v[124:125], v[124:125], v[220:221]
	v_pk_mul_f32 v[100:101], v[100:101], v[222:223]
	v_lshlrev_b32_e32 v28, 16, v20
	v_and_b32_e32 v29, 0xffff0000, v20
	v_lshlrev_b32_e32 v30, 16, v21
	v_and_b32_e32 v31, 0xffff0000, v21
	v_lshlrev_b32_e32 v32, 16, v22
	v_and_b32_e32 v33, 0xffff0000, v22
	v_lshlrev_b32_e32 v34, 16, v23
	v_and_b32_e32 v35, 0xffff0000, v23
	v_lshlrev_b32_e32 v240, 16, v24
	v_and_b32_e32 v241, 0xffff0000, v24
	v_lshlrev_b32_e32 v242, 16, v25
	v_and_b32_e32 v243, 0xffff0000, v25
	v_lshlrev_b32_e32 v244, 16, v26
	v_and_b32_e32 v245, 0xffff0000, v26
	v_lshlrev_b32_e32 v246, 16, v27
	v_and_b32_e32 v247, 0xffff0000, v27
	v_pk_mul_f32 v[28:29], v[28:29], v[110:111] op_sel_hi:[1,0]
	v_pk_mul_f32 v[30:31], v[30:31], v[110:111] op_sel_hi:[1,0]
	v_pk_mul_f32 v[32:33], v[32:33], v[110:111] op_sel_hi:[1,0]
	v_pk_mul_f32 v[34:35], v[34:35], v[110:111] op_sel_hi:[1,0]
	v_pk_mul_f32 v[240:241], v[240:241], v[110:111] op_sel_hi:[1,0]
	v_pk_mul_f32 v[242:243], v[242:243], v[110:111] op_sel_hi:[1,0]
	v_pk_mul_f32 v[244:245], v[244:245], v[110:111] op_sel_hi:[1,0]
	v_pk_mul_f32 v[246:247], v[246:247], v[110:111] op_sel_hi:[1,0]
	v_pk_mul_f32 v[28:29], v[28:29], v[176:177]
	v_pk_mul_f32 v[30:31], v[30:31], v[178:179]
	v_pk_mul_f32 v[32:33], v[32:33], v[180:181]
	v_pk_mul_f32 v[34:35], v[34:35], v[182:183]
	v_pk_mul_f32 v[240:241], v[240:241], v[184:185]
	v_pk_mul_f32 v[242:243], v[242:243], v[186:187]
	v_pk_mul_f32 v[244:245], v[244:245], v[188:189]
	v_pk_mul_f32 v[246:247], v[246:247], v[190:191]
	v_pk_fma_f32 v[4:5], v[160:161], v[28:29], v[4:5]
	v_pk_fma_f32 v[6:7], v[162:163], v[30:31], v[6:7]
	v_pk_fma_f32 v[8:9], v[164:165], v[32:33], v[8:9]
	v_pk_fma_f32 v[10:11], v[166:167], v[34:35], v[10:11]
	v_pk_fma_f32 v[12:13], v[168:169], v[240:241], v[12:13]
	v_pk_fma_f32 v[14:15], v[170:171], v[242:243], v[14:15]
	v_pk_fma_f32 v[16:17], v[172:173], v[244:245], v[16:17]
	v_pk_fma_f32 v[18:19], v[174:175], v[246:247], v[18:19]
	v_pk_fma_f32 v[4:5], v[192:193], v[112:113], v[4:5]
	v_pk_fma_f32 v[6:7], v[194:195], v[114:115], v[6:7]
	v_pk_fma_f32 v[8:9], v[196:197], v[116:117], v[8:9]
	v_pk_fma_f32 v[10:11], v[198:199], v[118:119], v[10:11]
	v_pk_fma_f32 v[12:13], v[200:201], v[120:121], v[12:13]
	v_pk_fma_f32 v[14:15], v[202:203], v[122:123], v[14:15]
	v_pk_fma_f32 v[16:17], v[204:205], v[124:125], v[16:17]
	v_pk_fma_f32 v[18:19], v[206:207], v[100:101], v[18:19]
	s_lshl_b32 s60, s55, 12
	s_add_u32 s72, s84, s60
	s_addc_u32 s73, s85, 0
	global_store_dwordx4 v0, v[4:7], s[72:73]
	global_store_dwordx4 v0, v[8:11], s[72:73] offset:1024
	global_store_dwordx4 v0, v[12:15], s[72:73] offset:2048
	global_store_dwordx4 v0, v[16:19], s[72:73] offset:3072
	s_add_u32 s55, s55, 8
	s_add_u32 s57, s55, 16
	s_min_u32 s57, s57, s54
	s_lshl_b32 s60, s57, 12
	s_add_u32 s64, s84, s60
	s_addc_u32 s65, s85, 0
	s_lshl_b32 s60, s57, 11
	s_add_u32 s66, s82, s60
	s_addc_u32 s67, s83, 0
	s_lshl_b32 s60, s57, 11
	s_add_u32 s68, s78, s60
	s_addc_u32 s69, s79, 0
	global_load_dwordx4 v[4:7], v0, s[64:65] nt
	global_load_dwordx4 v[8:11], v0, s[64:65] offset:1024 nt
	global_load_dwordx4 v[12:15], v0, s[64:65] offset:2048 nt
	global_load_dwordx4 v[16:19], v0, s[64:65] offset:3072 nt
	global_load_dwordx2 v[20:21], v1, s[66:67] nt
	global_load_dwordx2 v[22:23], v1, s[66:67] offset:512 nt
	global_load_dwordx2 v[24:25], v1, s[66:67] offset:1024 nt
	global_load_dwordx2 v[26:27], v1, s[66:67] offset:1536 nt
	global_load_dwordx2 v[28:29], v1, s[68:69] nt
	global_load_dwordx2 v[30:31], v1, s[68:69] offset:512 nt
	global_load_dwordx2 v[32:33], v1, s[68:69] offset:1024 nt
	global_load_dwordx2 v[34:35], v1, s[68:69] offset:1536 nt
	s_lshr_b32 s60, s55, 11
	s_sub_u32 s61, s55, 0x8000
	s_lshr_b32 s61, s61, 12
	s_add_u32 s61, s61, 16
	s_cmp_lt_u32 s55, 0x8000
	s_cselect_b32 s63, s60, s61
	s_cmp_eq_u32 s63, s56
	s_cbranch_scc1 .Lrp15_pk5
	s_mov_b32 s56, s63
	s_mul_i32 s60, s56, 0x9000
	s_add_u32 s60, s60, 0x3185000
	s_add_u32 s0, s92, s60
	s_addc_u32 s1, s93, 0
	global_load_dwordx4 v[160:163], v0, s[0:1]
	global_load_dwordx4 v[164:167], v0, s[0:1] offset:1024
	global_load_dwordx4 v[168:171], v0, s[0:1] offset:2048
	global_load_dwordx4 v[172:175], v0, s[0:1] offset:3072
	s_add_u32 s0, s22, 0x1000
	s_addc_u32 s1, s23, 0
	global_load_dwordx4 v[176:179], v0, s[0:1]
	global_load_dwordx4 v[180:183], v0, s[0:1] offset:1024
	global_load_dwordx4 v[184:187], v0, s[0:1] offset:2048
	global_load_dwordx4 v[188:191], v0, s[0:1] offset:3072
	s_mul_i32 s60, s56, 0x9000
	s_add_u32 s60, s60, 0x3188000
	s_add_u32 s0, s92, s60
	s_addc_u32 s1, s93, 0
	global_load_dwordx4 v[192:195], v0, s[0:1]
	global_load_dwordx4 v[196:199], v0, s[0:1] offset:1024
	global_load_dwordx4 v[200:203], v0, s[0:1] offset:2048
	global_load_dwordx4 v[204:207], v0, s[0:1] offset:3072
	s_add_u32 s0, s22, 0x2000
	s_addc_u32 s1, s23, 0
	global_load_dwordx4 v[208:211], v0, s[0:1]
	global_load_dwordx4 v[212:215], v0, s[0:1] offset:1024
	global_load_dwordx4 v[216:219], v0, s[0:1] offset:2048
	global_load_dwordx4 v[220:223], v0, s[0:1] offset:3072
	s_waitcnt vmcnt(0)
; __device__ __forceinline__ float lo_bf(unsigned w) { return __uint_as_float(w << 16); }
; __device__ __forceinline__ float hi_bf(unsigned w) { return __uint_as_float(w & 0xffff0000u); }
; __device__ __forceinline__ void phase_final(const Params& p) {
;     ...
;         for (int j = 0; j < 4; ++j) { v[j] = *(const f32x4*)(p.out + (size_t)row * D + 4 * lane + 256 * j);
;             const u32x2 wm = *(const u32x2*)(Fm + (size_t)row * D + 4 * lane + 256 * j), wf = *(const u32x2*)(F2 + (size_t)row * D + 4 * lane + 256 * j);
;             m[j] = (f32x4){lo_bf(wm.x), hi_bf(wm.x), lo_bf(wm.y), hi_bf(wm.y)}; f[j] = (f32x4){lo_bf(wf.x), hi_bf(wf.x), lo_bf(wf.y), hi_bf(wf.y)};
;             sm += (m[j].x * m[j].x + m[j].y * m[j].y) + (m[j].z * m[j].z + m[j].w * m[j].w); sf += (f[j].x * f[j].x + f[j].y * f[j].y) + (f[j].z * f[j].z + f[j].w * f[j].w); }
;         const float rm = 1.0f / sqrtf(wave_sum(sm) * (1.0f / D) + EPS), rf = 1.0f / sqrtf(wave_sum(sf) * (1.0f / D) + EPS) * 0.5f;
.Lrp15_pk5:
	s_waitcnt vmcnt(28)
	v_lshlrev_b32_e32 v112, 16, v52
	v_and_b32_e32 v113, 0xffff0000, v52
	v_lshlrev_b32_e32 v114, 16, v53
	v_and_b32_e32 v115, 0xffff0000, v53
	v_lshlrev_b32_e32 v116, 16, v54
	v_and_b32_e32 v117, 0xffff0000, v54
	v_lshlrev_b32_e32 v118, 16, v55
	v_and_b32_e32 v119, 0xffff0000, v55
	v_lshlrev_b32_e32 v120, 16, v56
	v_and_b32_e32 v121, 0xffff0000, v56
	v_lshlrev_b32_e32 v122, 16, v57
	v_and_b32_e32 v123, 0xffff0000, v57
	v_lshlrev_b32_e32 v124, 16, v58
	v_and_b32_e32 v125, 0xffff0000, v58
	v_lshlrev_b32_e32 v100, 16, v59
	v_and_b32_e32 v101, 0xffff0000, v59
	v_pk_mul_f32 v[102:103], v[112:113], v[112:113]
	v_pk_mul_f32 v[106:107], v[114:115], v[114:115]
	v_pk_fma_f32 v[102:103], v[116:117], v[116:117], v[102:103]
	v_pk_fma_f32 v[106:107], v[118:119], v[118:119], v[106:107]
	v_pk_fma_f32 v[102:103], v[120:121], v[120:121], v[102:103]
	v_pk_fma_f32 v[106:107], v[122:123], v[122:123], v[106:107]
	v_pk_fma_f32 v[102:103], v[124:125], v[124:125], v[102:103]
	v_pk_fma_f32 v[106:107], v[100:101], v[100:101], v[106:107]
	v_pk_add_f32 v[102:103], v[102:103], v[106:107]
	v_add_f32_e32 v102, v102, v103
	v_mov_b32_e32 v104, v102
	v_lshlrev_b32_e32 v112, 16, v60
	v_and_b32_e32 v113, 0xffff0000, v60
	v_lshlrev_b32_e32 v114, 16, v61
	v_and_b32_e32 v115, 0xffff0000, v61
	v_lshlrev_b32_e32 v116, 16, v62
	v_and_b32_e32 v117, 0xffff0000, v62
	v_lshlrev_b32_e32 v118, 16, v63
	v_and_b32_e32 v119, 0xffff0000, v63
	v_lshlrev_b32_e32 v120, 16, v64
	v_and_b32_e32 v121, 0xffff0000, v64
	v_lshlrev_b32_e32 v122, 16, v65
	v_and_b32_e32 v123, 0xffff0000, v65
	v_lshlrev_b32_e32 v124, 16, v66
	v_and_b32_e32 v125, 0xffff0000, v66
	v_lshlrev_b32_e32 v100, 16, v67
	v_and_b32_e32 v101, 0xffff0000, v67
	v_pk_mul_f32 v[102:103], v[112:113], v[112:113]
	v_pk_mul_f32 v[106:107], v[114:115], v[114:115]
	v_pk_fma_f32 v[102:103], v[116:117], v[116:117], v[102:103]
	v_pk_fma_f32 v[106:107], v[118:119], v[118:119], v[106:107]
	v_pk_fma_f32 v[102:103], v[120:121], v[120:121], v[102:103]
	v_pk_fma_f32 v[106:107], v[122:123], v[122:123], v[106:107]
	v_pk_fma_f32 v[102:103], v[124:125], v[124:125], v[102:103]
	v_pk_fma_f32 v[106:107], v[100:101], v[100:101], v[106:107]
	v_pk_add_f32 v[102:103], v[102:103], v[106:107]
	v_add_f32_e32 v102, v102, v103
	s_nop 1
	v_add_f32_dpp v104, v104, v104 quad_perm:[1,0,3,2] row_mask:0xf bank_mask:0xf
	v_add_f32_dpp v102, v102, v102 quad_perm:[1,0,3,2] row_mask:0xf bank_mask:0xf
	s_nop 1
	v_add_f32_dpp v104, v104, v104 quad_perm:[2,3,0,1] row_mask:0xf bank_mask:0xf
	v_add_f32_dpp v102, v102, v102 quad_perm:[2,3,0,1] row_mask:0xf bank_mask:0xf
	s_nop 1
	v_add_f32_dpp v104, v104, v104 row_half_mirror row_mask:0xf bank_mask:0xf
	v_add_f32_dpp v102, v102, v102 row_half_mirror row_mask:0xf bank_mask:0xf
	s_nop 1
	v_add_f32_dpp v104, v104, v104 row_mirror row_mask:0xf bank_mask:0xf
	v_add_f32_dpp v102, v102, v102 row_mirror row_mask:0xf bank_mask:0xf
	s_nop 1
	v_add_f32_dpp v104, v104, v104 row_bcast:15 row_mask:0xa bank_mask:0xf
	v_add_f32_dpp v102, v102, v102 row_bcast:15 row_mask:0xa bank_mask:0xf
	s_nop 1
	v_add_f32_dpp v104, v104, v104 row_bcast:31 row_mask:0xc bank_mask:0xf
	v_add_f32_dpp v102, v102, v102 row_bcast:31 row_mask:0xc bank_mask:0xf
	s_nop 1
	v_readlane_b32 s74, v104, 63
	v_readlane_b32 s75, v102, 63
	s_nop 2
	v_mov_b32_e32 v102, s74
	v_fmamk_f32 v102, v102, 0x3a800000, v2
	v_mul_f32_e32 v103, 0x4f800000, v102
	v_cmp_gt_f32_e32 vcc, 0xf800000, v102
	s_nop 1
	v_cndmask_b32_e32 v102, v102, v103, vcc
	v_sqrt_f32_e32 v103, v102
	s_nop 0
	v_add_u32_e32 v104, -1, v103
	v_add_u32_e32 v106, 1, v103
	v_fma_f32 v107, -v104, v103, v102
	v_fma_f32 v108, -v106, v103, v102
	v_cmp_ge_f32_e64 s[76:77], 0, v107
	s_nop 1
	v_cndmask_b32_e64 v103, v103, v104, s[76:77]
	v_cmp_lt_f32_e64 s[76:77], 0, v108
	s_nop 1
	v_cndmask_b32_e64 v103, v103, v106, s[76:77]
	v_mul_f32_e32 v104, 0x37800000, v103
	v_cndmask_b32_e32 v103, v103, v104, vcc
	v_cmp_class_f32_e32 vcc, v102, v3
	s_nop 1
	v_cndmask_b32_e32 v102, v103, v102, vcc
	v_div_scale_f32 v103, s[76:77], v102, v102, 1.0
	v_rcp_f32_e32 v104, v103
	v_div_scale_f32 v106, vcc, 1.0, v102, 1.0
	v_fma_f32 v107, -v103, v104, 1.0
	v_fmac_f32_e32 v104, v107, v104
	v_mul_f32_e32 v107, v106, v104
	v_fma_f32 v108, -v103, v107, v106
	v_fmac_f32_e32 v107, v108, v104
	v_fma_f32 v103, -v103, v107, v106
	v_div_fmas_f32 v103, v103, v104, v107
	v_div_fixup_f32 v110, v103, v102, 1.0
	v_mov_b32_e32 v102, s75
	v_fmamk_f32 v102, v102, 0x3a800000, v2
	v_mul_f32_e32 v103, 0x4f800000, v102
	v_cmp_gt_f32_e32 vcc, 0xf800000, v102
	s_nop 1
	v_cndmask_b32_e32 v102, v102, v103, vcc
	v_sqrt_f32_e32 v103, v102
	s_nop 0
	v_add_u32_e32 v104, -1, v103
	v_add_u32_e32 v106, 1, v103
	v_fma_f32 v107, -v104, v103, v102
	v_fma_f32 v108, -v106, v103, v102
	v_cmp_ge_f32_e64 s[76:77], 0, v107
	s_nop 1
	v_cndmask_b32_e64 v103, v103, v104, s[76:77]
	v_cmp_lt_f32_e64 s[76:77], 0, v108
	s_nop 1
	v_cndmask_b32_e64 v103, v103, v106, s[76:77]
	v_mul_f32_e32 v104, 0x37800000, v103
	v_cndmask_b32_e32 v103, v103, v104, vcc
	v_cmp_class_f32_e32 vcc, v102, v3
	s_nop 1
	v_cndmask_b32_e32 v102, v103, v102, vcc
	v_div_scale_f32 v103, s[76:77], v102, v102, 1.0
	v_rcp_f32_e32 v104, v103
	v_div_scale_f32 v106, vcc, 1.0, v102, 1.0
	v_fma_f32 v107, -v103, v104, 1.0
	v_fmac_f32_e32 v104, v107, v104
	v_mul_f32_e32 v107, v106, v104
	v_fma_f32 v108, -v103, v107, v106
	v_fmac_f32_e32 v107, v108, v104
	v_fma_f32 v103, -v103, v107, v106
	v_div_fmas_f32 v103, v103, v104, v107
	v_div_fixup_f32 v108, v103, v102, 1.0
	v_mul_f32_e32 v108, 0.5, v108
	v_pk_mul_f32 v[112:113], v[112:113], v[108:109] op_sel_hi:[1,0]
	v_pk_mul_f32 v[114:115], v[114:115], v[108:109] op_sel_hi:[1,0]
; __device__ __forceinline__ float lo_bf(unsigned w) { return __uint_as_float(w << 16); }
; __device__ __forceinline__ float hi_bf(unsigned w) { return __uint_as_float(w & 0xffff0000u); }
; __device__ __forceinline__ void phase_final(const Params& p) {
;     ...
;         for (int j = 0; j < 4; ++j) { v[j] = *(const f32x4*)(p.out + (size_t)row * D + 4 * lane + 256 * j);
;             const u32x2 wm = *(const u32x2*)(Fm + (size_t)row * D + 4 * lane + 256 * j), wf = *(const u32x2*)(F2 + (size_t)row * D + 4 * lane + 256 * j);
;             m[j] = (f32x4){lo_bf(wm.x), hi_bf(wm.x), lo_bf(wm.y), hi_bf(wm.y)}; f[j] = (f32x4){lo_bf(wf.x), hi_bf(wf.x), lo_bf(wf.y), hi_bf(wf.y)};
;             sm += (m[j].x * m[j].x + m[j].y * m[j].y) + (m[j].z * m[j].z + m[j].w * m[j].w); sf += (f[j].x * f[j].x + f[j].y * f[j].y) + (f[j].z * f[j].z + f[j].w * f[j].w); }
;         const float rm = 1.0f / sqrtf(wave_sum(sm) * (1.0f / D) + EPS), rf = 1.0f / sqrtf(wave_sum(sf) * (1.0f / D) + EPS) * 0.5f;
;         const float* g1 = mod + b * 9216 + 1 * 3072 + 2048; const float* g2 = mod + b * 9216 + 2 * 3072 + 2048;
;         const float* q1 = p.in[7] + 1 * D; const float* q2 = p.in[7] + 2 * D;
; #pragma unroll
;         for (int j = 0; j < 4; ++j) { const int c = 4 * lane + 256 * j;
;             const f32x4 x2 = v[j] + *(const f32x4*)(g1 + c) * (m[j] * rm * *(const f32x4*)(q1 + c));
;             *(f32x4*)(p.out + (size_t)row * D + c) = x2 + *(const f32x4*)(g2 + c) * (f[j] * rf * *(const f32x4*)(q2 + c)); }
	v_pk_mul_f32 v[116:117], v[116:117], v[108:109] op_sel_hi:[1,0]
	v_pk_mul_f32 v[118:119], v[118:119], v[108:109] op_sel_hi:[1,0]
	v_pk_mul_f32 v[120:121], v[120:121], v[108:109] op_sel_hi:[1,0]
	v_pk_mul_f32 v[122:123], v[122:123], v[108:109] op_sel_hi:[1,0]
	v_pk_mul_f32 v[124:125], v[124:125], v[108:109] op_sel_hi:[1,0]
	v_pk_mul_f32 v[100:101], v[100:101], v[108:109] op_sel_hi:[1,0]
	v_pk_mul_f32 v[112:113], v[112:113], v[208:209]
	v_pk_mul_f32 v[114:115], v[114:115], v[210:211]
	v_pk_mul_f32 v[116:117], v[116:117], v[212:213]
	v_pk_mul_f32 v[118:119], v[118:119], v[214:215]
	v_pk_mul_f32 v[120:121], v[120:121], v[216:217]
	v_pk_mul_f32 v[122:123], v[122:123], v[218:219]
	v_pk_mul_f32 v[124:125], v[124:125], v[220:221]
	v_pk_mul_f32 v[100:101], v[100:101], v[222:223]
	v_lshlrev_b32_e32 v60, 16, v52
	v_and_b32_e32 v61, 0xffff0000, v52
	v_lshlrev_b32_e32 v62, 16, v53
	v_and_b32_e32 v63, 0xffff0000, v53
	v_lshlrev_b32_e32 v64, 16, v54
	v_and_b32_e32 v65, 0xffff0000, v54
	v_lshlrev_b32_e32 v66, 16, v55
	v_and_b32_e32 v67, 0xffff0000, v55
	v_lshlrev_b32_e32 v240, 16, v56
	v_and_b32_e32 v241, 0xffff0000, v56
	v_lshlrev_b32_e32 v242, 16, v57
	v_and_b32_e32 v243, 0xffff0000, v57
	v_lshlrev_b32_e32 v244, 16, v58
	v_and_b32_e32 v245, 0xffff0000, v58
	v_lshlrev_b32_e32 v246, 16, v59
	v_and_b32_e32 v247, 0xffff0000, v59
	v_pk_mul_f32 v[60:61], v[60:61], v[110:111] op_sel_hi:[1,0]
	v_pk_mul_f32 v[62:63], v[62:63], v[110:111] op_sel_hi:[1,0]
	v_pk_mul_f32 v[64:65], v[64:65], v[110:111] op_sel_hi:[1,0]
	v_pk_mul_f32 v[66:67], v[66:67], v[110:111] op_sel_hi:[1,0]
	v_pk_mul_f32 v[240:241], v[240:241], v[110:111] op_sel_hi:[1,0]
	v_pk_mul_f32 v[242:243], v[242:243], v[110:111] op_sel_hi:[1,0]
	v_pk_mul_f32 v[244:245], v[244:245], v[110:111] op_sel_hi:[1,0]
	v_pk_mul_f32 v[246:247], v[246:247], v[110:111] op_sel_hi:[1,0]
	v_pk_mul_f32 v[60:61], v[60:61], v[176:177]
	v_pk_mul_f32 v[62:63], v[62:63], v[178:179]
	v_pk_mul_f32 v[64:65], v[64:65], v[180:181]
	v_pk_mul_f32 v[66:67], v[66:67], v[182:183]
	v_pk_mul_f32 v[240:241], v[240:241], v[184:185]
	v_pk_mul_f32 v[242:243], v[242:243], v[186:187]
	v_pk_mul_f32 v[244:245], v[244:245], v[188:189]
	v_pk_mul_f32 v[246:247], v[246:247], v[190:191]
	v_pk_fma_f32 v[36:37], v[160:161], v[60:61], v[36:37]
	v_pk_fma_f32 v[38:39], v[162:163], v[62:63], v[38:39]
	v_pk_fma_f32 v[40:41], v[164:165], v[64:65], v[40:41]
	v_pk_fma_f32 v[42:43], v[166:167], v[66:67], v[42:43]
	v_pk_fma_f32 v[44:45], v[168:169], v[240:241], v[44:45]
	v_pk_fma_f32 v[46:47], v[170:171], v[242:243], v[46:47]
	v_pk_fma_f32 v[48:49], v[172:173], v[244:245], v[48:49]
	v_pk_fma_f32 v[50:51], v[174:175], v[246:247], v[50:51]
	v_pk_fma_f32 v[36:37], v[192:193], v[112:113], v[36:37]
	v_pk_fma_f32 v[38:39], v[194:195], v[114:115], v[38:39]
	v_pk_fma_f32 v[40:41], v[196:197], v[116:117], v[40:41]
	v_pk_fma_f32 v[42:43], v[198:199], v[118:119], v[42:43]
	v_pk_fma_f32 v[44:45], v[200:201], v[120:121], v[44:45]
	v_pk_fma_f32 v[46:47], v[202:203], v[122:123], v[46:47]
	v_pk_fma_f32 v[48:49], v[204:205], v[124:125], v[48:49]
	v_pk_fma_f32 v[50:51], v[206:207], v[100:101], v[50:51]
	s_lshl_b32 s60, s55, 12
	s_add_u32 s72, s84, s60
	s_addc_u32 s73, s85, 0
	global_store_dwordx4 v0, v[36:39], s[72:73]
	global_store_dwordx4 v0, v[40:43], s[72:73] offset:1024
	global_store_dwordx4 v0, v[44:47], s[72:73] offset:2048
	global_store_dwordx4 v0, v[48:51], s[72:73] offset:3072
	s_add_u32 s55, s55, 8
	s_add_u32 s57, s55, 16
	s_min_u32 s57, s57, s54
	s_lshl_b32 s60, s57, 12
	s_add_u32 s64, s84, s60
	s_addc_u32 s65, s85, 0
	s_lshl_b32 s60, s57, 11
	s_add_u32 s66, s82, s60
	s_addc_u32 s67, s83, 0
	s_lshl_b32 s60, s57, 11
	s_add_u32 s68, s78, s60
	s_addc_u32 s69, s79, 0
	global_load_dwordx4 v[36:39], v0, s[64:65] nt
	global_load_dwordx4 v[40:43], v0, s[64:65] offset:1024 nt
	global_load_dwordx4 v[44:47], v0, s[64:65] offset:2048 nt
	global_load_dwordx4 v[48:51], v0, s[64:65] offset:3072 nt
	global_load_dwordx2 v[52:53], v1, s[66:67] nt
	global_load_dwordx2 v[54:55], v1, s[66:67] offset:512 nt
	global_load_dwordx2 v[56:57], v1, s[66:67] offset:1024 nt
	global_load_dwordx2 v[58:59], v1, s[66:67] offset:1536 nt
	global_load_dwordx2 v[60:61], v1, s[68:69] nt
	global_load_dwordx2 v[62:63], v1, s[68:69] offset:512 nt
	global_load_dwordx2 v[64:65], v1, s[68:69] offset:1024 nt
	global_load_dwordx2 v[66:67], v1, s[68:69] offset:1536 nt
	s_lshr_b32 s60, s55, 11
	s_sub_u32 s61, s55, 0x8000
	s_lshr_b32 s61, s61, 12
	s_add_u32 s61, s61, 16
	s_cmp_lt_u32 s55, 0x8000
	s_cselect_b32 s63, s60, s61
	s_cmp_eq_u32 s63, s56
	s_cbranch_scc1 .Lrp15_pk6
	s_mov_b32 s56, s63
	s_mul_i32 s60, s56, 0x9000
	s_add_u32 s60, s60, 0x3185000
	s_add_u32 s0, s92, s60
	s_addc_u32 s1, s93, 0
	global_load_dwordx4 v[160:163], v0, s[0:1]
	global_load_dwordx4 v[164:167], v0, s[0:1] offset:1024
	global_load_dwordx4 v[168:171], v0, s[0:1] offset:2048
	global_load_dwordx4 v[172:175], v0, s[0:1] offset:3072
	s_add_u32 s0, s22, 0x1000
	s_addc_u32 s1, s23, 0
	global_load_dwordx4 v[176:179], v0, s[0:1]
	global_load_dwordx4 v[180:183], v0, s[0:1] offset:1024
	global_load_dwordx4 v[184:187], v0, s[0:1] offset:2048
	global_load_dwordx4 v[188:191], v0, s[0:1] offset:3072
	s_mul_i32 s60, s56, 0x9000
	s_add_u32 s60, s60, 0x3188000
	s_add_u32 s0, s92, s60
	s_addc_u32 s1, s93, 0
	global_load_dwordx4 v[192:195], v0, s[0:1]
	global_load_dwordx4 v[196:199], v0, s[0:1] offset:1024
	global_load_dwordx4 v[200:203], v0, s[0:1] offset:2048
	global_load_dwordx4 v[204:207], v0, s[0:1] offset:3072
	s_add_u32 s0, s22, 0x2000
	s_addc_u32 s1, s23, 0
	global_load_dwordx4 v[208:211], v0, s[0:1]
	global_load_dwordx4 v[212:215], v0, s[0:1] offset:1024
	global_load_dwordx4 v[216:219], v0, s[0:1] offset:2048
	global_load_dwordx4 v[220:223], v0, s[0:1] offset:3072
	s_waitcnt vmcnt(0)

; __device__ __forceinline__ float lo_bf(unsigned w) { return __uint_as_float(w << 16); }
; __device__ __forceinline__ float hi_bf(unsigned w) { return __uint_as_float(w & 0xffff0000u); }
; __device__ __forceinline__ void phase_final(const Params& p) {
;     ...
;     for (int row = gw; row < T; row += NGW) {
;         const int b = row_batch(row);
;         f32x4 v[4], m[4], f[4]; float sm = 0.f, sf = 0.f;
; #pragma unroll
;         for (int j = 0; j < 4; ++j) { v[j] = *(const f32x4*)(p.out + (size_t)row * D + 4 * lane + 256 * j);
;             const u32x2 wm = *(const u32x2*)(Fm + (size_t)row * D + 4 * lane + 256 * j), wf = *(const u32x2*)(F2 + (size_t)row * D + 4 * lane + 256 * j);
;             m[j] = (f32x4){lo_bf(wm.x), hi_bf(wm.x), lo_bf(wm.y), hi_bf(wm.y)}; f[j] = (f32x4){lo_bf(wf.x), hi_bf(wf.x), lo_bf(wf.y), hi_bf(wf.y)};
;             sm += (m[j].x * m[j].x + m[j].y * m[j].y) + (m[j].z * m[j].z + m[j].w * m[j].w); sf += (f[j].x * f[j].x + f[j].y * f[j].y) + (f[j].z * f[j].z + f[j].w * f[j].w); }
;         const float rm = 1.0f / sqrtf(wave_sum(sm) * (1.0f / D) + EPS), rf = 1.0f / sqrtf(wave_sum(sf) * (1.0f / D) + EPS) * 0.5f;
.Lrp15_loop3:
	s_add_u32 s57, s55, 16
	s_min_u32 s57, s57, s54
	s_lshl_b32 s60, s57, 12
	s_add_u32 s64, s84, s60
	s_addc_u32 s65, s85, 0
	s_lshl_b32 s60, s57, 11
	s_add_u32 s66, s82, s60
	s_addc_u32 s67, s83, 0
	s_lshl_b32 s60, s57, 11
	s_add_u32 s68, s78, s60
	s_addc_u32 s69, s79, 0
	global_load_dwordx4 v[68:71], v0, s[64:65] nt
	global_load_dwordx4 v[72:75], v0, s[64:65] offset:1024 nt
	global_load_dwordx4 v[76:79], v0, s[64:65] offset:2048 nt
	global_load_dwordx4 v[80:83], v0, s[64:65] offset:3072 nt
	global_load_dwordx2 v[84:85], v1, s[66:67] nt
	global_load_dwordx2 v[86:87], v1, s[66:67] offset:512 nt
	global_load_dwordx2 v[88:89], v1, s[66:67] offset:1024 nt
	global_load_dwordx2 v[90:91], v1, s[66:67] offset:1536 nt
	global_load_dwordx2 v[92:93], v1, s[68:69] nt
	global_load_dwordx2 v[94:95], v1, s[68:69] offset:512 nt
	global_load_dwordx2 v[96:97], v1, s[68:69] offset:1024 nt
	global_load_dwordx2 v[98:99], v1, s[68:69] offset:1536 nt
	s_lshr_b32 s60, s55, 11
	s_sub_u32 s61, s55, 0x8000
	s_lshr_b32 s61, s61, 12
	s_add_u32 s61, s61, 16
	s_cmp_lt_u32 s55, 0x8000
	s_cselect_b32 s63, s60, s61
	s_cmp_eq_u32 s63, s56
	s_cbranch_scc1 .Lrp15_pk7
	s_mov_b32 s56, s63
	s_mul_i32 s60, s56, 0x9000
	s_add_u32 s60, s60, 0x3185000
	s_add_u32 s0, s92, s60
	s_addc_u32 s1, s93, 0
	global_load_dwordx4 v[160:163], v0, s[0:1]
	global_load_dwordx4 v[164:167], v0, s[0:1] offset:1024
	global_load_dwordx4 v[168:171], v0, s[0:1] offset:2048
	global_load_dwordx4 v[172:175], v0, s[0:1] offset:3072
	s_add_u32 s0, s22, 0x1000
	s_addc_u32 s1, s23, 0
	global_load_dwordx4 v[176:179], v0, s[0:1]
	global_load_dwordx4 v[180:183], v0, s[0:1] offset:1024
	global_load_dwordx4 v[184:187], v0, s[0:1] offset:2048
	global_load_dwordx4 v[188:191], v0, s[0:1] offset:3072
	s_mul_i32 s60, s56, 0x9000
	s_add_u32 s60, s60, 0x3188000
	s_add_u32 s0, s92, s60
	s_addc_u32 s1, s93, 0
	global_load_dwordx4 v[192:195], v0, s[0:1]
	global_load_dwordx4 v[196:199], v0, s[0:1] offset:1024
	global_load_dwordx4 v[200:203], v0, s[0:1] offset:2048
	global_load_dwordx4 v[204:207], v0, s[0:1] offset:3072
	s_add_u32 s0, s22, 0x2000
	s_addc_u32 s1, s23, 0
	global_load_dwordx4 v[208:211], v0, s[0:1]
	global_load_dwordx4 v[212:215], v0, s[0:1] offset:1024
	global_load_dwordx4 v[216:219], v0, s[0:1] offset:2048
	global_load_dwordx4 v[220:223], v0, s[0:1] offset:3072
	s_waitcnt vmcnt(0)
.Lrp15_pk7:
	s_waitcnt vmcnt(32)
	v_lshlrev_b32_e32 v112, 16, v20
	v_and_b32_e32 v113, 0xffff0000, v20
	v_lshlrev_b32_e32 v114, 16, v21
	v_and_b32_e32 v115, 0xffff0000, v21
	v_lshlrev_b32_e32 v116, 16, v22
	v_and_b32_e32 v117, 0xffff0000, v22
	v_lshlrev_b32_e32 v118, 16, v23
	v_and_b32_e32 v119, 0xffff0000, v23
	v_lshlrev_b32_e32 v120, 16, v24
	v_and_b32_e32 v121, 0xffff0000, v24
	v_lshlrev_b32_e32 v122, 16, v25
	v_and_b32_e32 v123, 0xffff0000, v25
	v_lshlrev_b32_e32 v124, 16, v26
	v_and_b32_e32 v125, 0xffff0000, v26
	v_lshlrev_b32_e32 v100, 16, v27
	v_and_b32_e32 v101, 0xffff0000, v27
	v_pk_mul_f32 v[102:103], v[112:113], v[112:113]
	v_pk_mul_f32 v[106:107], v[114:115], v[114:115]
	v_pk_fma_f32 v[102:103], v[116:117], v[116:117], v[102:103]
	v_pk_fma_f32 v[106:107], v[118:119], v[118:119], v[106:107]
	v_pk_fma_f32 v[102:103], v[120:121], v[120:121], v[102:103]
	v_pk_fma_f32 v[106:107], v[122:123], v[122:123], v[106:107]
	v_pk_fma_f32 v[102:103], v[124:125], v[124:125], v[102:103]
	v_pk_fma_f32 v[106:107], v[100:101], v[100:101], v[106:107]
	v_pk_add_f32 v[102:103], v[102:103], v[106:107]
	v_add_f32_e32 v102, v102, v103
	v_mov_b32_e32 v104, v102
	v_lshlrev_b32_e32 v112, 16, v28
	v_and_b32_e32 v113, 0xffff0000, v28
	v_lshlrev_b32_e32 v114, 16, v29
	v_and_b32_e32 v115, 0xffff0000, v29
	v_lshlrev_b32_e32 v116, 16, v30
	v_and_b32_e32 v117, 0xffff0000, v30
	v_lshlrev_b32_e32 v118, 16, v31
	v_and_b32_e32 v119, 0xffff0000, v31
	v_lshlrev_b32_e32 v120, 16, v32
	v_and_b32_e32 v121, 0xffff0000, v32
	v_lshlrev_b32_e32 v122, 16, v33
	v_and_b32_e32 v123, 0xffff0000, v33
	v_lshlrev_b32_e32 v124, 16, v34
	v_and_b32_e32 v125, 0xffff0000, v34
	v_lshlrev_b32_e32 v100, 16, v35
	v_and_b32_e32 v101, 0xffff0000, v35
	v_pk_mul_f32 v[102:103], v[112:113], v[112:113]
	v_pk_mul_f32 v[106:107], v[114:115], v[114:115]
	v_pk_fma_f32 v[102:103], v[116:117], v[116:117], v[102:103]
	v_pk_fma_f32 v[106:107], v[118:119], v[118:119], v[106:107]
	v_pk_fma_f32 v[102:103], v[120:121], v[120:121], v[102:103]
	v_pk_fma_f32 v[106:107], v[122:123], v[122:123], v[106:107]
	v_pk_fma_f32 v[102:103], v[124:125], v[124:125], v[102:103]
	v_pk_fma_f32 v[106:107], v[100:101], v[100:101], v[106:107]
	v_pk_add_f32 v[102:103], v[102:103], v[106:107]
	v_add_f32_e32 v102, v102, v103
	s_nop 1
	v_add_f32_dpp v104, v104, v104 quad_perm:[1,0,3,2] row_mask:0xf bank_mask:0xf
	v_add_f32_dpp v102, v102, v102 quad_perm:[1,0,3,2] row_mask:0xf bank_mask:0xf
	s_nop 1
	v_add_f32_dpp v104, v104, v104 quad_perm:[2,3,0,1] row_mask:0xf bank_mask:0xf
	v_add_f32_dpp v102, v102, v102 quad_perm:[2,3,0,1] row_mask:0xf bank_mask:0xf
	s_nop 1
	v_add_f32_dpp v104, v104, v104 row_half_mirror row_mask:0xf bank_mask:0xf
	v_add_f32_dpp v102, v102, v102 row_half_mirror row_mask:0xf bank_mask:0xf
	s_nop 1
	v_add_f32_dpp v104, v104, v104 row_mirror row_mask:0xf bank_mask:0xf
	v_add_f32_dpp v102, v102, v102 row_mirror row_mask:0xf bank_mask:0xf
	s_nop 1
	v_add_f32_dpp v104, v104, v104 row_bcast:15 row_mask:0xa bank_mask:0xf
	v_add_f32_dpp v102, v102, v102 row_bcast:15 row_mask:0xa bank_mask:0xf
	s_nop 1
	v_add_f32_dpp v104, v104, v104 row_bcast:31 row_mask:0xc bank_mask:0xf
	v_add_f32_dpp v102, v102, v102 row_bcast:31 row_mask:0xc bank_mask:0xf
	s_nop 1
	v_readlane_b32 s74, v104, 63
	v_readlane_b32 s75, v102, 63
; __device__ __forceinline__ void phase_final(const Params& p) {
;     ...
;         const float rm = 1.0f / sqrtf(wave_sum(sm) * (1.0f / D) + EPS), rf = 1.0f / sqrtf(wave_sum(sf) * (1.0f / D) + EPS) * 0.5f;
;         const float* g1 = mod + b * 9216 + 1 * 3072 + 2048; const float* g2 = mod + b * 9216 + 2 * 3072 + 2048;
;         const float* q1 = p.in[7] + 1 * D; const float* q2 = p.in[7] + 2 * D;
; #pragma unroll
;         for (int j = 0; j < 4; ++j) { const int c = 4 * lane + 256 * j;
;             const f32x4 x2 = v[j] + *(const f32x4*)(g1 + c) * (m[j] * rm * *(const f32x4*)(q1 + c));
;             *(f32x4*)(p.out + (size_t)row * D + c) = x2 + *(const f32x4*)(g2 + c) * (f[j] * rf * *(const f32x4*)(q2 + c)); }
	s_nop 2
	v_mov_b32_e32 v102, s74
	v_fmamk_f32 v102, v102, 0x3a800000, v2
	v_mul_f32_e32 v103, 0x4f800000, v102
	v_cmp_gt_f32_e32 vcc, 0xf800000, v102
	s_nop 1
	v_cndmask_b32_e32 v102, v102, v103, vcc
	v_sqrt_f32_e32 v103, v102
	s_nop 0
	v_add_u32_e32 v104, -1, v103
	v_add_u32_e32 v106, 1, v103
	v_fma_f32 v107, -v104, v103, v102
	v_fma_f32 v108, -v106, v103, v102
	v_cmp_ge_f32_e64 s[76:77], 0, v107
	s_nop 1
	v_cndmask_b32_e64 v103, v103, v104, s[76:77]
	v_cmp_lt_f32_e64 s[76:77], 0, v108
	s_nop 1
	v_cndmask_b32_e64 v103, v103, v106, s[76:77]
	v_mul_f32_e32 v104, 0x37800000, v103
	v_cndmask_b32_e32 v103, v103, v104, vcc
	v_cmp_class_f32_e32 vcc, v102, v3
	s_nop 1
	v_cndmask_b32_e32 v102, v103, v102, vcc
	v_div_scale_f32 v103, s[76:77], v102, v102, 1.0
	v_rcp_f32_e32 v104, v103
	v_div_scale_f32 v106, vcc, 1.0, v102, 1.0
	v_fma_f32 v107, -v103, v104, 1.0
	v_fmac_f32_e32 v104, v107, v104
	v_mul_f32_e32 v107, v106, v104
	v_fma_f32 v108, -v103, v107, v106
	v_fmac_f32_e32 v107, v108, v104
	v_fma_f32 v103, -v103, v107, v106
	v_div_fmas_f32 v103, v103, v104, v107
	v_div_fixup_f32 v110, v103, v102, 1.0
	v_mov_b32_e32 v102, s75
	v_fmamk_f32 v102, v102, 0x3a800000, v2
	v_mul_f32_e32 v103, 0x4f800000, v102
	v_cmp_gt_f32_e32 vcc, 0xf800000, v102
	s_nop 1
	v_cndmask_b32_e32 v102, v102, v103, vcc
	v_sqrt_f32_e32 v103, v102
	s_nop 0
	v_add_u32_e32 v104, -1, v103
	v_add_u32_e32 v106, 1, v103
	v_fma_f32 v107, -v104, v103, v102
	v_fma_f32 v108, -v106, v103, v102
	v_cmp_ge_f32_e64 s[76:77], 0, v107
	s_nop 1
	v_cndmask_b32_e64 v103, v103, v104, s[76:77]
	v_cmp_lt_f32_e64 s[76:77], 0, v108
	s_nop 1
	v_cndmask_b32_e64 v103, v103, v106, s[76:77]
	v_mul_f32_e32 v104, 0x37800000, v103
	v_cndmask_b32_e32 v103, v103, v104, vcc
	v_cmp_class_f32_e32 vcc, v102, v3
	s_nop 1
	v_cndmask_b32_e32 v102, v103, v102, vcc
	v_div_scale_f32 v103, s[76:77], v102, v102, 1.0
	v_rcp_f32_e32 v104, v103
	v_div_scale_f32 v106, vcc, 1.0, v102, 1.0
	v_fma_f32 v107, -v103, v104, 1.0
	v_fmac_f32_e32 v104, v107, v104
	v_mul_f32_e32 v107, v106, v104
	v_fma_f32 v108, -v103, v107, v106
	v_fmac_f32_e32 v107, v108, v104
	v_fma_f32 v103, -v103, v107, v106
	v_div_fmas_f32 v103, v103, v104, v107
	v_div_fixup_f32 v108, v103, v102, 1.0
	v_mul_f32_e32 v108, 0.5, v108
	v_pk_mul_f32 v[112:113], v[112:113], v[108:109] op_sel_hi:[1,0]
	v_pk_mul_f32 v[114:115], v[114:115], v[108:109] op_sel_hi:[1,0]
	v_pk_mul_f32 v[116:117], v[116:117], v[108:109] op_sel_hi:[1,0]
	v_pk_mul_f32 v[118:119], v[118:119], v[108:109] op_sel_hi:[1,0]
	v_pk_mul_f32 v[120:121], v[120:121], v[108:109] op_sel_hi:[1,0]
	v_pk_mul_f32 v[122:123], v[122:123], v[108:109] op_sel_hi:[1,0]
	v_pk_mul_f32 v[124:125], v[124:125], v[108:109] op_sel_hi:[1,0]
	v_pk_mul_f32 v[100:101], v[100:101], v[108:109] op_sel_hi:[1,0]
	v_pk_mul_f32 v[112:113], v[112:113], v[208:209]
	v_pk_mul_f32 v[114:115], v[114:115], v[210:211]
	v_pk_mul_f32 v[116:117], v[116:117], v[212:213]
	v_pk_mul_f32 v[118:119], v[118:119], v[214:215]
	v_pk_mul_f32 v[120:121], v[120:121], v[216:217]
	v_pk_mul_f32 v[122:123], v[122:123], v[218:219]
	v_pk_mul_f32 v[124:125], v[124:125], v[220:221]
	v_pk_mul_f32 v[100:101], v[100:101], v[222:223]
	v_lshlrev_b32_e32 v28, 16, v20
	v_and_b32_e32 v29, 0xffff0000, v20
	v_lshlrev_b32_e32 v30, 16, v21
	v_and_b32_e32 v31, 0xffff0000, v21
	v_lshlrev_b32_e32 v32, 16, v22
	v_and_b32_e32 v33, 0xffff0000, v22
	v_lshlrev_b32_e32 v34, 16, v23
	v_and_b32_e32 v35, 0xffff0000, v23
	v_lshlrev_b32_e32 v240, 16, v24
	v_and_b32_e32 v241, 0xffff0000, v24
	v_lshlrev_b32_e32 v242, 16, v25
	v_and_b32_e32 v243, 0xffff0000, v25
	v_lshlrev_b32_e32 v244, 16, v26
	v_and_b32_e32 v245, 0xffff0000, v26
	v_lshlrev_b32_e32 v246, 16, v27
	v_and_b32_e32 v247, 0xffff0000, v27
	v_pk_mul_f32 v[28:29], v[28:29], v[110:111] op_sel_hi:[1,0]
	v_pk_mul_f32 v[30:31], v[30:31], v[110:111] op_sel_hi:[1,0]
	v_pk_mul_f32 v[32:33], v[32:33], v[110:111] op_sel_hi:[1,0]
	v_pk_mul_f32 v[34:35], v[34:35], v[110:111] op_sel_hi:[1,0]
	v_pk_mul_f32 v[240:241], v[240:241], v[110:111] op_sel_hi:[1,0]
	v_pk_mul_f32 v[242:243], v[242:243], v[110:111] op_sel_hi:[1,0]
	v_pk_mul_f32 v[244:245], v[244:245], v[110:111] op_sel_hi:[1,0]
	v_pk_mul_f32 v[246:247], v[246:247], v[110:111] op_sel_hi:[1,0]
	v_pk_mul_f32 v[28:29], v[28:29], v[176:177]
	v_pk_mul_f32 v[30:31], v[30:31], v[178:179]
	v_pk_mul_f32 v[32:33], v[32:33], v[180:181]
	v_pk_mul_f32 v[34:35], v[34:35], v[182:183]
	v_pk_mul_f32 v[240:241], v[240:241], v[184:185]
	v_pk_mul_f32 v[242:243], v[242:243], v[186:187]
	v_pk_mul_f32 v[244:245], v[244:245], v[188:189]
	v_pk_mul_f32 v[246:247], v[246:247], v[190:191]
	v_pk_fma_f32 v[4:5], v[160:161], v[28:29], v[4:5]
	v_pk_fma_f32 v[6:7], v[162:163], v[30:31], v[6:7]
	v_pk_fma_f32 v[8:9], v[164:165], v[32:33], v[8:9]
	v_pk_fma_f32 v[10:11], v[166:167], v[34:35], v[10:11]
	v_pk_fma_f32 v[12:13], v[168:169], v[240:241], v[12:13]
	v_pk_fma_f32 v[14:15], v[170:171], v[242:243], v[14:15]
	v_pk_fma_f32 v[16:17], v[172:173], v[244:245], v[16:17]
	v_pk_fma_f32 v[18:19], v[174:175], v[246:247], v[18:19]
	v_pk_fma_f32 v[4:5], v[192:193], v[112:113], v[4:5]
	v_pk_fma_f32 v[6:7], v[194:195], v[114:115], v[6:7]
	v_pk_fma_f32 v[8:9], v[196:197], v[116:117], v[8:9]
	v_pk_fma_f32 v[10:11], v[198:199], v[118:119], v[10:11]
	v_pk_fma_f32 v[12:13], v[200:201], v[120:121], v[12:13]
	v_pk_fma_f32 v[14:15], v[202:203], v[122:123], v[14:15]
	v_pk_fma_f32 v[16:17], v[204:205], v[124:125], v[16:17]
	v_pk_fma_f32 v[18:19], v[206:207], v[100:101], v[18:19]
	s_lshl_b32 s60, s55, 12
	s_add_u32 s72, s84, s60
	s_addc_u32 s73, s85, 0
	global_store_dwordx4 v0, v[4:7], s[72:73]
	global_store_dwordx4 v0, v[8:11], s[72:73] offset:1024
	global_store_dwordx4 v0, v[12:15], s[72:73] offset:2048
	global_store_dwordx4 v0, v[16:19], s[72:73] offset:3072
	s_add_u32 s55, s55, 8
	s_add_u32 s57, s55, 16
	s_min_u32 s57, s57, s54
	s_lshl_b32 s60, s57, 12
	s_add_u32 s64, s84, s60
	s_addc_u32 s65, s85, 0
	s_lshl_b32 s60, s57, 11
	s_add_u32 s66, s82, s60
	s_addc_u32 s67, s83, 0
	s_lshl_b32 s60, s57, 11
	s_add_u32 s68, s78, s60
	s_addc_u32 s69, s79, 0
	global_load_dwordx4 v[4:7], v0, s[64:65] nt
	global_load_dwordx4 v[8:11], v0, s[64:65] offset:1024 nt
	global_load_dwordx4 v[12:15], v0, s[64:65] offset:2048 nt
	global_load_dwordx4 v[16:19], v0, s[64:65] offset:3072 nt
	global_load_dwordx2 v[20:21], v1, s[66:67] nt
	global_load_dwordx2 v[22:23], v1, s[66:67] offset:512 nt
	global_load_dwordx2 v[24:25], v1, s[66:67] offset:1024 nt
	global_load_dwordx2 v[26:27], v1, s[66:67] offset:1536 nt
	global_load_dwordx2 v[28:29], v1, s[68:69] nt
	global_load_dwordx2 v[30:31], v1, s[68:69] offset:512 nt
	global_load_dwordx2 v[32:33], v1, s[68:69] offset:1024 nt
	global_load_dwordx2 v[34:35], v1, s[68:69] offset:1536 nt
	s_lshr_b32 s60, s55, 11
	s_sub_u32 s61, s55, 0x8000
	s_lshr_b32 s61, s61, 12
	s_add_u32 s61, s61, 16
	s_cmp_lt_u32 s55, 0x8000
	s_cselect_b32 s63, s60, s61
	s_cmp_eq_u32 s63, s56
	s_cbranch_scc1 .Lrp15_pk8
; __device__ __forceinline__ float lo_bf(unsigned w) { return __uint_as_float(w << 16); }
; __device__ __forceinline__ float hi_bf(unsigned w) { return __uint_as_float(w & 0xffff0000u); }
; __device__ __forceinline__ void phase_final(const Params& p) {
;     ...
;         for (int j = 0; j < 4; ++j) { v[j] = *(const f32x4*)(p.out + (size_t)row * D + 4 * lane + 256 * j);
;             const u32x2 wm = *(const u32x2*)(Fm + (size_t)row * D + 4 * lane + 256 * j), wf = *(const u32x2*)(F2 + (size_t)row * D + 4 * lane + 256 * j);
;             m[j] = (f32x4){lo_bf(wm.x), hi_bf(wm.x), lo_bf(wm.y), hi_bf(wm.y)}; f[j] = (f32x4){lo_bf(wf.x), hi_bf(wf.x), lo_bf(wf.y), hi_bf(wf.y)};
;             sm += (m[j].x * m[j].x + m[j].y * m[j].y) + (m[j].z * m[j].z + m[j].w * m[j].w); sf += (f[j].x * f[j].x + f[j].y * f[j].y) + (f[j].z * f[j].z + f[j].w * f[j].w); }
;         const float rm = 1.0f / sqrtf(wave_sum(sm) * (1.0f / D) + EPS), rf = 1.0f / sqrtf(wave_sum(sf) * (1.0f / D) + EPS) * 0.5f;
;         const float* g1 = mod + b * 9216 + 1 * 3072 + 2048; const float* g2 = mod + b * 9216 + 2 * 3072 + 2048;
;         const float* q1 = p.in[7] + 1 * D; const float* q2 = p.in[7] + 2 * D;
	s_mov_b32 s56, s63
	s_mul_i32 s60, s56, 0x9000
	s_add_u32 s60, s60, 0x3185000
	s_add_u32 s0, s92, s60
	s_addc_u32 s1, s93, 0
	global_load_dwordx4 v[160:163], v0, s[0:1]
	global_load_dwordx4 v[164:167], v0, s[0:1] offset:1024
	global_load_dwordx4 v[168:171], v0, s[0:1] offset:2048
	global_load_dwordx4 v[172:175], v0, s[0:1] offset:3072
	s_add_u32 s0, s22, 0x1000
	s_addc_u32 s1, s23, 0
	global_load_dwordx4 v[176:179], v0, s[0:1]
	global_load_dwordx4 v[180:183], v0, s[0:1] offset:1024
	global_load_dwordx4 v[184:187], v0, s[0:1] offset:2048
	global_load_dwordx4 v[188:191], v0, s[0:1] offset:3072
	s_mul_i32 s60, s56, 0x9000
	s_add_u32 s60, s60, 0x3188000
	s_add_u32 s0, s92, s60
	s_addc_u32 s1, s93, 0
	global_load_dwordx4 v[192:195], v0, s[0:1]
	global_load_dwordx4 v[196:199], v0, s[0:1] offset:1024
	global_load_dwordx4 v[200:203], v0, s[0:1] offset:2048
	global_load_dwordx4 v[204:207], v0, s[0:1] offset:3072
	s_add_u32 s0, s22, 0x2000
	s_addc_u32 s1, s23, 0
	global_load_dwordx4 v[208:211], v0, s[0:1]
	global_load_dwordx4 v[212:215], v0, s[0:1] offset:1024
	global_load_dwordx4 v[216:219], v0, s[0:1] offset:2048
	global_load_dwordx4 v[220:223], v0, s[0:1] offset:3072
	s_waitcnt vmcnt(0)
.Lrp15_pk8:
	s_waitcnt vmcnt(32)
	v_lshlrev_b32_e32 v112, 16, v52
	v_and_b32_e32 v113, 0xffff0000, v52
	v_lshlrev_b32_e32 v114, 16, v53
	v_and_b32_e32 v115, 0xffff0000, v53
	v_lshlrev_b32_e32 v116, 16, v54
	v_and_b32_e32 v117, 0xffff0000, v54
	v_lshlrev_b32_e32 v118, 16, v55
	v_and_b32_e32 v119, 0xffff0000, v55
	v_lshlrev_b32_e32 v120, 16, v56
	v_and_b32_e32 v121, 0xffff0000, v56
	v_lshlrev_b32_e32 v122, 16, v57
	v_and_b32_e32 v123, 0xffff0000, v57
	v_lshlrev_b32_e32 v124, 16, v58
	v_and_b32_e32 v125, 0xffff0000, v58
	v_lshlrev_b32_e32 v100, 16, v59
	v_and_b32_e32 v101, 0xffff0000, v59
	v_pk_mul_f32 v[102:103], v[112:113], v[112:113]
	v_pk_mul_f32 v[106:107], v[114:115], v[114:115]
	v_pk_fma_f32 v[102:103], v[116:117], v[116:117], v[102:103]
	v_pk_fma_f32 v[106:107], v[118:119], v[118:119], v[106:107]
	v_pk_fma_f32 v[102:103], v[120:121], v[120:121], v[102:103]
	v_pk_fma_f32 v[106:107], v[122:123], v[122:123], v[106:107]
	v_pk_fma_f32 v[102:103], v[124:125], v[124:125], v[102:103]
	v_pk_fma_f32 v[106:107], v[100:101], v[100:101], v[106:107]
	v_pk_add_f32 v[102:103], v[102:103], v[106:107]
	v_add_f32_e32 v102, v102, v103
	v_mov_b32_e32 v104, v102
	v_lshlrev_b32_e32 v112, 16, v60
	v_and_b32_e32 v113, 0xffff0000, v60
	v_lshlrev_b32_e32 v114, 16, v61
	v_and_b32_e32 v115, 0xffff0000, v61
	v_lshlrev_b32_e32 v116, 16, v62
	v_and_b32_e32 v117, 0xffff0000, v62
	v_lshlrev_b32_e32 v118, 16, v63
	v_and_b32_e32 v119, 0xffff0000, v63
	v_lshlrev_b32_e32 v120, 16, v64
	v_and_b32_e32 v121, 0xffff0000, v64
	v_lshlrev_b32_e32 v122, 16, v65
	v_and_b32_e32 v123, 0xffff0000, v65
	v_lshlrev_b32_e32 v124, 16, v66
	v_and_b32_e32 v125, 0xffff0000, v66
	v_lshlrev_b32_e32 v100, 16, v67
	v_and_b32_e32 v101, 0xffff0000, v67
	v_pk_mul_f32 v[102:103], v[112:113], v[112:113]
	v_pk_mul_f32 v[106:107], v[114:115], v[114:115]
	v_pk_fma_f32 v[102:103], v[116:117], v[116:117], v[102:103]
	v_pk_fma_f32 v[106:107], v[118:119], v[118:119], v[106:107]
	v_pk_fma_f32 v[102:103], v[120:121], v[120:121], v[102:103]
	v_pk_fma_f32 v[106:107], v[122:123], v[122:123], v[106:107]
	v_pk_fma_f32 v[102:103], v[124:125], v[124:125], v[102:103]
	v_pk_fma_f32 v[106:107], v[100:101], v[100:101], v[106:107]
	v_pk_add_f32 v[102:103], v[102:103], v[106:107]
	v_add_f32_e32 v102, v102, v103
	s_nop 1
	v_add_f32_dpp v104, v104, v104 quad_perm:[1,0,3,2] row_mask:0xf bank_mask:0xf
	v_add_f32_dpp v102, v102, v102 quad_perm:[1,0,3,2] row_mask:0xf bank_mask:0xf
	s_nop 1
	v_add_f32_dpp v104, v104, v104 quad_perm:[2,3,0,1] row_mask:0xf bank_mask:0xf
	v_add_f32_dpp v102, v102, v102 quad_perm:[2,3,0,1] row_mask:0xf bank_mask:0xf
	s_nop 1
	v_add_f32_dpp v104, v104, v104 row_half_mirror row_mask:0xf bank_mask:0xf
	v_add_f32_dpp v102, v102, v102 row_half_mirror row_mask:0xf bank_mask:0xf
	s_nop 1
	v_add_f32_dpp v104, v104, v104 row_mirror row_mask:0xf bank_mask:0xf
	v_add_f32_dpp v102, v102, v102 row_mirror row_mask:0xf bank_mask:0xf
	s_nop 1
	v_add_f32_dpp v104, v104, v104 row_bcast:15 row_mask:0xa bank_mask:0xf
	v_add_f32_dpp v102, v102, v102 row_bcast:15 row_mask:0xa bank_mask:0xf
	s_nop 1
	v_add_f32_dpp v104, v104, v104 row_bcast:31 row_mask:0xc bank_mask:0xf
	v_add_f32_dpp v102, v102, v102 row_bcast:31 row_mask:0xc bank_mask:0xf
	s_nop 1
	v_readlane_b32 s74, v104, 63
	v_readlane_b32 s75, v102, 63
	s_nop 2
	v_mov_b32_e32 v102, s74
	v_fmamk_f32 v102, v102, 0x3a800000, v2
	v_mul_f32_e32 v103, 0x4f800000, v102
	v_cmp_gt_f32_e32 vcc, 0xf800000, v102
	s_nop 1
	v_cndmask_b32_e32 v102, v102, v103, vcc
	v_sqrt_f32_e32 v103, v102
	s_nop 0
	v_add_u32_e32 v104, -1, v103
	v_add_u32_e32 v106, 1, v103
	v_fma_f32 v107, -v104, v103, v102
	v_fma_f32 v108, -v106, v103, v102
	v_cmp_ge_f32_e64 s[76:77], 0, v107
	s_nop 1
	v_cndmask_b32_e64 v103, v103, v104, s[76:77]
	v_cmp_lt_f32_e64 s[76:77], 0, v108
	s_nop 1
	v_cndmask_b32_e64 v103, v103, v106, s[76:77]
	v_mul_f32_e32 v104, 0x37800000, v103
	v_cndmask_b32_e32 v103, v103, v104, vcc
	v_cmp_class_f32_e32 vcc, v102, v3
	s_nop 1
	v_cndmask_b32_e32 v102, v103, v102, vcc
	v_div_scale_f32 v103, s[76:77], v102, v102, 1.0
	v_rcp_f32_e32 v104, v103
	v_div_scale_f32 v106, vcc, 1.0, v102, 1.0
	v_fma_f32 v107, -v103, v104, 1.0
	v_fmac_f32_e32 v104, v107, v104
	v_mul_f32_e32 v107, v106, v104
	v_fma_f32 v108, -v103, v107, v106
	v_fmac_f32_e32 v107, v108, v104
	v_fma_f32 v103, -v103, v107, v106
	v_div_fmas_f32 v103, v103, v104, v107
	v_div_fixup_f32 v110, v103, v102, 1.0
	v_mov_b32_e32 v102, s75
; __device__ __forceinline__ void phase_final(const Params& p) {
;     ...
;         const float rm = 1.0f / sqrtf(wave_sum(sm) * (1.0f / D) + EPS), rf = 1.0f / sqrtf(wave_sum(sf) * (1.0f / D) + EPS) * 0.5f;
;         const float* g1 = mod + b * 9216 + 1 * 3072 + 2048; const float* g2 = mod + b * 9216 + 2 * 3072 + 2048;
;         const float* q1 = p.in[7] + 1 * D; const float* q2 = p.in[7] + 2 * D;
; #pragma unroll
;         for (int j = 0; j < 4; ++j) { const int c = 4 * lane + 256 * j;
;             const f32x4 x2 = v[j] + *(const f32x4*)(g1 + c) * (m[j] * rm * *(const f32x4*)(q1 + c));
;             *(f32x4*)(p.out + (size_t)row * D + c) = x2 + *(const f32x4*)(g2 + c) * (f[j] * rf * *(const f32x4*)(q2 + c)); }
	v_fmamk_f32 v102, v102, 0x3a800000, v2
	v_mul_f32_e32 v103, 0x4f800000, v102
	v_cmp_gt_f32_e32 vcc, 0xf800000, v102
	s_nop 1
	v_cndmask_b32_e32 v102, v102, v103, vcc
	v_sqrt_f32_e32 v103, v102
	s_nop 0
	v_add_u32_e32 v104, -1, v103
	v_add_u32_e32 v106, 1, v103
	v_fma_f32 v107, -v104, v103, v102
	v_fma_f32 v108, -v106, v103, v102
	v_cmp_ge_f32_e64 s[76:77], 0, v107
	s_nop 1
	v_cndmask_b32_e64 v103, v103, v104, s[76:77]
	v_cmp_lt_f32_e64 s[76:77], 0, v108
	s_nop 1
	v_cndmask_b32_e64 v103, v103, v106, s[76:77]
	v_mul_f32_e32 v104, 0x37800000, v103
	v_cndmask_b32_e32 v103, v103, v104, vcc
	v_cmp_class_f32_e32 vcc, v102, v3
	s_nop 1
	v_cndmask_b32_e32 v102, v103, v102, vcc
	v_div_scale_f32 v103, s[76:77], v102, v102, 1.0
	v_rcp_f32_e32 v104, v103
	v_div_scale_f32 v106, vcc, 1.0, v102, 1.0
	v_fma_f32 v107, -v103, v104, 1.0
	v_fmac_f32_e32 v104, v107, v104
	v_mul_f32_e32 v107, v106, v104
	v_fma_f32 v108, -v103, v107, v106
	v_fmac_f32_e32 v107, v108, v104
	v_fma_f32 v103, -v103, v107, v106
	v_div_fmas_f32 v103, v103, v104, v107
	v_div_fixup_f32 v108, v103, v102, 1.0
	v_mul_f32_e32 v108, 0.5, v108
	v_pk_mul_f32 v[112:113], v[112:113], v[108:109] op_sel_hi:[1,0]
	v_pk_mul_f32 v[114:115], v[114:115], v[108:109] op_sel_hi:[1,0]
	v_pk_mul_f32 v[116:117], v[116:117], v[108:109] op_sel_hi:[1,0]
	v_pk_mul_f32 v[118:119], v[118:119], v[108:109] op_sel_hi:[1,0]
	v_pk_mul_f32 v[120:121], v[120:121], v[108:109] op_sel_hi:[1,0]
	v_pk_mul_f32 v[122:123], v[122:123], v[108:109] op_sel_hi:[1,0]
	v_pk_mul_f32 v[124:125], v[124:125], v[108:109] op_sel_hi:[1,0]
	v_pk_mul_f32 v[100:101], v[100:101], v[108:109] op_sel_hi:[1,0]
	v_pk_mul_f32 v[112:113], v[112:113], v[208:209]
	v_pk_mul_f32 v[114:115], v[114:115], v[210:211]
	v_pk_mul_f32 v[116:117], v[116:117], v[212:213]
	v_pk_mul_f32 v[118:119], v[118:119], v[214:215]
	v_pk_mul_f32 v[120:121], v[120:121], v[216:217]
	v_pk_mul_f32 v[122:123], v[122:123], v[218:219]
	v_pk_mul_f32 v[124:125], v[124:125], v[220:221]
	v_pk_mul_f32 v[100:101], v[100:101], v[222:223]
	v_lshlrev_b32_e32 v60, 16, v52
	v_and_b32_e32 v61, 0xffff0000, v52
	v_lshlrev_b32_e32 v62, 16, v53
	v_and_b32_e32 v63, 0xffff0000, v53
	v_lshlrev_b32_e32 v64, 16, v54
	v_and_b32_e32 v65, 0xffff0000, v54
	v_lshlrev_b32_e32 v66, 16, v55
	v_and_b32_e32 v67, 0xffff0000, v55
	v_lshlrev_b32_e32 v240, 16, v56
	v_and_b32_e32 v241, 0xffff0000, v56
	v_lshlrev_b32_e32 v242, 16, v57
	v_and_b32_e32 v243, 0xffff0000, v57
	v_lshlrev_b32_e32 v244, 16, v58
	v_and_b32_e32 v245, 0xffff0000, v58
	v_lshlrev_b32_e32 v246, 16, v59
	v_and_b32_e32 v247, 0xffff0000, v59
	v_pk_mul_f32 v[60:61], v[60:61], v[110:111] op_sel_hi:[1,0]
	v_pk_mul_f32 v[62:63], v[62:63], v[110:111] op_sel_hi:[1,0]
	v_pk_mul_f32 v[64:65], v[64:65], v[110:111] op_sel_hi:[1,0]
	v_pk_mul_f32 v[66:67], v[66:67], v[110:111] op_sel_hi:[1,0]
	v_pk_mul_f32 v[240:241], v[240:241], v[110:111] op_sel_hi:[1,0]
	v_pk_mul_f32 v[242:243], v[242:243], v[110:111] op_sel_hi:[1,0]
	v_pk_mul_f32 v[244:245], v[244:245], v[110:111] op_sel_hi:[1,0]
	v_pk_mul_f32 v[246:247], v[246:247], v[110:111] op_sel_hi:[1,0]
	v_pk_mul_f32 v[60:61], v[60:61], v[176:177]
	v_pk_mul_f32 v[62:63], v[62:63], v[178:179]
	v_pk_mul_f32 v[64:65], v[64:65], v[180:181]
	v_pk_mul_f32 v[66:67], v[66:67], v[182:183]
	v_pk_mul_f32 v[240:241], v[240:241], v[184:185]
	v_pk_mul_f32 v[242:243], v[242:243], v[186:187]
	v_pk_mul_f32 v[244:245], v[244:245], v[188:189]
	v_pk_mul_f32 v[246:247], v[246:247], v[190:191]
	v_pk_fma_f32 v[36:37], v[160:161], v[60:61], v[36:37]
	v_pk_fma_f32 v[38:39], v[162:163], v[62:63], v[38:39]
	v_pk_fma_f32 v[40:41], v[164:165], v[64:65], v[40:41]
	v_pk_fma_f32 v[42:43], v[166:167], v[66:67], v[42:43]
	v_pk_fma_f32 v[44:45], v[168:169], v[240:241], v[44:45]
	v_pk_fma_f32 v[46:47], v[170:171], v[242:243], v[46:47]
	v_pk_fma_f32 v[48:49], v[172:173], v[244:245], v[48:49]
	v_pk_fma_f32 v[50:51], v[174:175], v[246:247], v[50:51]
	v_pk_fma_f32 v[36:37], v[192:193], v[112:113], v[36:37]
	v_pk_fma_f32 v[38:39], v[194:195], v[114:115], v[38:39]
	v_pk_fma_f32 v[40:41], v[196:197], v[116:117], v[40:41]
	v_pk_fma_f32 v[42:43], v[198:199], v[118:119], v[42:43]
	v_pk_fma_f32 v[44:45], v[200:201], v[120:121], v[44:45]
	v_pk_fma_f32 v[46:47], v[202:203], v[122:123], v[46:47]
	v_pk_fma_f32 v[48:49], v[204:205], v[124:125], v[48:49]
	v_pk_fma_f32 v[50:51], v[206:207], v[100:101], v[50:51]
	s_lshl_b32 s60, s55, 12
	s_add_u32 s72, s84, s60
	s_addc_u32 s73, s85, 0
	global_store_dwordx4 v0, v[36:39], s[72:73]
	global_store_dwordx4 v0, v[40:43], s[72:73] offset:1024
	global_store_dwordx4 v0, v[44:47], s[72:73] offset:2048
	global_store_dwordx4 v0, v[48:51], s[72:73] offset:3072
	s_add_u32 s55, s55, 8
	s_add_u32 s57, s55, 16
	s_min_u32 s57, s57, s54
	s_lshl_b32 s60, s57, 12
	s_add_u32 s64, s84, s60
	s_addc_u32 s65, s85, 0
	s_lshl_b32 s60, s57, 11
	s_add_u32 s66, s82, s60
	s_addc_u32 s67, s83, 0
	s_lshl_b32 s60, s57, 11
	s_add_u32 s68, s78, s60
	s_addc_u32 s69, s79, 0
	global_load_dwordx4 v[36:39], v0, s[64:65] nt
	global_load_dwordx4 v[40:43], v0, s[64:65] offset:1024 nt
	global_load_dwordx4 v[44:47], v0, s[64:65] offset:2048 nt
	global_load_dwordx4 v[48:51], v0, s[64:65] offset:3072 nt
	global_load_dwordx2 v[52:53], v1, s[66:67] nt
	global_load_dwordx2 v[54:55], v1, s[66:67] offset:512 nt
	global_load_dwordx2 v[56:57], v1, s[66:67] offset:1024 nt
	global_load_dwordx2 v[58:59], v1, s[66:67] offset:1536 nt
	global_load_dwordx2 v[60:61], v1, s[68:69] nt
	global_load_dwordx2 v[62:63], v1, s[68:69] offset:512 nt
	global_load_dwordx2 v[64:65], v1, s[68:69] offset:1024 nt
	global_load_dwordx2 v[66:67], v1, s[68:69] offset:1536 nt
	s_lshr_b32 s60, s55, 11
	s_sub_u32 s61, s55, 0x8000
	s_lshr_b32 s61, s61, 12
	s_add_u32 s61, s61, 16
	s_cmp_lt_u32 s55, 0x8000
	s_cselect_b32 s63, s60, s61
	s_cmp_eq_u32 s63, s56
	s_cbranch_scc1 .Lrp15_pk9
	s_mov_b32 s56, s63
	s_mul_i32 s60, s56, 0x9000
	s_add_u32 s60, s60, 0x3185000
	s_add_u32 s0, s92, s60
	s_addc_u32 s1, s93, 0
	global_load_dwordx4 v[160:163], v0, s[0:1]
	global_load_dwordx4 v[164:167], v0, s[0:1] offset:1024
	global_load_dwordx4 v[168:171], v0, s[0:1] offset:2048
	global_load_dwordx4 v[172:175], v0, s[0:1] offset:3072
	s_add_u32 s0, s22, 0x1000
	s_addc_u32 s1, s23, 0
	global_load_dwordx4 v[176:179], v0, s[0:1]
	global_load_dwordx4 v[180:183], v0, s[0:1] offset:1024
	global_load_dwordx4 v[184:187], v0, s[0:1] offset:2048
	global_load_dwordx4 v[188:191], v0, s[0:1] offset:3072
	s_mul_i32 s60, s56, 0x9000
	s_add_u32 s60, s60, 0x3188000
	s_add_u32 s0, s92, s60
	s_addc_u32 s1, s93, 0
	global_load_dwordx4 v[192:195], v0, s[0:1]
	global_load_dwordx4 v[196:199], v0, s[0:1] offset:1024
	global_load_dwordx4 v[200:203], v0, s[0:1] offset:2048
	global_load_dwordx4 v[204:207], v0, s[0:1] offset:3072
	s_add_u32 s0, s22, 0x2000
	s_addc_u32 s1, s23, 0
	global_load_dwordx4 v[208:211], v0, s[0:1]
	global_load_dwordx4 v[212:215], v0, s[0:1] offset:1024
	global_load_dwordx4 v[216:219], v0, s[0:1] offset:2048
	global_load_dwordx4 v[220:223], v0, s[0:1] offset:3072
	s_waitcnt vmcnt(0)
